# v9b: rcp-based silu division in SwiGLU epilogues (f32, 1-ulp rcp) + nt cmp gather + QK batching + earlier edits
# speedup vs baseline: 1.0166x; 1.0111x over previous
.LBB0_797:
	v_mul_f32_e32 v133, 0xbfb8aa3b, v126
	v_exp_f32_e32 v133, v133
	s_lshl_b32 s10, s40, 7
	v_mul_f32_e32 v144, 0xbfb8aa3b, v127
	v_exp_f32_e32 v144, v144
	v_add_f32_e32 v133, 1.0, v133
	s_or_b32 s8, s35, s10
	v_or_b32_e32 v138, s8, v131
	v_add_u32_e32 v140, 0x4000, v1
	v_add_f32_e32 v141, 1.0, v144
	v_rcp_f32_e32 v131, v133
	s_nop 0
	v_mul_f32_e32 v126, v126, v131
	v_mul_f32_e32 v122, v126, v122
	v_mul_f32_e32 v133, 0xbfb8aa3b, v128
	v_exp_f32_e32 v133, v133
	v_rcp_f32_e32 v126, v141
	s_nop 0
	v_mul_f32_e32 v126, v127, v126
	v_add_f32_e32 v131, 1.0, v133
	v_mul_f32_e32 v123, v126, v123
	v_mul_f32_e32 v127, 0xbfb8aa3b, v129
	v_cvt_pk_bf16_f32 v122, v122, v123
	v_exp_f32_e32 v127, v127
	s_nop 0
	v_add_f32_e32 v127, 1.0, v127
	v_rcp_f32_e32 v123, v131
	s_nop 0
	v_mul_f32_e32 v123, v128, v123
	v_mul_f32_e32 v123, v123, v124
	v_mul_f32_e32 v128, 0xbfb8aa3b, v118
	v_exp_f32_e32 v128, v128
	v_rcp_f32_e32 v124, v127
	s_nop 0
	v_mul_f32_e32 v124, v129, v124
	v_add_f32_e32 v126, 1.0, v128
	v_mul_f32_e32 v124, v124, v125
	v_mul_f32_e32 v127, 0xbfb8aa3b, v119
	v_cvt_pk_bf16_f32 v123, v123, v124
	v_exp_f32_e32 v127, v127
	s_nop 0
	v_add_f32_e32 v127, 1.0, v127
	v_rcp_f32_e32 v124, v126
	s_nop 0
	v_mul_f32_e32 v118, v118, v124
	v_mul_f32_e32 v114, v118, v114
	v_mul_f32_e32 v125, 0xbfb8aa3b, v120
	v_exp_f32_e32 v125, v125
	v_rcp_f32_e32 v118, v127
	s_nop 0
	v_mul_f32_e32 v118, v119, v118
	v_add_f32_e32 v125, 1.0, v125
	v_mul_f32_e32 v115, v118, v115
	v_mul_f32_e32 v118, 0xbfb8aa3b, v121
	v_exp_f32_e32 v118, v118
	v_cvt_pk_bf16_f32 v124, v114, v115
	v_add_f32_e32 v118, 1.0, v118
	v_rcp_f32_e32 v114, v125
	s_nop 0
	v_mul_f32_e32 v114, v120, v114
	v_mul_f32_e32 v114, v114, v116
	v_rcp_f32_e32 v115, v118
	s_nop 0
	v_mul_f32_e32 v115, v121, v115
	v_mul_f32_e32 v115, v115, v117
	v_cvt_pk_bf16_f32 v125, v114, v115
	v_mul_f32_e32 v114, 0xbfb8aa3b, v110
	v_exp_f32_e32 v116, v114
	v_ashrrev_i32_e32 v139, 31, v138
	s_movk_i32 s8, 0x1600
	v_mov_b64_e32 v[114:115], s[16:17]
	v_add_f32_e32 v120, 1.0, v116
	v_mad_i64_i32 v[118:119], s[10:11], v140, s8, v[114:115]
	v_lshlrev_b64 v[116:117], 1, v[138:139]
	v_lshl_add_u64 v[118:119], v[118:119], 0, v[116:117]
	global_store_dwordx4 v[118:119], v[122:125], off
	s_nop 1
	v_mul_f32_e32 v122, 0xbfb8aa3b, v111
	v_exp_f32_e32 v122, v122
	s_nop 0
	v_add_f32_e32 v121, 1.0, v122
	v_rcp_f32_e32 v118, v120
	s_nop 0
	v_mul_f32_e32 v110, v110, v118
	v_mul_f32_e32 v106, v110, v106
	v_mul_f32_e32 v119, 0xbfb8aa3b, v112
	v_exp_f32_e32 v119, v119
	v_rcp_f32_e32 v110, v121
	s_nop 0
	v_mul_f32_e32 v110, v111, v110
	v_add_f32_e32 v118, 1.0, v119
	v_mul_f32_e32 v107, v110, v107
	v_mul_f32_e32 v111, 0xbfb8aa3b, v113
	v_cvt_pk_bf16_f32 v106, v106, v107
	v_exp_f32_e32 v111, v111
	s_nop 0
	v_add_f32_e32 v111, 1.0, v111
	v_rcp_f32_e32 v107, v118
	s_nop 0
	v_mul_f32_e32 v107, v112, v107
	v_mul_f32_e32 v107, v107, v108
	v_mul_f32_e32 v112, 0xbfb8aa3b, v102
	v_exp_f32_e32 v112, v112
	v_rcp_f32_e32 v108, v111
	s_nop 0
	v_mul_f32_e32 v108, v113, v108
	v_add_f32_e32 v110, 1.0, v112
	v_mul_f32_e32 v108, v108, v109
	v_mul_f32_e32 v111, 0xbfb8aa3b, v103
	v_cvt_pk_bf16_f32 v107, v107, v108
	v_exp_f32_e32 v111, v111
	s_nop 0
	v_add_f32_e32 v111, 1.0, v111
	v_rcp_f32_e32 v108, v110
	s_nop 0
	v_mul_f32_e32 v102, v102, v108
	v_mul_f32_e32 v98, v102, v98
	v_mul_f32_e32 v109, 0xbfb8aa3b, v104
	v_exp_f32_e32 v109, v109
	v_rcp_f32_e32 v102, v111
	s_nop 0
	v_mul_f32_e32 v102, v103, v102
	v_add_f32_e32 v109, 1.0, v109
	v_mul_f32_e32 v99, v102, v99
	v_mul_f32_e32 v102, 0xbfb8aa3b, v105
	v_exp_f32_e32 v102, v102
	v_cvt_pk_bf16_f32 v108, v98, v99
	v_add_f32_e32 v102, 1.0, v102
	v_rcp_f32_e32 v98, v109
	s_nop 0
	v_mul_f32_e32 v98, v104, v98
	v_mul_f32_e32 v98, v98, v100
	v_mul_f32_e32 v100, 0xbfb8aa3b, v94
	v_exp_f32_e32 v100, v100
	v_rcp_f32_e32 v99, v102
	s_nop 0
	v_mul_f32_e32 v99, v105, v99
	v_mul_f32_e32 v99, v99, v101
	v_cvt_pk_bf16_f32 v109, v98, v99
	v_add_f32_e32 v100, 1.0, v100
	v_add_u32_e32 v98, 0x4010, v1
	v_mad_i64_i32 v[98:99], s[10:11], v98, s8, v[114:115]
	v_lshl_add_u64 v[98:99], v[98:99], 0, v[116:117]
	global_store_dwordx4 v[98:99], v[106:109], off
	v_mul_f32_e32 v103, 0xbfb8aa3b, v95
	v_exp_f32_e32 v103, v103
	s_nop 0
	v_add_f32_e32 v101, 1.0, v103
	v_rcp_f32_e32 v98, v100
	s_nop 0
	v_mul_f32_e32 v94, v94, v98
	v_mul_f32_e32 v90, v94, v90
	v_mul_f32_e32 v99, 0xbfb8aa3b, v96
	v_exp_f32_e32 v99, v99
	v_rcp_f32_e32 v94, v101
	s_nop 0
	v_mul_f32_e32 v94, v95, v94
	v_add_f32_e32 v98, 1.0, v99
	v_mul_f32_e32 v91, v94, v91
	v_mul_f32_e32 v95, 0xbfb8aa3b, v97
	v_cvt_pk_bf16_f32 v90, v90, v91
	v_exp_f32_e32 v95, v95
	s_nop 0
	v_add_f32_e32 v95, 1.0, v95
	v_rcp_f32_e32 v91, v98
	s_nop 0
	v_mul_f32_e32 v91, v96, v91
	v_mul_f32_e32 v91, v91, v92
	v_mul_f32_e32 v96, 0xbfb8aa3b, v86
	v_exp_f32_e32 v96, v96
	v_rcp_f32_e32 v92, v95
	s_nop 0
	v_mul_f32_e32 v92, v97, v92
	v_add_f32_e32 v94, 1.0, v96
	v_mul_f32_e32 v92, v92, v93
	v_mul_f32_e32 v95, 0xbfb8aa3b, v87
	v_cvt_pk_bf16_f32 v91, v91, v92
	v_exp_f32_e32 v95, v95
	s_nop 0
	v_add_f32_e32 v95, 1.0, v95
	v_rcp_f32_e32 v92, v94
	s_nop 0
	v_mul_f32_e32 v86, v86, v92
	v_mul_f32_e32 v82, v86, v82
	v_mul_f32_e32 v93, 0xbfb8aa3b, v88
	v_exp_f32_e32 v93, v93
	v_rcp_f32_e32 v86, v95
	s_nop 0
	v_mul_f32_e32 v86, v87, v86
	v_add_f32_e32 v93, 1.0, v93
	v_mul_f32_e32 v83, v86, v83
	v_mul_f32_e32 v86, 0xbfb8aa3b, v89
	v_exp_f32_e32 v86, v86
	v_cvt_pk_bf16_f32 v92, v82, v83
	v_add_f32_e32 v86, 1.0, v86
	v_rcp_f32_e32 v82, v93
	s_nop 0
	v_mul_f32_e32 v82, v88, v82
	v_mul_f32_e32 v82, v82, v84
	v_mul_f32_e32 v84, 0xbfb8aa3b, v78
	v_exp_f32_e32 v84, v84
	v_rcp_f32_e32 v83, v86
	s_nop 0
	v_mul_f32_e32 v83, v89, v83
	v_mul_f32_e32 v83, v83, v85
	v_cvt_pk_bf16_f32 v93, v82, v83
	v_add_f32_e32 v84, 1.0, v84
	v_add_u32_e32 v82, 0x4020, v1
	v_mad_i64_i32 v[82:83], s[10:11], v82, s8, v[114:115]
	v_lshl_add_u64 v[82:83], v[82:83], 0, v[116:117]
	global_store_dwordx4 v[82:83], v[90:93], off
	v_mul_f32_e32 v87, 0xbfb8aa3b, v79
	v_exp_f32_e32 v87, v87
	s_nop 0
	v_add_f32_e32 v85, 1.0, v87
	v_rcp_f32_e32 v82, v84
	s_nop 0
	v_mul_f32_e32 v78, v78, v82
	v_mul_f32_e32 v74, v78, v74
	v_mul_f32_e32 v83, 0xbfb8aa3b, v80
	v_exp_f32_e32 v83, v83
	v_rcp_f32_e32 v78, v85
	s_nop 0
	v_mul_f32_e32 v78, v79, v78
	v_add_f32_e32 v82, 1.0, v83
	v_mul_f32_e32 v75, v78, v75
	v_mul_f32_e32 v79, 0xbfb8aa3b, v81
	v_cvt_pk_bf16_f32 v74, v74, v75
	v_exp_f32_e32 v79, v79
	s_nop 0
	v_add_f32_e32 v79, 1.0, v79
	v_rcp_f32_e32 v75, v82
	s_nop 0
	v_mul_f32_e32 v75, v80, v75
	v_mul_f32_e32 v75, v75, v76
	v_mul_f32_e32 v80, 0xbfb8aa3b, v70
	v_exp_f32_e32 v80, v80
	v_rcp_f32_e32 v76, v79
	s_nop 0
	v_mul_f32_e32 v76, v81, v76
	v_add_f32_e32 v78, 1.0, v80
	v_mul_f32_e32 v76, v76, v77
	v_mul_f32_e32 v79, 0xbfb8aa3b, v71
	v_cvt_pk_bf16_f32 v75, v75, v76
	v_exp_f32_e32 v79, v79
	s_nop 0
	v_add_f32_e32 v79, 1.0, v79
	v_rcp_f32_e32 v76, v78
	s_nop 0
	v_mul_f32_e32 v70, v70, v76
	v_mul_f32_e32 v66, v70, v66
	v_mul_f32_e32 v77, 0xbfb8aa3b, v72
	v_exp_f32_e32 v77, v77
	v_rcp_f32_e32 v70, v79
	s_nop 0
	v_mul_f32_e32 v70, v71, v70
	v_add_f32_e32 v77, 1.0, v77
	v_mul_f32_e32 v67, v70, v67
	v_mul_f32_e32 v70, 0xbfb8aa3b, v73
	v_exp_f32_e32 v70, v70
	v_cvt_pk_bf16_f32 v76, v66, v67
	v_add_f32_e32 v70, 1.0, v70
	v_rcp_f32_e32 v66, v77
	s_nop 0
	v_mul_f32_e32 v66, v72, v66
	v_mul_f32_e32 v66, v66, v68
	v_rcp_f32_e32 v67, v70
	s_nop 0
	v_mul_f32_e32 v67, v73, v67
	v_mul_f32_e32 v67, v67, v69
	v_cvt_pk_bf16_f32 v77, v66, v67
	v_mul_f32_e32 v66, 0xbfb8aa3b, v62
	v_exp_f32_e32 v68, v66
	v_add_u32_e32 v66, 0x4030, v1
	v_mad_i64_i32 v[66:67], s[10:11], v66, s8, v[114:115]
	v_add_f32_e32 v68, 1.0, v68
	v_lshl_add_u64 v[66:67], v[66:67], 0, v[116:117]
	global_store_dwordx4 v[66:67], v[74:77], off
	v_mul_f32_e32 v72, 0xbfb8aa3b, v63
	v_exp_f32_e32 v72, v72
	s_nop 0
	v_add_f32_e32 v69, 1.0, v72
	v_rcp_f32_e32 v67, v68
	s_nop 0
	v_mul_f32_e32 v62, v62, v67
	v_mul_f32_e32 v58, v62, v58
	v_mul_f32_e32 v68, 0xbfb8aa3b, v64
	v_exp_f32_e32 v68, v68
	v_rcp_f32_e32 v62, v69
	s_nop 0
	v_mul_f32_e32 v62, v63, v62
	v_add_f32_e32 v67, 1.0, v68
	v_mul_f32_e32 v59, v62, v59
	v_mul_f32_e32 v63, 0xbfb8aa3b, v65
	v_cvt_pk_bf16_f32 v58, v58, v59
	v_exp_f32_e32 v63, v63
	s_nop 0
	v_add_f32_e32 v63, 1.0, v63
	v_rcp_f32_e32 v59, v67
	s_nop 0
	v_mul_f32_e32 v59, v64, v59
	v_mul_f32_e32 v59, v59, v60
	v_mul_f32_e32 v64, 0xbfb8aa3b, v54
	v_exp_f32_e32 v64, v64
	v_rcp_f32_e32 v60, v63
	s_nop 0
	v_mul_f32_e32 v60, v65, v60
	v_add_f32_e32 v62, 1.0, v64
	v_mul_f32_e32 v60, v60, v61
	v_mul_f32_e32 v63, 0xbfb8aa3b, v55
	v_cvt_pk_bf16_f32 v59, v59, v60
	v_exp_f32_e32 v63, v63
	s_nop 0
	v_add_f32_e32 v63, 1.0, v63
	v_rcp_f32_e32 v60, v62
	s_nop 0
	v_mul_f32_e32 v54, v54, v60
	v_mul_f32_e32 v50, v54, v50
	v_mul_f32_e32 v61, 0xbfb8aa3b, v56
	v_exp_f32_e32 v61, v61
	v_rcp_f32_e32 v54, v63
	s_nop 0
	v_mul_f32_e32 v54, v55, v54
	v_add_f32_e32 v61, 1.0, v61
	v_mul_f32_e32 v51, v54, v51
	v_mul_f32_e32 v54, 0xbfb8aa3b, v57
	v_exp_f32_e32 v54, v54
	v_cvt_pk_bf16_f32 v60, v50, v51
	v_add_f32_e32 v54, 1.0, v54
	v_rcp_f32_e32 v50, v61
	s_nop 0
	v_mul_f32_e32 v50, v56, v50
	v_mul_f32_e32 v50, v50, v52
	v_mul_f32_e32 v52, 0xbfb8aa3b, v46
	v_exp_f32_e32 v52, v52
	v_rcp_f32_e32 v51, v54
	s_nop 0
	v_mul_f32_e32 v51, v57, v51
	v_mul_f32_e32 v51, v51, v53
	v_add_u32_e32 v66, 0x4080, v1
	v_add_f32_e32 v52, 1.0, v52
	v_cvt_pk_bf16_f32 v61, v50, v51
	v_mad_i64_i32 v[50:51], s[10:11], v66, s8, v[114:115]
	v_lshl_add_u64 v[50:51], v[50:51], 0, v[116:117]
	global_store_dwordx4 v[50:51], v[58:61], off
	v_mul_f32_e32 v55, 0xbfb8aa3b, v47
	v_exp_f32_e32 v55, v55
	s_nop 0
	v_add_f32_e32 v53, 1.0, v55
	v_rcp_f32_e32 v50, v52
	s_nop 0
	v_mul_f32_e32 v46, v46, v50
	v_mul_f32_e32 v42, v46, v42
	v_mul_f32_e32 v51, 0xbfb8aa3b, v48
	v_exp_f32_e32 v51, v51
	v_rcp_f32_e32 v46, v53
	s_nop 0
	v_mul_f32_e32 v46, v47, v46
	v_add_f32_e32 v50, 1.0, v51
	v_mul_f32_e32 v43, v46, v43
	v_mul_f32_e32 v47, 0xbfb8aa3b, v49
	v_cvt_pk_bf16_f32 v42, v42, v43
	v_exp_f32_e32 v47, v47
	s_nop 0
	v_add_f32_e32 v47, 1.0, v47
	v_rcp_f32_e32 v43, v50
	s_nop 0
	v_mul_f32_e32 v43, v48, v43
	v_mul_f32_e32 v43, v43, v44
	v_mul_f32_e32 v48, 0xbfb8aa3b, v38
	v_exp_f32_e32 v48, v48
	v_rcp_f32_e32 v44, v47
	s_nop 0
	v_mul_f32_e32 v44, v49, v44
	v_add_f32_e32 v46, 1.0, v48
	v_mul_f32_e32 v44, v44, v45
	v_mul_f32_e32 v47, 0xbfb8aa3b, v39
	v_cvt_pk_bf16_f32 v43, v43, v44
	v_exp_f32_e32 v47, v47
	s_nop 0
	v_add_f32_e32 v47, 1.0, v47
	v_rcp_f32_e32 v44, v46
	s_nop 0
	v_mul_f32_e32 v38, v38, v44
	v_mul_f32_e32 v34, v38, v34
	v_mul_f32_e32 v45, 0xbfb8aa3b, v40
	v_exp_f32_e32 v45, v45
	v_rcp_f32_e32 v38, v47
	s_nop 0
	v_mul_f32_e32 v38, v39, v38
	v_add_f32_e32 v45, 1.0, v45
	v_mul_f32_e32 v35, v38, v35
	v_mul_f32_e32 v38, 0xbfb8aa3b, v41
	v_exp_f32_e32 v38, v38
	v_cvt_pk_bf16_f32 v44, v34, v35
	v_add_f32_e32 v38, 1.0, v38
	v_rcp_f32_e32 v34, v45
	s_nop 0
	v_mul_f32_e32 v34, v40, v34
	v_mul_f32_e32 v34, v34, v36
	v_mul_f32_e32 v36, 0xbfb8aa3b, v30
	v_exp_f32_e32 v36, v36
	v_rcp_f32_e32 v35, v38
	s_nop 0
	v_mul_f32_e32 v35, v41, v35
	v_mul_f32_e32 v35, v35, v37
	v_cvt_pk_bf16_f32 v45, v34, v35
	v_add_f32_e32 v36, 1.0, v36
	v_add_u32_e32 v34, 0x4090, v1
	v_mad_i64_i32 v[34:35], s[10:11], v34, s8, v[114:115]
	v_lshl_add_u64 v[34:35], v[34:35], 0, v[116:117]
	global_store_dwordx4 v[34:35], v[42:45], off
	v_mul_f32_e32 v39, 0xbfb8aa3b, v31
	v_exp_f32_e32 v39, v39
	s_nop 0
	v_add_f32_e32 v37, 1.0, v39
	v_rcp_f32_e32 v34, v36
	s_nop 0
	v_mul_f32_e32 v30, v30, v34
	v_mul_f32_e32 v26, v30, v26
	v_mul_f32_e32 v35, 0xbfb8aa3b, v32
	v_exp_f32_e32 v35, v35
	v_rcp_f32_e32 v30, v37
	s_nop 0
	v_mul_f32_e32 v30, v31, v30
	v_add_f32_e32 v34, 1.0, v35
	v_mul_f32_e32 v27, v30, v27
	v_mul_f32_e32 v31, 0xbfb8aa3b, v33
	v_cvt_pk_bf16_f32 v26, v26, v27
	v_exp_f32_e32 v31, v31
	s_nop 0
	v_add_f32_e32 v31, 1.0, v31
	v_rcp_f32_e32 v27, v34
	s_nop 0
	v_mul_f32_e32 v27, v32, v27
	v_mul_f32_e32 v27, v27, v28
	v_mul_f32_e32 v32, 0xbfb8aa3b, v22
	v_exp_f32_e32 v32, v32
	v_rcp_f32_e32 v28, v31
	s_nop 0
	v_mul_f32_e32 v28, v33, v28
	v_add_f32_e32 v30, 1.0, v32
	v_mul_f32_e32 v28, v28, v29
	v_mul_f32_e32 v31, 0xbfb8aa3b, v23
	v_cvt_pk_bf16_f32 v27, v27, v28
	v_exp_f32_e32 v31, v31
	s_nop 0
	v_add_f32_e32 v31, 1.0, v31
	v_rcp_f32_e32 v28, v30
	s_nop 0
	v_mul_f32_e32 v22, v22, v28
	v_mul_f32_e32 v18, v22, v18
	v_mul_f32_e32 v29, 0xbfb8aa3b, v24
	v_exp_f32_e32 v29, v29
	v_rcp_f32_e32 v22, v31
	s_nop 0
	v_mul_f32_e32 v22, v23, v22
	v_add_f32_e32 v29, 1.0, v29
	v_mul_f32_e32 v19, v22, v19
	v_mul_f32_e32 v22, 0xbfb8aa3b, v25
	v_exp_f32_e32 v22, v22
	v_cvt_pk_bf16_f32 v28, v18, v19
	v_add_f32_e32 v22, 1.0, v22
	v_rcp_f32_e32 v18, v29
	s_nop 0
	v_mul_f32_e32 v18, v24, v18
	v_mul_f32_e32 v18, v18, v20
	v_mul_f32_e32 v20, 0xbfb8aa3b, v14
	v_exp_f32_e32 v20, v20
	v_rcp_f32_e32 v19, v22
	s_nop 0
	v_mul_f32_e32 v19, v25, v19
	v_mul_f32_e32 v19, v19, v21
	v_cvt_pk_bf16_f32 v29, v18, v19
	v_add_f32_e32 v20, 1.0, v20
	v_add_u32_e32 v18, 0x40a0, v1
	v_mad_i64_i32 v[18:19], s[10:11], v18, s8, v[114:115]
	v_lshl_add_u64 v[18:19], v[18:19], 0, v[116:117]
	global_store_dwordx4 v[18:19], v[26:29], off
	v_mul_f32_e32 v23, 0xbfb8aa3b, v15
	v_exp_f32_e32 v23, v23
	s_nop 0
	v_add_f32_e32 v21, 1.0, v23
	v_rcp_f32_e32 v18, v20
	s_nop 0
	v_mul_f32_e32 v14, v14, v18
	v_mul_f32_e32 v10, v14, v10
	v_mul_f32_e32 v19, 0xbfb8aa3b, v16
	v_exp_f32_e32 v19, v19
	v_rcp_f32_e32 v14, v21
	s_nop 0
	v_mul_f32_e32 v14, v15, v14
	v_add_f32_e32 v18, 1.0, v19
	v_mul_f32_e32 v11, v14, v11
	v_mul_f32_e32 v15, 0xbfb8aa3b, v17
	v_cvt_pk_bf16_f32 v10, v10, v11
	v_exp_f32_e32 v15, v15
	s_nop 0
	v_add_f32_e32 v15, 1.0, v15
	v_rcp_f32_e32 v11, v18
	s_nop 0
	v_mul_f32_e32 v11, v16, v11
	v_mul_f32_e32 v11, v11, v12
	v_mul_f32_e32 v16, 0xbfb8aa3b, v6
	v_exp_f32_e32 v16, v16
	v_rcp_f32_e32 v12, v15
	s_nop 0
	v_mul_f32_e32 v12, v17, v12
	v_add_f32_e32 v14, 1.0, v16
	v_mul_f32_e32 v12, v12, v13
	v_mul_f32_e32 v15, 0xbfb8aa3b, v7
	v_cvt_pk_bf16_f32 v11, v11, v12
	v_exp_f32_e32 v15, v15
	s_nop 0
	v_add_f32_e32 v15, 1.0, v15
	v_rcp_f32_e32 v12, v14
	s_nop 0
	v_mul_f32_e32 v6, v6, v12
	v_mul_f32_e32 v2, v6, v2
	v_mul_f32_e32 v13, 0xbfb8aa3b, v8
	v_exp_f32_e32 v13, v13
	v_rcp_f32_e32 v6, v15
	s_nop 0
	v_mul_f32_e32 v6, v7, v6
	v_add_f32_e32 v13, 1.0, v13
	v_mul_f32_e32 v3, v6, v3
	v_mul_f32_e32 v6, 0xbfb8aa3b, v9
	v_exp_f32_e32 v6, v6
	v_cvt_pk_bf16_f32 v12, v2, v3
	v_add_f32_e32 v6, 1.0, v6
	v_rcp_f32_e32 v2, v13
	s_nop 0
	v_mul_f32_e32 v2, v8, v2
	v_mul_f32_e32 v2, v2, v4
	v_rcp_f32_e32 v3, v6
	s_nop 0
	v_mul_f32_e32 v3, v9, v3
	v_mul_f32_e32 v3, v3, v5
	v_add_u32_e32 v1, 0x40b0, v1
	v_cvt_pk_bf16_f32 v13, v2, v3
	v_mad_i64_i32 v[2:3], s[8:9], v1, s8, v[114:115]
	v_lshl_add_u64 v[2:3], v[2:3], 0, v[116:117]
	global_store_dwordx4 v[2:3], v[10:13], off
	s_waitcnt vmcnt(0)
	s_barrier
	s_waitcnt vmcnt(0)
	s_waitcnt vmcnt(0) lgkmcnt(0)
	s_barrier
	s_mov_b64 s[8:9], exec
	v_readlane_b32 s10, v228, 2
	v_readlane_b32 s11, v228, 3
	s_and_b64 s[10:11], s[8:9], s[10:11]
	s_mov_b64 exec, s[10:11]
	s_cbranch_execz .LBB0_800
	s_mov_b64 s[10:11], exec
	v_mbcnt_lo_u32_b32 v1, s10, 0
	buffer_wbl2 sc1
	s_waitcnt vmcnt(0)
	v_mbcnt_hi_u32_b32 v1, s11, v1
	v_cmp_eq_u32_e32 vcc, 0, v1
	s_and_b64 s[18:19], exec, vcc
	s_mov_b64 exec, s[18:19]
	s_cbranch_execz .LBB0_800
	s_bcnt1_i32_b64 s10, s[10:11]
	v_mov_b32_e32 v1, 0
	v_mov_b32_e32 v2, s10
	global_atomic_add v1, v2, s[6:7]

.LBB0_863:
	v_mul_f32_e32 v154, 0xbfb8aa3b, v126
	v_exp_f32_e32 v155, v154
	v_mul_f32_e32 v162, 0xbfb8aa3b, v127
	v_exp_f32_e32 v162, v162
	v_lshl_or_b32 v156, s65, 7, v131
	v_add_f32_e32 v155, 1.0, v155
	v_lshl_add_u32 v154, s50, 8, v1
	v_add_f32_e32 v160, 1.0, v162
	v_rcp_f32_e32 v158, v155
	s_nop 0
	v_mul_f32_e32 v126, v126, v158
	v_mul_f32_e32 v122, v126, v122
	v_mul_f32_e32 v158, 0xbfb8aa3b, v128
	v_exp_f32_e32 v158, v158
	v_rcp_f32_e32 v126, v160
	s_nop 0
	v_mul_f32_e32 v126, v127, v126
	v_add_f32_e32 v155, 1.0, v158
	v_mul_f32_e32 v123, v126, v123
	v_mul_f32_e32 v127, 0xbfb8aa3b, v129
	v_cvt_pk_bf16_f32 v122, v122, v123
	v_exp_f32_e32 v127, v127
	s_nop 0
	v_add_f32_e32 v127, 1.0, v127
	v_rcp_f32_e32 v123, v155
	s_nop 0
	v_mul_f32_e32 v123, v128, v123
	v_mul_f32_e32 v123, v123, v124
	v_mul_f32_e32 v128, 0xbfb8aa3b, v118
	v_exp_f32_e32 v128, v128
	v_rcp_f32_e32 v124, v127
	s_nop 0
	v_mul_f32_e32 v124, v129, v124
	v_add_f32_e32 v126, 1.0, v128
	v_mul_f32_e32 v124, v124, v125
	v_mul_f32_e32 v127, 0xbfb8aa3b, v119
	v_cvt_pk_bf16_f32 v123, v123, v124
	v_exp_f32_e32 v127, v127
	s_nop 0
	v_add_f32_e32 v127, 1.0, v127
	v_rcp_f32_e32 v124, v126
	s_nop 0
	v_mul_f32_e32 v118, v118, v124
	v_mul_f32_e32 v114, v118, v114
	v_mul_f32_e32 v125, 0xbfb8aa3b, v120
	v_exp_f32_e32 v125, v125
	v_rcp_f32_e32 v118, v127
	s_nop 0
	v_mul_f32_e32 v118, v119, v118
	v_add_f32_e32 v125, 1.0, v125
	v_mul_f32_e32 v115, v118, v115
	v_mul_f32_e32 v118, 0xbfb8aa3b, v121
	v_exp_f32_e32 v118, v118
	v_cvt_pk_bf16_f32 v124, v114, v115
	v_add_f32_e32 v118, 1.0, v118
	v_rcp_f32_e32 v114, v125
	s_nop 0
	v_mul_f32_e32 v114, v120, v114
	v_mul_f32_e32 v114, v114, v116
	v_rcp_f32_e32 v115, v118
	s_nop 0
	v_mul_f32_e32 v115, v121, v115
	v_mul_f32_e32 v115, v115, v117
	v_cvt_pk_bf16_f32 v125, v114, v115
	v_mul_f32_e32 v114, 0xbfb8aa3b, v110
	v_exp_f32_e32 v116, v114
	v_ashrrev_i32_e32 v157, 31, v156
	v_mov_b64_e32 v[114:115], s[16:17]
	v_mad_i64_i32 v[118:119], s[52:53], v154, s64, v[114:115]
	v_add_f32_e32 v120, 1.0, v116
	v_lshlrev_b64 v[116:117], 1, v[156:157]
	v_lshl_add_u64 v[118:119], v[118:119], 0, v[116:117]
	global_store_dwordx4 v[118:119], v[122:125], off
	s_nop 1
	v_mul_f32_e32 v122, 0xbfb8aa3b, v111
	v_exp_f32_e32 v122, v122
	s_nop 0
	v_add_f32_e32 v121, 1.0, v122
	v_rcp_f32_e32 v118, v120
	s_nop 0
	v_mul_f32_e32 v110, v110, v118
	v_mul_f32_e32 v106, v110, v106
	v_mul_f32_e32 v119, 0xbfb8aa3b, v112
	v_exp_f32_e32 v119, v119
	v_rcp_f32_e32 v110, v121
	s_nop 0
	v_mul_f32_e32 v110, v111, v110
	v_add_f32_e32 v118, 1.0, v119
	v_mul_f32_e32 v107, v110, v107
	v_mul_f32_e32 v111, 0xbfb8aa3b, v113
	v_cvt_pk_bf16_f32 v106, v106, v107
	v_exp_f32_e32 v111, v111
	s_nop 0
	v_add_f32_e32 v111, 1.0, v111
	v_rcp_f32_e32 v107, v118
	s_nop 0
	v_mul_f32_e32 v107, v112, v107
	v_mul_f32_e32 v107, v107, v108
	v_mul_f32_e32 v112, 0xbfb8aa3b, v102
	v_exp_f32_e32 v112, v112
	v_rcp_f32_e32 v108, v111
	s_nop 0
	v_mul_f32_e32 v108, v113, v108
	v_add_f32_e32 v110, 1.0, v112
	v_mul_f32_e32 v108, v108, v109
	v_mul_f32_e32 v111, 0xbfb8aa3b, v103
	v_cvt_pk_bf16_f32 v107, v107, v108
	v_exp_f32_e32 v111, v111
	s_nop 0
	v_add_f32_e32 v111, 1.0, v111
	v_rcp_f32_e32 v108, v110
	s_nop 0
	v_mul_f32_e32 v102, v102, v108
	v_mul_f32_e32 v98, v102, v98
	v_mul_f32_e32 v109, 0xbfb8aa3b, v104
	v_exp_f32_e32 v109, v109
	v_rcp_f32_e32 v102, v111
	s_nop 0
	v_mul_f32_e32 v102, v103, v102
	v_add_f32_e32 v109, 1.0, v109
	v_mul_f32_e32 v99, v102, v99
	v_mul_f32_e32 v102, 0xbfb8aa3b, v105
	v_exp_f32_e32 v102, v102
	v_cvt_pk_bf16_f32 v108, v98, v99
	v_add_f32_e32 v102, 1.0, v102
	v_rcp_f32_e32 v98, v109
	s_nop 0
	v_mul_f32_e32 v98, v104, v98
	v_mul_f32_e32 v98, v98, v100
	v_mul_f32_e32 v100, 0xbfb8aa3b, v94
	v_exp_f32_e32 v100, v100
	v_rcp_f32_e32 v99, v102
	s_nop 0
	v_mul_f32_e32 v99, v105, v99
	v_mul_f32_e32 v99, v99, v101
	v_cvt_pk_bf16_f32 v109, v98, v99
	v_add_f32_e32 v100, 1.0, v100
	v_or_b32_e32 v98, 16, v154
	v_mad_i64_i32 v[98:99], s[52:53], v98, s64, v[114:115]
	v_lshl_add_u64 v[98:99], v[98:99], 0, v[116:117]
	global_store_dwordx4 v[98:99], v[106:109], off
	v_mul_f32_e32 v103, 0xbfb8aa3b, v95
	v_exp_f32_e32 v103, v103
	s_nop 0
	v_add_f32_e32 v101, 1.0, v103
	v_rcp_f32_e32 v98, v100
	s_nop 0
	v_mul_f32_e32 v94, v94, v98
	v_mul_f32_e32 v90, v94, v90
	v_mul_f32_e32 v99, 0xbfb8aa3b, v96
	v_exp_f32_e32 v99, v99
	v_rcp_f32_e32 v94, v101
	s_nop 0
	v_mul_f32_e32 v94, v95, v94
	v_add_f32_e32 v98, 1.0, v99
	v_mul_f32_e32 v91, v94, v91
	v_mul_f32_e32 v95, 0xbfb8aa3b, v97
	v_cvt_pk_bf16_f32 v90, v90, v91
	v_exp_f32_e32 v95, v95
	s_nop 0
	v_add_f32_e32 v95, 1.0, v95
	v_rcp_f32_e32 v91, v98
	s_nop 0
	v_mul_f32_e32 v91, v96, v91
	v_mul_f32_e32 v91, v91, v92
	v_mul_f32_e32 v96, 0xbfb8aa3b, v86
	v_exp_f32_e32 v96, v96
	v_rcp_f32_e32 v92, v95
	s_nop 0
	v_mul_f32_e32 v92, v97, v92
	v_add_f32_e32 v94, 1.0, v96
	v_mul_f32_e32 v92, v92, v93
	v_mul_f32_e32 v95, 0xbfb8aa3b, v87
	v_cvt_pk_bf16_f32 v91, v91, v92
	v_exp_f32_e32 v95, v95
	s_nop 0
	v_add_f32_e32 v95, 1.0, v95
	v_rcp_f32_e32 v92, v94
	s_nop 0
	v_mul_f32_e32 v86, v86, v92
	v_mul_f32_e32 v82, v86, v82
	v_mul_f32_e32 v93, 0xbfb8aa3b, v88
	v_exp_f32_e32 v93, v93
	v_rcp_f32_e32 v86, v95
	s_nop 0
	v_mul_f32_e32 v86, v87, v86
	v_add_f32_e32 v93, 1.0, v93
	v_mul_f32_e32 v83, v86, v83
	v_mul_f32_e32 v86, 0xbfb8aa3b, v89
	v_exp_f32_e32 v86, v86
	v_cvt_pk_bf16_f32 v92, v82, v83
	v_add_f32_e32 v86, 1.0, v86
	v_rcp_f32_e32 v82, v93
	s_nop 0
	v_mul_f32_e32 v82, v88, v82
	v_mul_f32_e32 v82, v82, v84
	v_mul_f32_e32 v84, 0xbfb8aa3b, v78
	v_exp_f32_e32 v84, v84
	v_rcp_f32_e32 v83, v86
	s_nop 0
	v_mul_f32_e32 v83, v89, v83
	v_mul_f32_e32 v83, v83, v85
	v_cvt_pk_bf16_f32 v93, v82, v83
	v_add_f32_e32 v84, 1.0, v84
	v_or_b32_e32 v82, 32, v154
	v_mad_i64_i32 v[82:83], s[52:53], v82, s64, v[114:115]
	v_lshl_add_u64 v[82:83], v[82:83], 0, v[116:117]
	global_store_dwordx4 v[82:83], v[90:93], off
	v_mul_f32_e32 v87, 0xbfb8aa3b, v79
	v_exp_f32_e32 v87, v87
	s_nop 0
	v_add_f32_e32 v85, 1.0, v87
	v_rcp_f32_e32 v82, v84
	s_nop 0
	v_mul_f32_e32 v78, v78, v82
	v_mul_f32_e32 v74, v78, v74
	v_mul_f32_e32 v83, 0xbfb8aa3b, v80
	v_exp_f32_e32 v83, v83
	v_rcp_f32_e32 v78, v85
	s_nop 0
	v_mul_f32_e32 v78, v79, v78
	v_add_f32_e32 v82, 1.0, v83
	v_mul_f32_e32 v75, v78, v75
	v_mul_f32_e32 v79, 0xbfb8aa3b, v81
	v_cvt_pk_bf16_f32 v74, v74, v75
	v_exp_f32_e32 v79, v79
	s_nop 0
	v_add_f32_e32 v79, 1.0, v79
	v_rcp_f32_e32 v75, v82
	s_nop 0
	v_mul_f32_e32 v75, v80, v75
	v_mul_f32_e32 v75, v75, v76
	v_mul_f32_e32 v80, 0xbfb8aa3b, v70
	v_exp_f32_e32 v80, v80
	v_rcp_f32_e32 v76, v79
	s_nop 0
	v_mul_f32_e32 v76, v81, v76
	v_add_f32_e32 v78, 1.0, v80
	v_mul_f32_e32 v76, v76, v77
	v_mul_f32_e32 v79, 0xbfb8aa3b, v71
	v_cvt_pk_bf16_f32 v75, v75, v76
	v_exp_f32_e32 v79, v79
	s_nop 0
	v_add_f32_e32 v79, 1.0, v79
	v_rcp_f32_e32 v76, v78
	s_nop 0
	v_mul_f32_e32 v70, v70, v76
	v_mul_f32_e32 v66, v70, v66
	v_mul_f32_e32 v77, 0xbfb8aa3b, v72
	v_exp_f32_e32 v77, v77
	v_rcp_f32_e32 v70, v79
	s_nop 0
	v_mul_f32_e32 v70, v71, v70
	v_add_f32_e32 v77, 1.0, v77
	v_mul_f32_e32 v67, v70, v67
	v_mul_f32_e32 v70, 0xbfb8aa3b, v73
	v_exp_f32_e32 v70, v70
	v_cvt_pk_bf16_f32 v76, v66, v67
	v_add_f32_e32 v70, 1.0, v70
	v_rcp_f32_e32 v66, v77
	s_nop 0
	v_mul_f32_e32 v66, v72, v66
	v_mul_f32_e32 v66, v66, v68
	v_rcp_f32_e32 v67, v70
	s_nop 0
	v_mul_f32_e32 v67, v73, v67
	v_mul_f32_e32 v67, v67, v69
	v_cvt_pk_bf16_f32 v77, v66, v67
	v_mul_f32_e32 v66, 0xbfb8aa3b, v62
	v_exp_f32_e32 v68, v66
	v_or_b32_e32 v66, 48, v154
	v_mad_i64_i32 v[66:67], s[52:53], v66, s64, v[114:115]
	v_add_f32_e32 v68, 1.0, v68
	v_lshl_add_u64 v[66:67], v[66:67], 0, v[116:117]
	global_store_dwordx4 v[66:67], v[74:77], off
	v_mul_f32_e32 v72, 0xbfb8aa3b, v63
	v_exp_f32_e32 v72, v72
	s_nop 0
	v_add_f32_e32 v69, 1.0, v72
	v_rcp_f32_e32 v67, v68
	s_nop 0
	v_mul_f32_e32 v62, v62, v67
	v_mul_f32_e32 v58, v62, v58
	v_mul_f32_e32 v68, 0xbfb8aa3b, v64
	v_exp_f32_e32 v68, v68
	v_rcp_f32_e32 v62, v69
	s_nop 0
	v_mul_f32_e32 v62, v63, v62
	v_add_f32_e32 v67, 1.0, v68
	v_mul_f32_e32 v59, v62, v59
	v_mul_f32_e32 v63, 0xbfb8aa3b, v65
	v_cvt_pk_bf16_f32 v58, v58, v59
	v_exp_f32_e32 v63, v63
	s_nop 0
	v_add_f32_e32 v63, 1.0, v63
	v_rcp_f32_e32 v59, v67
	s_nop 0
	v_mul_f32_e32 v59, v64, v59
	v_mul_f32_e32 v59, v59, v60
	v_mul_f32_e32 v64, 0xbfb8aa3b, v54
	v_exp_f32_e32 v64, v64
	v_rcp_f32_e32 v60, v63
	s_nop 0
	v_mul_f32_e32 v60, v65, v60
	v_add_f32_e32 v62, 1.0, v64
	v_mul_f32_e32 v60, v60, v61
	v_mul_f32_e32 v63, 0xbfb8aa3b, v55
	v_cvt_pk_bf16_f32 v59, v59, v60
	v_exp_f32_e32 v63, v63
	s_nop 0
	v_add_f32_e32 v63, 1.0, v63
	v_rcp_f32_e32 v60, v62
	s_nop 0
	v_mul_f32_e32 v54, v54, v60
	v_mul_f32_e32 v50, v54, v50
	v_mul_f32_e32 v61, 0xbfb8aa3b, v56
	v_exp_f32_e32 v61, v61
	v_rcp_f32_e32 v54, v63
	s_nop 0
	v_mul_f32_e32 v54, v55, v54
	v_add_f32_e32 v61, 1.0, v61
	v_mul_f32_e32 v51, v54, v51
	v_mul_f32_e32 v54, 0xbfb8aa3b, v57
	v_exp_f32_e32 v54, v54
	v_cvt_pk_bf16_f32 v60, v50, v51
	v_add_f32_e32 v54, 1.0, v54
	v_rcp_f32_e32 v50, v61
	s_nop 0
	v_mul_f32_e32 v50, v56, v50
	v_mul_f32_e32 v50, v50, v52
	v_mul_f32_e32 v52, 0xbfb8aa3b, v46
	v_exp_f32_e32 v52, v52
	v_rcp_f32_e32 v51, v54
	s_nop 0
	v_mul_f32_e32 v51, v57, v51
	v_mul_f32_e32 v51, v51, v53
	v_add_u32_e32 v66, 0x80, v154
	v_add_f32_e32 v52, 1.0, v52
	v_cvt_pk_bf16_f32 v61, v50, v51
	v_mad_i64_i32 v[50:51], s[52:53], v66, s64, v[114:115]
	v_lshl_add_u64 v[50:51], v[50:51], 0, v[116:117]
	global_store_dwordx4 v[50:51], v[58:61], off
	v_mul_f32_e32 v55, 0xbfb8aa3b, v47
	v_exp_f32_e32 v55, v55
	s_nop 0
	v_add_f32_e32 v53, 1.0, v55
	v_rcp_f32_e32 v50, v52
	s_nop 0
	v_mul_f32_e32 v46, v46, v50
	v_mul_f32_e32 v42, v46, v42
	v_mul_f32_e32 v51, 0xbfb8aa3b, v48
	v_exp_f32_e32 v51, v51
	v_rcp_f32_e32 v46, v53
	s_nop 0
	v_mul_f32_e32 v46, v47, v46
	v_add_f32_e32 v50, 1.0, v51
	v_mul_f32_e32 v43, v46, v43
	v_mul_f32_e32 v47, 0xbfb8aa3b, v49
	v_cvt_pk_bf16_f32 v42, v42, v43
	v_exp_f32_e32 v47, v47
	s_nop 0
	v_add_f32_e32 v47, 1.0, v47
	v_rcp_f32_e32 v43, v50
	s_nop 0
	v_mul_f32_e32 v43, v48, v43
	v_mul_f32_e32 v43, v43, v44
	v_mul_f32_e32 v48, 0xbfb8aa3b, v38
	v_exp_f32_e32 v48, v48
	v_rcp_f32_e32 v44, v47
	s_nop 0
	v_mul_f32_e32 v44, v49, v44
	v_add_f32_e32 v46, 1.0, v48
	v_mul_f32_e32 v44, v44, v45
	v_mul_f32_e32 v47, 0xbfb8aa3b, v39
	v_cvt_pk_bf16_f32 v43, v43, v44
	v_exp_f32_e32 v47, v47
	s_nop 0
	v_add_f32_e32 v47, 1.0, v47
	v_rcp_f32_e32 v44, v46
	s_nop 0
	v_mul_f32_e32 v38, v38, v44
	v_mul_f32_e32 v34, v38, v34
	v_mul_f32_e32 v45, 0xbfb8aa3b, v40
	v_exp_f32_e32 v45, v45
	v_rcp_f32_e32 v38, v47
	s_nop 0
	v_mul_f32_e32 v38, v39, v38
	v_add_f32_e32 v45, 1.0, v45
	v_mul_f32_e32 v35, v38, v35
	v_mul_f32_e32 v38, 0xbfb8aa3b, v41
	v_exp_f32_e32 v38, v38
	v_cvt_pk_bf16_f32 v44, v34, v35
	v_add_f32_e32 v38, 1.0, v38
	v_rcp_f32_e32 v34, v45
	s_nop 0
	v_mul_f32_e32 v34, v40, v34
	v_mul_f32_e32 v34, v34, v36
	v_mul_f32_e32 v36, 0xbfb8aa3b, v30
	v_exp_f32_e32 v36, v36
	v_rcp_f32_e32 v35, v38
	s_nop 0
	v_mul_f32_e32 v35, v41, v35
	v_mul_f32_e32 v35, v35, v37
	v_cvt_pk_bf16_f32 v45, v34, v35
	v_add_f32_e32 v36, 1.0, v36
	v_add_u32_e32 v34, 0x90, v154
	v_mad_i64_i32 v[34:35], s[52:53], v34, s64, v[114:115]
	v_lshl_add_u64 v[34:35], v[34:35], 0, v[116:117]
	global_store_dwordx4 v[34:35], v[42:45], off
	v_mul_f32_e32 v39, 0xbfb8aa3b, v31
	v_exp_f32_e32 v39, v39
	s_nop 0
	v_add_f32_e32 v37, 1.0, v39
	v_rcp_f32_e32 v34, v36
	s_nop 0
	v_mul_f32_e32 v30, v30, v34
	v_mul_f32_e32 v26, v30, v26
	v_mul_f32_e32 v35, 0xbfb8aa3b, v32
	v_exp_f32_e32 v35, v35
	v_rcp_f32_e32 v30, v37
	s_nop 0
	v_mul_f32_e32 v30, v31, v30
	v_add_f32_e32 v34, 1.0, v35
	v_mul_f32_e32 v27, v30, v27
	v_mul_f32_e32 v31, 0xbfb8aa3b, v33
	v_cvt_pk_bf16_f32 v26, v26, v27
	v_exp_f32_e32 v31, v31
	s_nop 0
	v_add_f32_e32 v31, 1.0, v31
	v_rcp_f32_e32 v27, v34
	s_nop 0
	v_mul_f32_e32 v27, v32, v27
	v_mul_f32_e32 v27, v27, v28
	v_mul_f32_e32 v32, 0xbfb8aa3b, v22
	v_exp_f32_e32 v32, v32
	v_rcp_f32_e32 v28, v31
	s_nop 0
	v_mul_f32_e32 v28, v33, v28
	v_add_f32_e32 v30, 1.0, v32
	v_mul_f32_e32 v28, v28, v29
	v_mul_f32_e32 v31, 0xbfb8aa3b, v23
	v_cvt_pk_bf16_f32 v27, v27, v28
	v_exp_f32_e32 v31, v31
	s_nop 0
	v_add_f32_e32 v31, 1.0, v31
	v_rcp_f32_e32 v28, v30
	s_nop 0
	v_mul_f32_e32 v22, v22, v28
	v_mul_f32_e32 v18, v22, v18
	v_mul_f32_e32 v29, 0xbfb8aa3b, v24
	v_exp_f32_e32 v29, v29
	v_rcp_f32_e32 v22, v31
	s_nop 0
	v_mul_f32_e32 v22, v23, v22
	v_add_f32_e32 v29, 1.0, v29
	v_mul_f32_e32 v19, v22, v19
	v_mul_f32_e32 v22, 0xbfb8aa3b, v25
	v_exp_f32_e32 v22, v22
	v_cvt_pk_bf16_f32 v28, v18, v19
	v_add_f32_e32 v22, 1.0, v22
	v_rcp_f32_e32 v18, v29
	s_nop 0
	v_mul_f32_e32 v18, v24, v18
	v_mul_f32_e32 v18, v18, v20
	v_mul_f32_e32 v20, 0xbfb8aa3b, v14
	v_exp_f32_e32 v20, v20
	v_rcp_f32_e32 v19, v22
	s_nop 0
	v_mul_f32_e32 v19, v25, v19
	v_mul_f32_e32 v19, v19, v21
	v_cvt_pk_bf16_f32 v29, v18, v19
	v_add_f32_e32 v20, 1.0, v20
	v_add_u32_e32 v18, 0xa0, v154
	v_mad_i64_i32 v[18:19], s[52:53], v18, s64, v[114:115]
	v_lshl_add_u64 v[18:19], v[18:19], 0, v[116:117]
	global_store_dwordx4 v[18:19], v[26:29], off
	v_mul_f32_e32 v23, 0xbfb8aa3b, v15
	v_exp_f32_e32 v23, v23
	s_nop 0
	v_add_f32_e32 v21, 1.0, v23
	v_rcp_f32_e32 v18, v20
	s_nop 0
	v_mul_f32_e32 v14, v14, v18
	v_mul_f32_e32 v10, v14, v10
	v_mul_f32_e32 v19, 0xbfb8aa3b, v16
	v_exp_f32_e32 v19, v19
	v_rcp_f32_e32 v14, v21
	s_nop 0
	v_mul_f32_e32 v14, v15, v14
	v_add_f32_e32 v18, 1.0, v19
	v_mul_f32_e32 v11, v14, v11
	v_mul_f32_e32 v15, 0xbfb8aa3b, v17
	v_cvt_pk_bf16_f32 v10, v10, v11
	v_exp_f32_e32 v15, v15
	s_nop 0
	v_add_f32_e32 v15, 1.0, v15
	v_rcp_f32_e32 v11, v18
	s_nop 0
	v_mul_f32_e32 v11, v16, v11
	v_mul_f32_e32 v11, v11, v12
	v_mul_f32_e32 v16, 0xbfb8aa3b, v6
	v_exp_f32_e32 v16, v16
	v_rcp_f32_e32 v12, v15
	s_nop 0
	v_mul_f32_e32 v12, v17, v12
	v_add_f32_e32 v14, 1.0, v16
	v_mul_f32_e32 v12, v12, v13
	v_mul_f32_e32 v15, 0xbfb8aa3b, v7
	v_cvt_pk_bf16_f32 v11, v11, v12
	v_exp_f32_e32 v15, v15
	s_nop 0
	v_add_f32_e32 v15, 1.0, v15
	v_rcp_f32_e32 v12, v14
	s_nop 0
	v_mul_f32_e32 v6, v6, v12
	v_mul_f32_e32 v2, v6, v2
	v_mul_f32_e32 v13, 0xbfb8aa3b, v8
	v_exp_f32_e32 v13, v13
	v_rcp_f32_e32 v6, v15
	s_nop 0
	v_mul_f32_e32 v6, v7, v6
	v_add_f32_e32 v13, 1.0, v13
	v_mul_f32_e32 v3, v6, v3
	v_mul_f32_e32 v6, 0xbfb8aa3b, v9
	v_exp_f32_e32 v6, v6
	v_cvt_pk_bf16_f32 v12, v2, v3
	v_add_f32_e32 v6, 1.0, v6
	v_rcp_f32_e32 v2, v13
	s_nop 0
	v_mul_f32_e32 v2, v8, v2
	v_mul_f32_e32 v2, v2, v4
	v_rcp_f32_e32 v3, v6
	s_nop 0
	v_mul_f32_e32 v3, v9, v3
	v_mul_f32_e32 v3, v3, v5
	v_cvt_pk_bf16_f32 v13, v2, v3
	v_add_u32_e32 v2, 0xb0, v154
	v_mad_i64_i32 v[2:3], s[52:53], v2, s64, v[114:115]
	v_lshl_add_u64 v[2:3], v[2:3], 0, v[116:117]
	s_andn2_b64 vcc, exec, s[46:47]
	s_mov_b64 s[46:47], -1
	global_store_dwordx4 v[2:3], v[10:13], off
	s_cbranch_vccnz .LBB0_852
	s_andn2_b64 vcc, exec, s[6:7]
	s_cbranch_vccnz .LBB0_851
	s_barrier
	s_branch .LBB0_851

.LBB0_2749:
	s_or_b32 s6, s14, 1
	s_ashr_i32 s7, s6, 31
	s_lshl_b32 s26, s10, 6
	s_lshl_b32 s27, s11, 6
	s_add_i32 s28, s14, 0x601
	s_lshl_b64 s[6:7], s[6:7], 10
	v_lshrrev_b32_e32 v100, 4, v1
	s_add_u32 s8, s18, s52
	v_or_b32_e32 v14, s26, v100
	s_addc_u32 s9, s19, 0
	v_or_b32_e32 v17, 4, v14
	s_add_u32 s29, s8, 0xc00
	v_subrev_u32_e32 v12, s26, v17
	v_lshl_add_u64 v[104:105], v[6:7], 0, s[52:53]
	s_addc_u32 s30, s9, 0
	v_lshlrev_b32_e32 v98, 10, v100
	v_ashrrev_i32_e32 v13, 31, v12
	v_lshl_add_u64 v[2:3], v[104:105], 0, v[98:99]
	v_mov_b32_e32 v15, s30
	v_cmp_gt_i32_e32 vcc, s44, v14
	v_mov_b32_e32 v16, s29
	v_lshlrev_b64 v[12:13], 10, v[12:13]
	v_and_b32_e32 v50, 15, v138
	v_cndmask_b32_e32 v3, v15, v3, vcc
	v_cndmask_b32_e32 v2, v16, v2, vcc
	v_lshl_add_u64 v[12:13], v[104:105], 0, v[12:13]
	v_cmp_gt_i32_e32 vcc, s44, v17
	v_lshlrev_b32_e32 v98, 4, v50
	v_lshl_add_u64 v[6:7], v[2:3], 0, v[98:99]
	v_cndmask_b32_e32 v13, v15, v13, vcc
	v_cndmask_b32_e32 v12, v16, v12, vcc
	v_lshl_add_u64 v[12:13], v[12:13], 0, v[98:99]
	v_or_b32_e32 v17, 8, v14
	global_load_dwordx4 v[2:5], v[6:7], off
	s_nop 0
	global_load_dwordx4 v[6:9], v[6:7], off offset:512
	s_nop 0
	global_load_dwordx4 v[26:29], v[12:13], off
	global_load_dwordx4 v[30:33], v[12:13], off offset:512
	v_subrev_u32_e32 v12, s26, v17
	v_ashrrev_i32_e32 v13, 31, v12
	v_lshlrev_b64 v[12:13], 10, v[12:13]
	v_lshl_add_u64 v[12:13], v[104:105], 0, v[12:13]
	v_cmp_gt_i32_e32 vcc, s44, v17
	v_or_b32_e32 v14, 12, v14
	v_lshl_add_u64 v[108:109], v[42:43], 0, s[52:53]
	v_cndmask_b32_e32 v13, v15, v13, vcc
	v_cndmask_b32_e32 v12, v16, v12, vcc
	v_lshl_add_u64 v[12:13], v[12:13], 0, v[98:99]
	global_load_dwordx4 v[34:37], v[12:13], off
	global_load_dwordx4 v[38:41], v[12:13], off offset:512
	v_subrev_u32_e32 v12, s26, v14
	v_ashrrev_i32_e32 v13, 31, v12
	v_lshlrev_b64 v[12:13], 10, v[12:13]
	v_lshl_add_u64 v[12:13], v[104:105], 0, v[12:13]
	v_cmp_gt_i32_e32 vcc, s44, v14
	v_and_b32_e32 v43, 64, v166
	v_xor_b32_e32 v42, 1, v166
	v_cndmask_b32_e32 v13, v15, v13, vcc
	v_cndmask_b32_e32 v12, v16, v12, vcc
	v_lshl_add_u64 v[12:13], v[12:13], 0, v[98:99]
	global_load_dwordx4 v[46:49], v[12:13], off
	global_load_dwordx4 v[54:57], v[12:13], off offset:512
	v_add_u32_e32 v43, 64, v43
	v_cmp_lt_i32_e32 vcc, v42, v43
	v_lshl_add_u64 v[10:11], v[10:11], 0, s[56:57]
	v_lshl_add_u64 v[10:11], v[10:11], 0, s[6:7]
	v_cndmask_b32_e32 v42, v166, v42, vcc
	v_lshlrev_b32_e32 v138, 2, v42
	v_xor_b32_e32 v42, 2, v166
	v_cmp_lt_i32_e32 vcc, v42, v43
	v_lshlrev_b32_e32 v103, 4, v1
	v_lshl_add_u64 v[106:107], v[10:11], 0, s[52:53]
	v_cndmask_b32_e32 v42, v166, v42, vcc
	v_lshlrev_b32_e32 v139, 2, v42
	v_xor_b32_e32 v42, 4, v166
	v_cmp_lt_i32_e32 vcc, v42, v43
	v_and_b32_e32 v10, 0xf0, v103
	v_add_u32_e32 v22, s36, v10
	v_cndmask_b32_e32 v42, v166, v42, vcc
	v_lshlrev_b32_e32 v140, 2, v42
	v_xor_b32_e32 v42, 8, v166
	v_cmp_lt_i32_e32 vcc, v42, v43
	ds_read_b128 v[10:13], v22
	ds_read_b128 v[14:17], v22 offset:256
	ds_read_b128 v[18:21], v22 offset:512
	ds_read_b128 v[22:25], v22 offset:768
	v_cndmask_b32_e32 v42, v166, v42, vcc
	v_lshlrev_b32_e32 v141, 2, v42
	v_xor_b32_e32 v42, 16, v166
	v_cmp_lt_i32_e32 vcc, v42, v43
	v_mov_b32_e32 v44, v99
	v_mov_b32_e32 v45, v99
	v_cndmask_b32_e32 v42, v166, v42, vcc
	v_lshlrev_b32_e32 v142, 2, v42
	v_xor_b32_e32 v42, 32, v166
	v_cmp_lt_i32_e32 vcc, v42, v43
	s_add_u32 s31, s8, 0x1000
	v_mov_b32_e32 v43, v99
	v_cndmask_b32_e32 v42, v166, v42, vcc
	v_lshlrev_b32_e32 v143, 2, v42
	v_mov_b32_e32 v42, v99
	v_mov_b32_e32 v111, 0xff800000
	v_mov_b32_e32 v110, 0
	v_lshlrev_b32_e32 v98, 4, v50
	v_mov_b64_e32 v[52:53], v[44:45]
	v_mov_b64_e32 v[60:61], v[44:45]
	v_mov_b64_e32 v[64:65], v[44:45]
	s_addc_u32 s48, s9, 0
	s_mov_b32 s52, 0
	s_mov_b32 s49, 32
	v_cmp_eq_u32_e64 s[6:7], 0, v1
	v_cmp_gt_u32_e64 s[8:9], 16, v1
	v_mov_b64_e32 v[50:51], v[42:43]
	v_mov_b64_e32 v[58:59], v[42:43]
	v_mov_b64_e32 v[62:63], v[42:43]
	v_mov_b32_e32 v114, v110
	v_mov_b32_e32 v115, v111
	v_mov_b32_e32 v116, v110
	v_mov_b32_e32 v117, v111
	v_mov_b32_e32 v112, v110
	v_mov_b32_e32 v113, v111
	s_branch .LBB0_2752

.LBB0_2752:
	s_lshr_b32 s10, s52, 2
	s_cmp_lt_u32 s52, 4
	s_cselect_b64 vcc, -1, 0
	s_cmp_eq_u32 s10, 2
	s_cselect_b32 s12, s31, s29
	s_cselect_b32 s13, s48, s30
	s_cmp_eq_u32 s10, 1
	s_cselect_b64 s[10:11], -1, 0
	v_cndmask_b32_e64 v66, v106, v108, s[10:11]
	v_cndmask_b32_e64 v67, v107, v109, s[10:11]
	s_and_b64 s[10:11], s[10:11], exec
	s_cselect_b32 s14, s27, s28
	s_and_b64 s[10:11], vcc, exec
	s_cselect_b32 s14, s26, s14
	s_sub_i32 s10, s49, 32
	s_and_b32 s15, s10, 32
	s_or_b32 s10, s15, s14
	v_add_u32_e32 v80, s10, v100
	v_add_u32_e32 v144, 16, v80
	v_cndmask_b32_e32 v78, v66, v104, vcc
	v_subrev_u32_e32 v66, s14, v144
	v_cndmask_b32_e32 v79, v67, v105, vcc
	v_ashrrev_i32_e32 v67, 31, v66
	v_lshlrev_b64 v[66:67], 10, v[66:67]
	v_lshl_add_u64 v[66:67], v[78:79], 0, v[66:67]
	v_mov_b32_e32 v82, s13
	v_cmp_gt_i32_e64 s[10:11], s44, v144
	v_mov_b32_e32 v83, s12
	v_add_u32_e32 v147, 20, v80
	v_cndmask_b32_e64 v67, v82, v67, s[10:11]
	v_cndmask_b32_e64 v66, v83, v66, s[10:11]
	v_lshl_add_u64 v[66:67], v[66:67], 0, v[98:99]
	v_add_u32_e32 v146, 24, v80
	v_add_u32_e32 v145, 28, v80
	global_load_dwordx4 v[94:97], v[66:67], off
	global_load_dwordx4 v[74:77], v[66:67], off offset:512
	v_subrev_u32_e32 v66, s14, v147
	v_subrev_u32_e32 v70, s14, v146
	v_subrev_u32_e32 v80, s14, v145
	v_ashrrev_i32_e32 v67, 31, v66
	v_ashrrev_i32_e32 v71, 31, v70
	v_ashrrev_i32_e32 v81, 31, v80
	v_lshlrev_b64 v[66:67], 10, v[66:67]
	v_lshlrev_b64 v[70:71], 10, v[70:71]
	v_lshlrev_b64 v[80:81], 10, v[80:81]
	v_lshl_add_u64 v[66:67], v[78:79], 0, v[66:67]
	v_lshl_add_u64 v[70:71], v[78:79], 0, v[70:71]
	v_lshl_add_u64 v[78:79], v[78:79], 0, v[80:81]
	s_waitcnt vmcnt(0) lgkmcnt(0)
	v_mul_f32_e32 v80, v11, v3
	v_fmac_f32_e32 v80, v10, v2
	v_fmac_f32_e32 v80, v12, v4
	v_fmac_f32_e32 v80, v13, v5
	ds_bpermute_b32 v81, v138, v80
	v_cmp_gt_i32_e64 s[10:11], s44, v147
	v_mul_f32_e32 v148, v11, v27
	v_fmac_f32_e32 v148, v10, v26
	v_cndmask_b32_e64 v67, v82, v67, s[10:11]
	s_waitcnt lgkmcnt(0)
	v_add_f32_e32 v80, v80, v81
	v_cndmask_b32_e64 v66, v83, v66, s[10:11]
	v_cmp_gt_i32_e64 s[10:11], s44, v146
	ds_bpermute_b32 v81, v139, v80
	v_mul_f32_e32 v125, v23, v3
	v_cndmask_b32_e64 v71, v82, v71, s[10:11]
	v_cndmask_b32_e64 v70, v83, v70, s[10:11]
	v_cmp_gt_i32_e64 s[10:11], s44, v145
	s_waitcnt lgkmcnt(0)
	v_add_f32_e32 v80, v80, v81
	ds_bpermute_b32 v81, v140, v80
	v_cndmask_b32_e64 v79, v82, v79, s[10:11]
	v_mul_f32_e32 v82, v15, v3
	v_fmac_f32_e32 v82, v14, v2
	v_fmac_f32_e32 v82, v16, v4
	v_fmac_f32_e32 v82, v17, v5
	v_cndmask_b32_e64 v78, v83, v78, s[10:11]
	ds_bpermute_b32 v83, v138, v82
	s_and_b32 s10, s52, 12
	s_waitcnt lgkmcnt(1)
	v_add_f32_e32 v118, v80, v81
	s_cmp_eq_u32 s10, 4
	ds_bpermute_b32 v119, v141, v118
	s_waitcnt lgkmcnt(1)
	v_add_f32_e32 v120, v82, v83
	ds_bpermute_b32 v121, v139, v120
	s_cselect_b32 s12, s27, s28
	s_and_b64 s[10:11], vcc, exec
	s_cselect_b32 s10, s26, s12
	s_or_b32 s10, s10, s15
	v_add_u32_e32 v156, s10, v100
	v_sub_u32_e32 v84, 0x800, v156
	s_waitcnt lgkmcnt(1)
	v_add_f32_e32 v118, v118, v119
	s_waitcnt lgkmcnt(0)
	v_add_f32_e32 v119, v120, v121
	v_cvt_f32_u32_e32 v124, v84
	ds_bpermute_b32 v120, v140, v119
	v_cmp_gt_i32_e32 vcc, s45, v156
	v_fmac_f32_e32 v125, v22, v2
	v_fma_f32 v118, -v127, v124, v118
	v_cndmask_b32_e32 v169, v135, v118, vcc
	s_waitcnt lgkmcnt(0)
	v_add_f32_e32 v120, v119, v120
	v_pk_mul_f32 v[118:119], v[12:13], v[28:29]
	v_fmac_f32_e32 v125, v24, v4
	v_add_f32_e32 v118, v118, v148
	v_add_f32_e32 v118, v119, v118
	ds_bpermute_b32 v119, v138, v118
	v_fmac_f32_e32 v125, v25, v5
	ds_bpermute_b32 v148, v138, v125
	v_mul_f32_e32 v150, v15, v27
	v_fmac_f32_e32 v150, v14, v26
	s_waitcnt lgkmcnt(1)
	v_add_f32_e32 v118, v118, v119
	ds_bpermute_b32 v119, v139, v118
	v_fmac_f32_e32 v150, v16, v28
	s_waitcnt lgkmcnt(1)
	v_add_f32_e32 v125, v125, v148
	v_fmac_f32_e32 v150, v17, v29
	ds_bpermute_b32 v148, v139, v125
	s_waitcnt lgkmcnt(1)
	v_add_f32_e32 v118, v118, v119
	ds_bpermute_b32 v119, v140, v118
	ds_bpermute_b32 v151, v138, v150
	s_movk_i32 s10, 0x7fd
	s_waitcnt lgkmcnt(2)
	v_add_f32_e32 v148, v125, v148
	v_sub_u32_e32 v125, 0x7fc, v156
	s_waitcnt lgkmcnt(1)
	v_add_f32_e32 v118, v118, v119
	ds_bpermute_b32 v119, v141, v118
	v_cvt_f32_u32_e32 v125, v125
	v_cmp_gt_i32_e64 s[10:11], s10, v156
	v_mul_f32_e32 v154, v11, v35
	v_fmac_f32_e32 v154, v10, v34
	s_waitcnt lgkmcnt(0)
	v_add_f32_e32 v118, v118, v119
	v_add_f32_e32 v119, v150, v151
	ds_bpermute_b32 v150, v139, v119
	v_mul_f32_e32 v151, v19, v27
	v_fma_f32 v118, -v127, v125, v118
	v_fmac_f32_e32 v151, v18, v26
	v_fmac_f32_e32 v151, v20, v28
	v_cndmask_b32_e64 v172, v135, v118, s[10:11]
	s_waitcnt lgkmcnt(0)
	v_add_f32_e32 v118, v119, v150
	v_fmac_f32_e32 v151, v21, v29
	ds_bpermute_b32 v119, v140, v118
	ds_bpermute_b32 v152, v138, v151
	v_lshl_add_u64 v[66:67], v[66:67], 0, v[98:99]
	v_lshl_add_u64 v[70:71], v[70:71], 0, v[98:99]
	v_lshl_add_u64 v[78:79], v[78:79], 0, v[98:99]
	s_waitcnt lgkmcnt(1)
	v_add_f32_e32 v164, v118, v119
	v_pk_mul_f32 v[118:119], v[12:13], v[36:37]
	s_waitcnt lgkmcnt(0)
	v_add_f32_e32 v150, v151, v152
	v_mul_f32_e32 v152, v23, v27
	v_add_f32_e32 v118, v118, v154
	v_fmac_f32_e32 v152, v22, v26
	v_add_f32_e32 v118, v119, v118
	v_fmac_f32_e32 v152, v24, v28
	ds_bpermute_b32 v119, v138, v118
	v_fmac_f32_e32 v152, v25, v29
	ds_bpermute_b32 v153, v138, v152
	ds_bpermute_b32 v151, v139, v150
	global_load_dwordx4 v[90:93], v[66:67], off
	s_nop 0
	global_load_dwordx4 v[66:69], v[66:67], off offset:512
	s_waitcnt lgkmcnt(0)
	v_add_f32_e32 v118, v118, v119
	ds_bpermute_b32 v119, v139, v118
	v_add_f32_e32 v152, v152, v153
	ds_bpermute_b32 v153, v139, v152
	global_load_dwordx4 v[86:89], v[70:71], off
	s_nop 0
	global_load_dwordx4 v[70:73], v[70:71], off offset:512
	s_nop 0
	global_load_dwordx4 v[82:85], v[78:79], off
	s_nop 0
	global_load_dwordx4 v[78:81], v[78:79], off offset:512
	v_mul_f32_e32 v154, v15, v35
	s_waitcnt lgkmcnt(0)
	v_add_f32_e32 v118, v118, v119
	v_fmac_f32_e32 v154, v14, v34
	ds_bpermute_b32 v119, v140, v118
	v_fmac_f32_e32 v154, v16, v36
	v_add_f32_e32 v150, v150, v151
	v_add_f32_e32 v152, v152, v153
	v_fmac_f32_e32 v154, v17, v37
	ds_bpermute_b32 v151, v140, v150
	ds_bpermute_b32 v153, v140, v152
	ds_bpermute_b32 v155, v138, v154
	s_waitcnt lgkmcnt(0)
	v_add_f32_e32 v118, v118, v119
	ds_bpermute_b32 v119, v141, v118
	v_add_f32_e32 v158, v150, v151
	v_add_f32_e32 v150, v152, v153
	v_sub_u32_e32 v152, 0x7f8, v156
	v_add_f32_e32 v154, v154, v155
	v_cvt_f32_u32_e32 v152, v152
	ds_bpermute_b32 v155, v139, v154
	v_or_b32_e32 v153, 8, v156
	s_waitcnt lgkmcnt(0)
	v_add_f32_e32 v118, v118, v119
	v_fma_f32 v118, -v127, v152, v118
	v_cmp_gt_i32_e64 s[12:13], s45, v153
	v_mul_f32_e32 v153, v19, v35
	v_fmac_f32_e32 v153, v18, v34
	v_cndmask_b32_e64 v173, v135, v118, s[12:13]
	v_add_f32_e32 v118, v154, v155
	v_mul_f32_e32 v155, v23, v35
	v_fmac_f32_e32 v155, v22, v34
	v_fmac_f32_e32 v153, v20, v36
	v_fmac_f32_e32 v155, v24, v36
	v_fmac_f32_e32 v153, v21, v37
	v_fmac_f32_e32 v155, v25, v37
	ds_bpermute_b32 v154, v138, v153
	ds_bpermute_b32 v160, v138, v155
	ds_bpermute_b32 v119, v140, v118
	s_movk_i32 s14, 0x7f5
	v_cmp_gt_i32_e64 s[14:15], s14, v156
	s_waitcnt lgkmcnt(0)
	v_add_f32_e32 v153, v153, v154
	v_add_f32_e32 v160, v155, v160
	v_pk_mul_f32 v[154:155], v[10:11], v[46:47]
	v_add_f32_e32 v167, v118, v119
	v_pk_mul_f32 v[118:119], v[12:13], v[48:49]
	v_add_f32_e32 v154, v154, v155
	v_add_f32_e32 v118, v118, v154
	ds_bpermute_b32 v161, v139, v153
	ds_bpermute_b32 v162, v139, v160
	v_add_f32_e32 v118, v119, v118
	ds_bpermute_b32 v119, v138, v118
	v_mul_f32_e32 v122, v19, v3
	s_waitcnt lgkmcnt(0)
	v_add_f32_e32 v153, v153, v161
	v_add_f32_e32 v155, v160, v162
	ds_bpermute_b32 v154, v140, v153
	ds_bpermute_b32 v162, v140, v155
	v_add_f32_e32 v118, v118, v119
	ds_bpermute_b32 v119, v139, v118
	v_fmac_f32_e32 v122, v18, v2
	s_waitcnt lgkmcnt(0)
	v_add_f32_e32 v160, v153, v154
	v_add_f32_e32 v153, v155, v162
	v_mul_f32_e32 v162, v15, v47
	v_add_f32_e32 v118, v118, v119
	v_fmac_f32_e32 v162, v14, v46
	ds_bpermute_b32 v119, v140, v118
	v_fmac_f32_e32 v162, v16, v48
	v_fmac_f32_e32 v162, v17, v49
	ds_bpermute_b32 v163, v138, v162
	v_sub_u32_e32 v155, 0x7f4, v156
	s_waitcnt lgkmcnt(0)
	v_add_f32_e32 v118, v118, v119
	ds_bpermute_b32 v119, v141, v118
	v_cvt_f32_u32_e32 v155, v155
	v_add_f32_e32 v162, v162, v163
	ds_bpermute_b32 v163, v139, v162
	v_mul_f32_e32 v156, v19, v47
	s_waitcnt lgkmcnt(0)
	v_add_f32_e32 v118, v118, v119
	v_fma_f32 v118, -v127, v155, v118
	v_cndmask_b32_e64 v174, v135, v118, s[14:15]
	v_add_f32_e32 v118, v162, v163
	v_mul_f32_e32 v163, v23, v47
	v_fmac_f32_e32 v156, v18, v46
	v_fmac_f32_e32 v163, v22, v46
	v_fmac_f32_e32 v122, v20, v4
	v_fmac_f32_e32 v156, v20, v48
	v_fmac_f32_e32 v163, v24, v48
	v_fmac_f32_e32 v122, v21, v5
	v_fmac_f32_e32 v156, v21, v49
	v_fmac_f32_e32 v163, v25, v49
	ds_bpermute_b32 v123, v138, v122
	ds_bpermute_b32 v119, v140, v118
	ds_bpermute_b32 v162, v138, v156
	ds_bpermute_b32 v171, v138, v163
	v_max3_f32 v157, v169, s35, v172
	s_waitcnt lgkmcnt(0)
	v_add_f32_e32 v122, v122, v123
	v_add_f32_e32 v170, v118, v119
	v_add_f32_e32 v118, v156, v162
	v_add_f32_e32 v156, v163, v171
	ds_bpermute_b32 v123, v139, v122
	ds_bpermute_b32 v119, v139, v118
	ds_bpermute_b32 v162, v139, v156
	v_max3_f32 v157, v157, v173, v174
	ds_bpermute_b32 v163, v142, v157
	s_waitcnt lgkmcnt(0)
	v_add_f32_e32 v122, v122, v123
	v_add_f32_e32 v118, v118, v119
	v_add_f32_e32 v156, v156, v162
	ds_bpermute_b32 v123, v140, v122
	ds_bpermute_b32 v149, v140, v148
	ds_bpermute_b32 v119, v140, v118
	ds_bpermute_b32 v175, v140, v156
	v_max_f32_e32 v162, v163, v163
	v_max_f32_e32 v176, v157, v162
	ds_bpermute_b32 v177, v143, v176
	s_waitcnt lgkmcnt(0)
	v_add_f32_e32 v122, v122, v123
	v_add_f32_e32 v148, v148, v149
	v_add_f32_e32 v162, v118, v119
	v_add_f32_e32 v156, v156, v175
	ds_bpermute_b32 v121, v141, v120
	ds_bpermute_b32 v123, v141, v122
	ds_bpermute_b32 v149, v141, v148
	ds_bpermute_b32 v165, v141, v164
	ds_bpermute_b32 v159, v141, v158
	ds_bpermute_b32 v151, v141, v150
	ds_bpermute_b32 v168, v141, v167
	ds_bpermute_b32 v161, v141, v160
	ds_bpermute_b32 v154, v141, v153
	ds_bpermute_b32 v171, v141, v170
	ds_bpermute_b32 v163, v141, v162
	ds_bpermute_b32 v157, v141, v156
	v_max_f32_e32 v118, v177, v177
	v_max_f32_e32 v175, v176, v118
	v_cmp_neq_f32_e64 s[16:17], s35, v175
	v_mov_b64_e32 v[118:119], v[112:113]
	s_and_saveexec_b64 s[22:23], s[16:17]
	s_cbranch_execz .LBB0_2754
	v_max_f32_e32 v118, v175, v175
	v_max_f32_e32 v119, v113, v113
	v_max_f32_e32 v119, v119, v118
	v_sub_f32_e32 v118, v169, v119
	v_mul_f32_e32 v118, 0x3fb8aa3b, v118
	v_exp_f32_e32 v118, v118
	v_sub_f32_e32 v113, v113, v119
	v_mul_f32_e32 v113, 0x3fb8aa3b, v113
	v_add_f32_e32 v169, 0, v118
	v_pk_fma_f32 v[176:177], v[8:9], v[118:119], 0 op_sel_hi:[1,0,0]
	v_pk_fma_f32 v[178:179], v[6:7], v[118:119], 0 op_sel_hi:[1,0,0]
	v_sub_f32_e32 v118, v172, v119
	v_mul_f32_e32 v118, 0x3fb8aa3b, v118
	v_exp_f32_e32 v118, v118
	s_nop 0
	v_add_f32_e32 v169, v118, v169
	v_pk_fma_f32 v[176:177], v[32:33], v[118:119], v[176:177] op_sel_hi:[1,0,1]
	v_pk_fma_f32 v[178:179], v[30:31], v[118:119], v[178:179] op_sel_hi:[1,0,1]
	v_sub_f32_e32 v118, v173, v119
	v_mul_f32_e32 v118, 0x3fb8aa3b, v118
	v_exp_f32_e32 v118, v118
	s_nop 0
	v_add_f32_e32 v169, v118, v169
	v_pk_fma_f32 v[172:173], v[38:39], v[118:119], v[178:179] op_sel_hi:[1,0,1]
	v_pk_fma_f32 v[176:177], v[40:41], v[118:119], v[176:177] op_sel_hi:[1,0,1]
	v_sub_f32_e32 v118, v174, v119
	v_mul_f32_e32 v118, 0x3fb8aa3b, v118
	v_exp_f32_e32 v118, v118
	s_nop 0
	v_add_f32_e32 v169, v118, v169
	v_pk_fma_f32 v[174:175], v[56:57], v[118:119], v[176:177] op_sel_hi:[1,0,1]
	v_exp_f32_e32 v176, v113
	ds_bpermute_b32 v113, v142, v169
	v_pk_fma_f32 v[172:173], v[54:55], v[118:119], v[172:173] op_sel_hi:[1,0,1]
	ds_bpermute_b32 v178, v142, v174
	ds_bpermute_b32 v179, v142, v175
	s_waitcnt lgkmcnt(0)
	v_add_f32_e32 v113, v169, v113
	ds_bpermute_b32 v118, v143, v113
	v_pk_add_f32 v[174:175], v[174:175], v[178:179]
	ds_bpermute_b32 v178, v143, v174
	ds_bpermute_b32 v179, v143, v175
	s_waitcnt lgkmcnt(0)
	v_add_f32_e32 v118, v113, v118
	v_fmac_f32_e32 v118, v112, v176
	ds_bpermute_b32 v112, v142, v172
	ds_bpermute_b32 v113, v142, v173
	s_waitcnt lgkmcnt(0)
	v_pk_add_f32 v[112:113], v[172:173], v[112:113]
	ds_bpermute_b32 v172, v143, v112
	ds_bpermute_b32 v173, v143, v113
	s_waitcnt lgkmcnt(0)
	v_pk_add_f32 v[112:113], v[112:113], v[172:173]
	v_pk_add_f32 v[172:173], v[174:175], v[178:179]
	v_pk_fma_f32 v[62:63], v[62:63], v[176:177], v[112:113] op_sel_hi:[1,0,1]
	v_pk_fma_f32 v[64:65], v[64:65], v[176:177], v[172:173] op_sel_hi:[1,0,1]
	v_mov_b32_e32 v112, v118
	v_mov_b32_e32 v113, v119

.LBB0_2760:
	s_or_b64 exec, exec, s[10:11]
	s_add_i32 s54, s52, 2
	s_cmp_gt_u32 s52, 9
	s_cselect_b64 s[22:23], -1, 0
	s_and_b64 vcc, exec, s[22:23]
	s_cbranch_vccnz .LBB0_2762
	s_lshr_b32 s10, s54, 2
	s_cmp_eq_u32 s10, 2
	s_cselect_b32 s12, s31, s29
	s_cselect_b32 s13, s48, s30
	s_cmp_eq_u32 s10, 1
	s_cselect_b64 vcc, -1, 0
	s_and_b64 s[10:11], vcc, exec
	s_cselect_b32 s14, s27, s28
	s_cmp_eq_u32 s52, 0
	v_cndmask_b32_e32 v2, v106, v108, vcc
	v_cndmask_b32_e32 v3, v107, v109, vcc
	s_cselect_b64 vcc, -1, 0
	s_and_b64 s[10:11], vcc, exec
	s_cselect_b32 s10, s26, s14
	s_and_b32 s11, s49, 32
	s_or_b32 s11, s10, s11
	v_add_u32_e32 v54, s11, v100
	v_subrev_u32_e32 v48, s10, v54
	v_ashrrev_i32_e32 v49, 31, v48
	v_add_u32_e32 v26, 4, v48
	v_or_b32_e32 v36, 8, v54
	v_cndmask_b32_e32 v47, v3, v105, vcc
	v_cndmask_b32_e32 v46, v2, v104, vcc
	v_lshlrev_b64 v[2:3], 10, v[48:49]
	v_ashrrev_i32_e32 v27, 31, v26
	v_subrev_u32_e32 v34, s10, v36
	v_lshl_add_u64 v[2:3], v[46:47], 0, v[2:3]
	v_mov_b32_e32 v55, s13
	v_cmp_gt_i32_e32 vcc, s44, v54
	v_mov_b32_e32 v56, s12
	v_lshlrev_b64 v[26:27], 10, v[26:27]
	s_movk_i32 s11, 0x7fc
	v_ashrrev_i32_e32 v35, 31, v34
	v_add_u32_e32 v48, 12, v48
	v_cndmask_b32_e32 v3, v55, v3, vcc
	v_cndmask_b32_e32 v2, v56, v2, vcc
	v_lshl_add_u64 v[26:27], v[46:47], 0, v[26:27]
	v_cmp_gt_i32_e32 vcc, s11, v54
	v_lshlrev_b64 v[34:35], 10, v[34:35]
	v_ashrrev_i32_e32 v49, 31, v48
	v_cndmask_b32_e32 v27, v55, v27, vcc
	v_cndmask_b32_e32 v26, v56, v26, vcc
	v_lshl_add_u64 v[34:35], v[46:47], 0, v[34:35]
	v_cmp_gt_i32_e32 vcc, s44, v36
	v_lshlrev_b64 v[48:49], 10, v[48:49]
	s_movk_i32 s10, 0x7f4
	v_cndmask_b32_e32 v35, v55, v35, vcc
	v_cndmask_b32_e32 v34, v56, v34, vcc
	v_lshl_add_u64 v[46:47], v[46:47], 0, v[48:49]
	v_cmp_gt_i32_e32 vcc, s10, v54
	v_lshl_add_u64 v[6:7], v[2:3], 0, v[98:99]
	v_lshl_add_u64 v[30:31], v[26:27], 0, v[98:99]
	v_cndmask_b32_e32 v47, v55, v47, vcc
	v_cndmask_b32_e32 v46, v56, v46, vcc
	v_lshl_add_u64 v[38:39], v[34:35], 0, v[98:99]
	v_lshl_add_u64 v[54:55], v[46:47], 0, v[98:99]
	global_load_dwordx4 v[2:5], v[6:7], off
	s_nop 0
	global_load_dwordx4 v[6:9], v[6:7], off offset:512
	s_nop 0
	global_load_dwordx4 v[26:29], v[30:31], off
	s_nop 0
	global_load_dwordx4 v[30:33], v[30:31], off offset:512
	s_nop 0
	global_load_dwordx4 v[34:37], v[38:39], off
	s_nop 0
	global_load_dwordx4 v[38:41], v[38:39], off offset:512
	s_nop 0
	global_load_dwordx4 v[46:49], v[54:55], off
	s_nop 0
	global_load_dwordx4 v[54:57], v[54:55], off offset:512

.LBB0_3149:
	v_mul_f32_e32 v130, 0xbfb8aa3b, v126
	v_exp_f32_e32 v130, v130
	v_mul_f32_e32 v138, 0xbfb8aa3b, v127
	v_exp_f32_e32 v138, v138
	s_lshl_b32 s5, s16, 7
	v_add_f32_e32 v133, 1.0, v130
	s_or_b32 s5, s36, s5
	v_or_b32_e32 v130, s5, v142
	v_add_u32_e32 v132, 0x4000, v1
	v_add_f32_e32 v136, 1.0, v138
	v_rcp_f32_e32 v134, v133
	s_nop 0
	v_mul_f32_e32 v126, v126, v134
	v_mul_f32_e32 v122, v126, v122
	v_mul_f32_e32 v134, 0xbfb8aa3b, v128
	v_exp_f32_e32 v134, v134
	v_rcp_f32_e32 v126, v136
	s_nop 0
	v_mul_f32_e32 v126, v127, v126
	v_add_f32_e32 v133, 1.0, v134
	v_mul_f32_e32 v123, v126, v123
	v_mul_f32_e32 v127, 0xbfb8aa3b, v129
	v_cvt_pk_bf16_f32 v122, v122, v123
	v_exp_f32_e32 v127, v127
	s_nop 0
	v_add_f32_e32 v127, 1.0, v127
	v_rcp_f32_e32 v123, v133
	s_nop 0
	v_mul_f32_e32 v123, v128, v123
	v_mul_f32_e32 v123, v123, v124
	v_mul_f32_e32 v128, 0xbfb8aa3b, v118
	v_exp_f32_e32 v128, v128
	v_rcp_f32_e32 v124, v127
	s_nop 0
	v_mul_f32_e32 v124, v129, v124
	v_add_f32_e32 v126, 1.0, v128
	v_mul_f32_e32 v124, v124, v125
	v_mul_f32_e32 v127, 0xbfb8aa3b, v119
	v_cvt_pk_bf16_f32 v123, v123, v124
	v_exp_f32_e32 v127, v127
	s_nop 0
	v_add_f32_e32 v127, 1.0, v127
	v_rcp_f32_e32 v124, v126
	s_nop 0
	v_mul_f32_e32 v118, v118, v124
	v_mul_f32_e32 v114, v118, v114
	v_mul_f32_e32 v125, 0xbfb8aa3b, v120
	v_exp_f32_e32 v125, v125
	v_rcp_f32_e32 v118, v127
	s_nop 0
	v_mul_f32_e32 v118, v119, v118
	v_add_f32_e32 v125, 1.0, v125
	v_mul_f32_e32 v115, v118, v115
	v_mul_f32_e32 v118, 0xbfb8aa3b, v121
	v_exp_f32_e32 v118, v118
	v_cvt_pk_bf16_f32 v124, v114, v115
	v_add_f32_e32 v118, 1.0, v118
	v_rcp_f32_e32 v114, v125
	s_nop 0
	v_mul_f32_e32 v114, v120, v114
	v_mul_f32_e32 v114, v114, v116
	v_rcp_f32_e32 v115, v118
	s_nop 0
	v_mul_f32_e32 v115, v121, v115
	v_mul_f32_e32 v115, v115, v117
	v_cvt_pk_bf16_f32 v125, v114, v115
	v_mul_f32_e32 v114, 0xbfb8aa3b, v110
	v_exp_f32_e32 v116, v114
	v_ashrrev_i32_e32 v131, 31, v130
	s_movk_i32 s5, 0x1600
	v_mov_b64_e32 v[114:115], s[22:23]
	v_add_f32_e32 v120, 1.0, v116
	v_mad_i64_i32 v[118:119], s[8:9], v132, s5, v[114:115]
	v_lshlrev_b64 v[116:117], 1, v[130:131]
	v_lshl_add_u64 v[118:119], v[118:119], 0, v[116:117]
	global_store_dwordx4 v[118:119], v[122:125], off
	s_nop 1
	v_mul_f32_e32 v122, 0xbfb8aa3b, v111
	v_exp_f32_e32 v122, v122
	s_nop 0
	v_add_f32_e32 v121, 1.0, v122
	v_rcp_f32_e32 v118, v120
	s_nop 0
	v_mul_f32_e32 v110, v110, v118
	v_mul_f32_e32 v106, v110, v106
	v_mul_f32_e32 v119, 0xbfb8aa3b, v112
	v_exp_f32_e32 v119, v119
	v_rcp_f32_e32 v110, v121
	s_nop 0
	v_mul_f32_e32 v110, v111, v110
	v_add_f32_e32 v118, 1.0, v119
	v_mul_f32_e32 v107, v110, v107
	v_mul_f32_e32 v111, 0xbfb8aa3b, v113
	v_cvt_pk_bf16_f32 v106, v106, v107
	v_exp_f32_e32 v111, v111
	s_nop 0
	v_add_f32_e32 v111, 1.0, v111
	v_rcp_f32_e32 v107, v118
	s_nop 0
	v_mul_f32_e32 v107, v112, v107
	v_mul_f32_e32 v107, v107, v108
	v_mul_f32_e32 v112, 0xbfb8aa3b, v102
	v_exp_f32_e32 v112, v112
	v_rcp_f32_e32 v108, v111
	s_nop 0
	v_mul_f32_e32 v108, v113, v108
	v_add_f32_e32 v110, 1.0, v112
	v_mul_f32_e32 v108, v108, v109
	v_mul_f32_e32 v111, 0xbfb8aa3b, v103
	v_cvt_pk_bf16_f32 v107, v107, v108
	v_exp_f32_e32 v111, v111
	s_nop 0
	v_add_f32_e32 v111, 1.0, v111
	v_rcp_f32_e32 v108, v110
	s_nop 0
	v_mul_f32_e32 v102, v102, v108
	v_mul_f32_e32 v98, v102, v98
	v_mul_f32_e32 v109, 0xbfb8aa3b, v104
	v_exp_f32_e32 v109, v109
	v_rcp_f32_e32 v102, v111
	s_nop 0
	v_mul_f32_e32 v102, v103, v102
	v_add_f32_e32 v109, 1.0, v109
	v_mul_f32_e32 v99, v102, v99
	v_mul_f32_e32 v102, 0xbfb8aa3b, v105
	v_exp_f32_e32 v102, v102
	v_cvt_pk_bf16_f32 v108, v98, v99
	v_add_f32_e32 v102, 1.0, v102
	v_rcp_f32_e32 v98, v109
	s_nop 0
	v_mul_f32_e32 v98, v104, v98
	v_mul_f32_e32 v98, v98, v100
	v_mul_f32_e32 v100, 0xbfb8aa3b, v94
	v_exp_f32_e32 v100, v100
	v_rcp_f32_e32 v99, v102
	s_nop 0
	v_mul_f32_e32 v99, v105, v99
	v_mul_f32_e32 v99, v99, v101
	v_cvt_pk_bf16_f32 v109, v98, v99
	v_add_f32_e32 v100, 1.0, v100
	v_add_u32_e32 v98, 0x4010, v1
	v_mad_i64_i32 v[98:99], s[8:9], v98, s5, v[114:115]
	v_lshl_add_u64 v[98:99], v[98:99], 0, v[116:117]
	global_store_dwordx4 v[98:99], v[106:109], off
	v_mul_f32_e32 v103, 0xbfb8aa3b, v95
	v_exp_f32_e32 v103, v103
	s_nop 0
	v_add_f32_e32 v101, 1.0, v103
	v_rcp_f32_e32 v98, v100
	s_nop 0
	v_mul_f32_e32 v94, v94, v98
	v_mul_f32_e32 v90, v94, v90
	v_mul_f32_e32 v99, 0xbfb8aa3b, v96
	v_exp_f32_e32 v99, v99
	v_rcp_f32_e32 v94, v101
	s_nop 0
	v_mul_f32_e32 v94, v95, v94
	v_add_f32_e32 v98, 1.0, v99
	v_mul_f32_e32 v91, v94, v91
	v_mul_f32_e32 v95, 0xbfb8aa3b, v97
	v_cvt_pk_bf16_f32 v90, v90, v91
	v_exp_f32_e32 v95, v95
	s_nop 0
	v_add_f32_e32 v95, 1.0, v95
	v_rcp_f32_e32 v91, v98
	s_nop 0
	v_mul_f32_e32 v91, v96, v91
	v_mul_f32_e32 v91, v91, v92
	v_mul_f32_e32 v96, 0xbfb8aa3b, v86
	v_exp_f32_e32 v96, v96
	v_rcp_f32_e32 v92, v95
	s_nop 0
	v_mul_f32_e32 v92, v97, v92
	v_add_f32_e32 v94, 1.0, v96
	v_mul_f32_e32 v92, v92, v93
	v_mul_f32_e32 v95, 0xbfb8aa3b, v87
	v_cvt_pk_bf16_f32 v91, v91, v92
	v_exp_f32_e32 v95, v95
	s_nop 0
	v_add_f32_e32 v95, 1.0, v95
	v_rcp_f32_e32 v92, v94
	s_nop 0
	v_mul_f32_e32 v86, v86, v92
	v_mul_f32_e32 v82, v86, v82
	v_mul_f32_e32 v93, 0xbfb8aa3b, v88
	v_exp_f32_e32 v93, v93
	v_rcp_f32_e32 v86, v95
	s_nop 0
	v_mul_f32_e32 v86, v87, v86
	v_add_f32_e32 v93, 1.0, v93
	v_mul_f32_e32 v83, v86, v83
	v_mul_f32_e32 v86, 0xbfb8aa3b, v89
	v_exp_f32_e32 v86, v86
	v_cvt_pk_bf16_f32 v92, v82, v83
	v_add_f32_e32 v86, 1.0, v86
	v_rcp_f32_e32 v82, v93
	s_nop 0
	v_mul_f32_e32 v82, v88, v82
	v_mul_f32_e32 v82, v82, v84
	v_mul_f32_e32 v84, 0xbfb8aa3b, v78
	v_exp_f32_e32 v84, v84
	v_rcp_f32_e32 v83, v86
	s_nop 0
	v_mul_f32_e32 v83, v89, v83
	v_mul_f32_e32 v83, v83, v85
	v_cvt_pk_bf16_f32 v93, v82, v83
	v_add_f32_e32 v84, 1.0, v84
	v_add_u32_e32 v82, 0x4020, v1
	v_mad_i64_i32 v[82:83], s[8:9], v82, s5, v[114:115]
	v_lshl_add_u64 v[82:83], v[82:83], 0, v[116:117]
	global_store_dwordx4 v[82:83], v[90:93], off
	v_mul_f32_e32 v87, 0xbfb8aa3b, v79
	v_exp_f32_e32 v87, v87
	s_nop 0
	v_add_f32_e32 v85, 1.0, v87
	v_rcp_f32_e32 v82, v84
	s_nop 0
	v_mul_f32_e32 v78, v78, v82
	v_mul_f32_e32 v74, v78, v74
	v_mul_f32_e32 v83, 0xbfb8aa3b, v80
	v_exp_f32_e32 v83, v83
	v_rcp_f32_e32 v78, v85
	s_nop 0
	v_mul_f32_e32 v78, v79, v78
	v_add_f32_e32 v82, 1.0, v83
	v_mul_f32_e32 v75, v78, v75
	v_mul_f32_e32 v79, 0xbfb8aa3b, v81
	v_cvt_pk_bf16_f32 v74, v74, v75
	v_exp_f32_e32 v79, v79
	s_nop 0
	v_add_f32_e32 v79, 1.0, v79
	v_rcp_f32_e32 v75, v82
	s_nop 0
	v_mul_f32_e32 v75, v80, v75
	v_mul_f32_e32 v75, v75, v76
	v_mul_f32_e32 v80, 0xbfb8aa3b, v70
	v_exp_f32_e32 v80, v80
	v_rcp_f32_e32 v76, v79
	s_nop 0
	v_mul_f32_e32 v76, v81, v76
	v_add_f32_e32 v78, 1.0, v80
	v_mul_f32_e32 v76, v76, v77
	v_mul_f32_e32 v79, 0xbfb8aa3b, v71
	v_cvt_pk_bf16_f32 v75, v75, v76
	v_exp_f32_e32 v79, v79
	s_nop 0
	v_add_f32_e32 v79, 1.0, v79
	v_rcp_f32_e32 v76, v78
	s_nop 0
	v_mul_f32_e32 v70, v70, v76
	v_mul_f32_e32 v66, v70, v66
	v_mul_f32_e32 v77, 0xbfb8aa3b, v72
	v_exp_f32_e32 v77, v77
	v_rcp_f32_e32 v70, v79
	s_nop 0
	v_mul_f32_e32 v70, v71, v70
	v_add_f32_e32 v77, 1.0, v77
	v_mul_f32_e32 v67, v70, v67
	v_mul_f32_e32 v70, 0xbfb8aa3b, v73
	v_exp_f32_e32 v70, v70
	v_cvt_pk_bf16_f32 v76, v66, v67
	v_add_f32_e32 v70, 1.0, v70
	v_rcp_f32_e32 v66, v77
	s_nop 0
	v_mul_f32_e32 v66, v72, v66
	v_mul_f32_e32 v66, v66, v68
	v_rcp_f32_e32 v67, v70
	s_nop 0
	v_mul_f32_e32 v67, v73, v67
	v_mul_f32_e32 v67, v67, v69
	v_cvt_pk_bf16_f32 v77, v66, v67
	v_mul_f32_e32 v66, 0xbfb8aa3b, v62
	v_exp_f32_e32 v68, v66
	v_add_u32_e32 v66, 0x4030, v1
	v_mad_i64_i32 v[66:67], s[8:9], v66, s5, v[114:115]
	v_add_f32_e32 v68, 1.0, v68
	v_lshl_add_u64 v[66:67], v[66:67], 0, v[116:117]
	global_store_dwordx4 v[66:67], v[74:77], off
	v_mul_f32_e32 v72, 0xbfb8aa3b, v63
	v_exp_f32_e32 v72, v72
	s_nop 0
	v_add_f32_e32 v69, 1.0, v72
	v_rcp_f32_e32 v67, v68
	s_nop 0
	v_mul_f32_e32 v62, v62, v67
	v_mul_f32_e32 v58, v62, v58
	v_mul_f32_e32 v68, 0xbfb8aa3b, v64
	v_exp_f32_e32 v68, v68
	v_rcp_f32_e32 v62, v69
	s_nop 0
	v_mul_f32_e32 v62, v63, v62
	v_add_f32_e32 v67, 1.0, v68
	v_mul_f32_e32 v59, v62, v59
	v_mul_f32_e32 v63, 0xbfb8aa3b, v65
	v_cvt_pk_bf16_f32 v58, v58, v59
	v_exp_f32_e32 v63, v63
	s_nop 0
	v_add_f32_e32 v63, 1.0, v63
	v_rcp_f32_e32 v59, v67
	s_nop 0
	v_mul_f32_e32 v59, v64, v59
	v_mul_f32_e32 v59, v59, v60
	v_mul_f32_e32 v64, 0xbfb8aa3b, v54
	v_exp_f32_e32 v64, v64
	v_rcp_f32_e32 v60, v63
	s_nop 0
	v_mul_f32_e32 v60, v65, v60
	v_add_f32_e32 v62, 1.0, v64
	v_mul_f32_e32 v60, v60, v61
	v_mul_f32_e32 v63, 0xbfb8aa3b, v55
	v_cvt_pk_bf16_f32 v59, v59, v60
	v_exp_f32_e32 v63, v63
	s_nop 0
	v_add_f32_e32 v63, 1.0, v63
	v_rcp_f32_e32 v60, v62
	s_nop 0
	v_mul_f32_e32 v54, v54, v60
	v_mul_f32_e32 v50, v54, v50
	v_mul_f32_e32 v61, 0xbfb8aa3b, v56
	v_exp_f32_e32 v61, v61
	v_rcp_f32_e32 v54, v63
	s_nop 0
	v_mul_f32_e32 v54, v55, v54
	v_add_f32_e32 v61, 1.0, v61
	v_mul_f32_e32 v51, v54, v51
	v_mul_f32_e32 v54, 0xbfb8aa3b, v57
	v_exp_f32_e32 v54, v54
	v_cvt_pk_bf16_f32 v60, v50, v51
	v_add_f32_e32 v54, 1.0, v54
	v_rcp_f32_e32 v50, v61
	s_nop 0
	v_mul_f32_e32 v50, v56, v50
	v_mul_f32_e32 v50, v50, v52
	v_mul_f32_e32 v52, 0xbfb8aa3b, v46
	v_exp_f32_e32 v52, v52
	v_rcp_f32_e32 v51, v54
	s_nop 0
	v_mul_f32_e32 v51, v57, v51
	v_mul_f32_e32 v51, v51, v53
	v_add_u32_e32 v66, 0x4080, v1
	v_add_f32_e32 v52, 1.0, v52
	v_cvt_pk_bf16_f32 v61, v50, v51
	v_mad_i64_i32 v[50:51], s[8:9], v66, s5, v[114:115]
	v_lshl_add_u64 v[50:51], v[50:51], 0, v[116:117]
	global_store_dwordx4 v[50:51], v[58:61], off
	v_mul_f32_e32 v55, 0xbfb8aa3b, v47
	v_exp_f32_e32 v55, v55
	s_nop 0
	v_add_f32_e32 v53, 1.0, v55
	v_rcp_f32_e32 v50, v52
	s_nop 0
	v_mul_f32_e32 v46, v46, v50
	v_mul_f32_e32 v42, v46, v42
	v_mul_f32_e32 v51, 0xbfb8aa3b, v48
	v_exp_f32_e32 v51, v51
	v_rcp_f32_e32 v46, v53
	s_nop 0
	v_mul_f32_e32 v46, v47, v46
	v_add_f32_e32 v50, 1.0, v51
	v_mul_f32_e32 v43, v46, v43
	v_mul_f32_e32 v47, 0xbfb8aa3b, v49
	v_cvt_pk_bf16_f32 v42, v42, v43
	v_exp_f32_e32 v47, v47
	s_nop 0
	v_add_f32_e32 v47, 1.0, v47
	v_rcp_f32_e32 v43, v50
	s_nop 0
	v_mul_f32_e32 v43, v48, v43
	v_mul_f32_e32 v43, v43, v44
	v_mul_f32_e32 v48, 0xbfb8aa3b, v38
	v_exp_f32_e32 v48, v48
	v_rcp_f32_e32 v44, v47
	s_nop 0
	v_mul_f32_e32 v44, v49, v44
	v_add_f32_e32 v46, 1.0, v48
	v_mul_f32_e32 v44, v44, v45
	v_mul_f32_e32 v47, 0xbfb8aa3b, v39
	v_cvt_pk_bf16_f32 v43, v43, v44
	v_exp_f32_e32 v47, v47
	s_nop 0
	v_add_f32_e32 v47, 1.0, v47
	v_rcp_f32_e32 v44, v46
	s_nop 0
	v_mul_f32_e32 v38, v38, v44
	v_mul_f32_e32 v34, v38, v34
	v_mul_f32_e32 v45, 0xbfb8aa3b, v40
	v_exp_f32_e32 v45, v45
	v_rcp_f32_e32 v38, v47
	s_nop 0
	v_mul_f32_e32 v38, v39, v38
	v_add_f32_e32 v45, 1.0, v45
	v_mul_f32_e32 v35, v38, v35
	v_mul_f32_e32 v38, 0xbfb8aa3b, v41
	v_exp_f32_e32 v38, v38
	v_cvt_pk_bf16_f32 v44, v34, v35
	v_add_f32_e32 v38, 1.0, v38
	v_rcp_f32_e32 v34, v45
	s_nop 0
	v_mul_f32_e32 v34, v40, v34
	v_mul_f32_e32 v34, v34, v36
	v_mul_f32_e32 v36, 0xbfb8aa3b, v30
	v_exp_f32_e32 v36, v36
	v_rcp_f32_e32 v35, v38
	s_nop 0
	v_mul_f32_e32 v35, v41, v35
	v_mul_f32_e32 v35, v35, v37
	v_cvt_pk_bf16_f32 v45, v34, v35
	v_add_f32_e32 v36, 1.0, v36
	v_add_u32_e32 v34, 0x4090, v1
	v_mad_i64_i32 v[34:35], s[8:9], v34, s5, v[114:115]
	v_lshl_add_u64 v[34:35], v[34:35], 0, v[116:117]
	global_store_dwordx4 v[34:35], v[42:45], off
	v_mul_f32_e32 v39, 0xbfb8aa3b, v31
	v_exp_f32_e32 v39, v39
	s_nop 0
	v_add_f32_e32 v37, 1.0, v39
	v_rcp_f32_e32 v34, v36
	s_nop 0
	v_mul_f32_e32 v30, v30, v34
	v_mul_f32_e32 v26, v30, v26
	v_mul_f32_e32 v35, 0xbfb8aa3b, v32
	v_exp_f32_e32 v35, v35
	v_rcp_f32_e32 v30, v37
	s_nop 0
	v_mul_f32_e32 v30, v31, v30
	v_add_f32_e32 v34, 1.0, v35
	v_mul_f32_e32 v27, v30, v27
	v_mul_f32_e32 v31, 0xbfb8aa3b, v33
	v_cvt_pk_bf16_f32 v26, v26, v27
	v_exp_f32_e32 v31, v31
	s_nop 0
	v_add_f32_e32 v31, 1.0, v31
	v_rcp_f32_e32 v27, v34
	s_nop 0
	v_mul_f32_e32 v27, v32, v27
	v_mul_f32_e32 v27, v27, v28
	v_mul_f32_e32 v32, 0xbfb8aa3b, v22
	v_exp_f32_e32 v32, v32
	v_rcp_f32_e32 v28, v31
	s_nop 0
	v_mul_f32_e32 v28, v33, v28
	v_add_f32_e32 v30, 1.0, v32
	v_mul_f32_e32 v28, v28, v29
	v_mul_f32_e32 v31, 0xbfb8aa3b, v23
	v_cvt_pk_bf16_f32 v27, v27, v28
	v_exp_f32_e32 v31, v31
	s_nop 0
	v_add_f32_e32 v31, 1.0, v31
	v_rcp_f32_e32 v28, v30
	s_nop 0
	v_mul_f32_e32 v22, v22, v28
	v_mul_f32_e32 v18, v22, v18
	v_mul_f32_e32 v29, 0xbfb8aa3b, v24
	v_exp_f32_e32 v29, v29
	v_rcp_f32_e32 v22, v31
	s_nop 0
	v_mul_f32_e32 v22, v23, v22
	v_add_f32_e32 v29, 1.0, v29
	v_mul_f32_e32 v19, v22, v19
	v_mul_f32_e32 v22, 0xbfb8aa3b, v25
	v_exp_f32_e32 v22, v22
	v_cvt_pk_bf16_f32 v28, v18, v19
	v_add_f32_e32 v22, 1.0, v22
	v_rcp_f32_e32 v18, v29
	s_nop 0
	v_mul_f32_e32 v18, v24, v18
	v_mul_f32_e32 v18, v18, v20
	v_mul_f32_e32 v20, 0xbfb8aa3b, v14
	v_exp_f32_e32 v20, v20
	v_rcp_f32_e32 v19, v22
	s_nop 0
	v_mul_f32_e32 v19, v25, v19
	v_mul_f32_e32 v19, v19, v21
	v_cvt_pk_bf16_f32 v29, v18, v19
	v_add_f32_e32 v20, 1.0, v20
	v_add_u32_e32 v18, 0x40a0, v1
	v_mad_i64_i32 v[18:19], s[8:9], v18, s5, v[114:115]
	v_lshl_add_u64 v[18:19], v[18:19], 0, v[116:117]
	global_store_dwordx4 v[18:19], v[26:29], off
	v_mul_f32_e32 v23, 0xbfb8aa3b, v15
	v_exp_f32_e32 v23, v23
	s_nop 0
	v_add_f32_e32 v21, 1.0, v23
	v_rcp_f32_e32 v18, v20
	s_nop 0
	v_mul_f32_e32 v14, v14, v18
	v_mul_f32_e32 v10, v14, v10
	v_mul_f32_e32 v19, 0xbfb8aa3b, v16
	v_exp_f32_e32 v19, v19
	v_rcp_f32_e32 v14, v21
	s_nop 0
	v_mul_f32_e32 v14, v15, v14
	v_add_f32_e32 v18, 1.0, v19
	v_mul_f32_e32 v11, v14, v11
	v_mul_f32_e32 v15, 0xbfb8aa3b, v17
	v_cvt_pk_bf16_f32 v10, v10, v11
	v_exp_f32_e32 v15, v15
	s_nop 0
	v_add_f32_e32 v15, 1.0, v15
	v_rcp_f32_e32 v11, v18
	s_nop 0
	v_mul_f32_e32 v11, v16, v11
	v_mul_f32_e32 v11, v11, v12
	v_mul_f32_e32 v16, 0xbfb8aa3b, v6
	v_exp_f32_e32 v16, v16
	v_rcp_f32_e32 v12, v15
	s_nop 0
	v_mul_f32_e32 v12, v17, v12
	v_add_f32_e32 v14, 1.0, v16
	v_mul_f32_e32 v12, v12, v13
	v_mul_f32_e32 v15, 0xbfb8aa3b, v7
	v_cvt_pk_bf16_f32 v11, v11, v12
	v_exp_f32_e32 v15, v15
	s_nop 0
	v_add_f32_e32 v15, 1.0, v15
	v_rcp_f32_e32 v12, v14
	s_nop 0
	v_mul_f32_e32 v6, v6, v12
	v_mul_f32_e32 v2, v6, v2
	v_mul_f32_e32 v13, 0xbfb8aa3b, v8
	v_exp_f32_e32 v13, v13
	v_rcp_f32_e32 v6, v15
	s_nop 0
	v_mul_f32_e32 v6, v7, v6
	v_add_f32_e32 v13, 1.0, v13
	v_mul_f32_e32 v3, v6, v3
	v_mul_f32_e32 v6, 0xbfb8aa3b, v9
	v_exp_f32_e32 v6, v6
	v_cvt_pk_bf16_f32 v12, v2, v3
	v_add_f32_e32 v6, 1.0, v6
	v_rcp_f32_e32 v2, v13
	s_nop 0
	v_mul_f32_e32 v2, v8, v2
	v_mul_f32_e32 v2, v2, v4
	v_rcp_f32_e32 v3, v6
	s_nop 0
	v_mul_f32_e32 v3, v9, v3
	v_mul_f32_e32 v3, v3, v5
	v_add_u32_e32 v1, 0x40b0, v1
	v_cvt_pk_bf16_f32 v13, v2, v3
	v_mad_i64_i32 v[2:3], s[8:9], v1, s5, v[114:115]
	v_lshl_add_u64 v[2:3], v[2:3], 0, v[116:117]
	global_store_dwordx4 v[2:3], v[10:13], off
	s_waitcnt vmcnt(0)
	s_barrier
	s_waitcnt vmcnt(0)
	s_waitcnt vmcnt(0) lgkmcnt(0)
	s_barrier
	s_mov_b64 s[8:9], exec
	v_readlane_b32 s10, v228, 2
	v_readlane_b32 s11, v228, 3
	s_and_b64 s[10:11], s[8:9], s[10:11]
	s_mov_b64 exec, s[10:11]
	s_cbranch_execz .LBB0_3152
	s_mov_b64 s[10:11], exec
	v_mbcnt_lo_u32_b32 v1, s10, 0
	buffer_wbl2 sc1
	s_waitcnt vmcnt(0)
	v_mbcnt_hi_u32_b32 v1, s11, v1
	v_cmp_eq_u32_e32 vcc, 0, v1
	s_and_b64 s[24:25], exec, vcc
	s_mov_b64 exec, s[24:25]
	s_cbranch_execz .LBB0_3152
	s_bcnt1_i32_b64 s5, s[10:11]
	v_mov_b32_e32 v1, 0
	v_mov_b32_e32 v2, s5
	global_atomic_add v1, v2, s[6:7]

.LBB0_3215:
	v_mul_f32_e32 v148, 0xbfb8aa3b, v126
	v_exp_f32_e32 v149, v148
	v_lshl_add_u32 v148, s48, 8, v1
	v_lshl_or_b32 v150, s49, 7, v142
	v_mul_f32_e32 v156, 0xbfb8aa3b, v127
	v_add_f32_e32 v149, 1.0, v149
	v_exp_f32_e32 v156, v156
	s_nop 0
	v_add_f32_e32 v154, 1.0, v156
	v_rcp_f32_e32 v152, v149
	s_nop 0
	v_mul_f32_e32 v126, v126, v152
	v_mul_f32_e32 v122, v126, v122
	v_mul_f32_e32 v152, 0xbfb8aa3b, v128
	v_exp_f32_e32 v152, v152
	v_rcp_f32_e32 v126, v154
	s_nop 0
	v_mul_f32_e32 v126, v127, v126
	v_add_f32_e32 v149, 1.0, v152
	v_mul_f32_e32 v123, v126, v123
	v_mul_f32_e32 v127, 0xbfb8aa3b, v129
	v_cvt_pk_bf16_f32 v122, v122, v123
	v_exp_f32_e32 v127, v127
	s_nop 0
	v_add_f32_e32 v127, 1.0, v127
	v_rcp_f32_e32 v123, v149
	s_nop 0
	v_mul_f32_e32 v123, v128, v123
	v_mul_f32_e32 v123, v123, v124
	v_mul_f32_e32 v128, 0xbfb8aa3b, v118
	v_exp_f32_e32 v128, v128
	v_rcp_f32_e32 v124, v127
	s_nop 0
	v_mul_f32_e32 v124, v129, v124
	v_add_f32_e32 v126, 1.0, v128
	v_mul_f32_e32 v124, v124, v125
	v_mul_f32_e32 v127, 0xbfb8aa3b, v119
	v_cvt_pk_bf16_f32 v123, v123, v124
	v_exp_f32_e32 v127, v127
	s_nop 0
	v_add_f32_e32 v127, 1.0, v127
	v_rcp_f32_e32 v124, v126
	s_nop 0
	v_mul_f32_e32 v118, v118, v124
	v_mul_f32_e32 v114, v118, v114
	v_mul_f32_e32 v125, 0xbfb8aa3b, v120
	v_exp_f32_e32 v125, v125
	v_rcp_f32_e32 v118, v127
	s_nop 0
	v_mul_f32_e32 v118, v119, v118
	v_add_f32_e32 v125, 1.0, v125
	v_mul_f32_e32 v115, v118, v115
	v_mul_f32_e32 v118, 0xbfb8aa3b, v121
	v_exp_f32_e32 v118, v118
	v_cvt_pk_bf16_f32 v124, v114, v115
	v_add_f32_e32 v118, 1.0, v118
	v_rcp_f32_e32 v114, v125
	s_nop 0
	v_mul_f32_e32 v114, v120, v114
	v_mul_f32_e32 v114, v114, v116
	v_rcp_f32_e32 v115, v118
	s_nop 0
	v_mul_f32_e32 v115, v121, v115
	v_mul_f32_e32 v115, v115, v117
	v_cvt_pk_bf16_f32 v125, v114, v115
	v_mul_f32_e32 v114, 0xbfb8aa3b, v110
	v_exp_f32_e32 v116, v114
	v_ashrrev_i32_e32 v151, 31, v150
	v_mov_b64_e32 v[114:115], s[22:23]
	v_mad_i64_i32 v[118:119], s[48:49], v148, s64, v[114:115]
	v_add_f32_e32 v120, 1.0, v116
	v_lshlrev_b64 v[116:117], 1, v[150:151]
	v_lshl_add_u64 v[118:119], v[118:119], 0, v[116:117]
	global_store_dwordx4 v[118:119], v[122:125], off
	s_nop 1
	v_mul_f32_e32 v122, 0xbfb8aa3b, v111
	v_exp_f32_e32 v122, v122
	s_nop 0
	v_add_f32_e32 v121, 1.0, v122
	v_rcp_f32_e32 v118, v120
	s_nop 0
	v_mul_f32_e32 v110, v110, v118
	v_mul_f32_e32 v106, v110, v106
	v_mul_f32_e32 v119, 0xbfb8aa3b, v112
	v_exp_f32_e32 v119, v119
	v_rcp_f32_e32 v110, v121
	s_nop 0
	v_mul_f32_e32 v110, v111, v110
	v_add_f32_e32 v118, 1.0, v119
	v_mul_f32_e32 v107, v110, v107
	v_mul_f32_e32 v111, 0xbfb8aa3b, v113
	v_cvt_pk_bf16_f32 v106, v106, v107
	v_exp_f32_e32 v111, v111
	s_nop 0
	v_add_f32_e32 v111, 1.0, v111
	v_rcp_f32_e32 v107, v118
	s_nop 0
	v_mul_f32_e32 v107, v112, v107
	v_mul_f32_e32 v107, v107, v108
	v_mul_f32_e32 v112, 0xbfb8aa3b, v102
	v_exp_f32_e32 v112, v112
	v_rcp_f32_e32 v108, v111
	s_nop 0
	v_mul_f32_e32 v108, v113, v108
	v_add_f32_e32 v110, 1.0, v112
	v_mul_f32_e32 v108, v108, v109
	v_mul_f32_e32 v111, 0xbfb8aa3b, v103
	v_cvt_pk_bf16_f32 v107, v107, v108
	v_exp_f32_e32 v111, v111
	s_nop 0
	v_add_f32_e32 v111, 1.0, v111
	v_rcp_f32_e32 v108, v110
	s_nop 0
	v_mul_f32_e32 v102, v102, v108
	v_mul_f32_e32 v98, v102, v98
	v_mul_f32_e32 v109, 0xbfb8aa3b, v104
	v_exp_f32_e32 v109, v109
	v_rcp_f32_e32 v102, v111
	s_nop 0
	v_mul_f32_e32 v102, v103, v102
	v_add_f32_e32 v109, 1.0, v109
	v_mul_f32_e32 v99, v102, v99
	v_mul_f32_e32 v102, 0xbfb8aa3b, v105
	v_exp_f32_e32 v102, v102
	v_cvt_pk_bf16_f32 v108, v98, v99
	v_add_f32_e32 v102, 1.0, v102
	v_rcp_f32_e32 v98, v109
	s_nop 0
	v_mul_f32_e32 v98, v104, v98
	v_mul_f32_e32 v98, v98, v100
	v_mul_f32_e32 v100, 0xbfb8aa3b, v94
	v_exp_f32_e32 v100, v100
	v_rcp_f32_e32 v99, v102
	s_nop 0
	v_mul_f32_e32 v99, v105, v99
	v_mul_f32_e32 v99, v99, v101
	v_cvt_pk_bf16_f32 v109, v98, v99
	v_add_f32_e32 v100, 1.0, v100
	v_or_b32_e32 v98, 16, v148
	v_mad_i64_i32 v[98:99], s[48:49], v98, s64, v[114:115]
	v_lshl_add_u64 v[98:99], v[98:99], 0, v[116:117]
	global_store_dwordx4 v[98:99], v[106:109], off
	v_mul_f32_e32 v103, 0xbfb8aa3b, v95
	v_exp_f32_e32 v103, v103
	s_nop 0
	v_add_f32_e32 v101, 1.0, v103
	v_rcp_f32_e32 v98, v100
	s_nop 0
	v_mul_f32_e32 v94, v94, v98
	v_mul_f32_e32 v90, v94, v90
	v_mul_f32_e32 v99, 0xbfb8aa3b, v96
	v_exp_f32_e32 v99, v99
	v_rcp_f32_e32 v94, v101
	s_nop 0
	v_mul_f32_e32 v94, v95, v94
	v_add_f32_e32 v98, 1.0, v99
	v_mul_f32_e32 v91, v94, v91
	v_mul_f32_e32 v95, 0xbfb8aa3b, v97
	v_cvt_pk_bf16_f32 v90, v90, v91
	v_exp_f32_e32 v95, v95
	s_nop 0
	v_add_f32_e32 v95, 1.0, v95
	v_rcp_f32_e32 v91, v98
	s_nop 0
	v_mul_f32_e32 v91, v96, v91
	v_mul_f32_e32 v91, v91, v92
	v_mul_f32_e32 v96, 0xbfb8aa3b, v86
	v_exp_f32_e32 v96, v96
	v_rcp_f32_e32 v92, v95
	s_nop 0
	v_mul_f32_e32 v92, v97, v92
	v_add_f32_e32 v94, 1.0, v96
	v_mul_f32_e32 v92, v92, v93
	v_mul_f32_e32 v95, 0xbfb8aa3b, v87
	v_cvt_pk_bf16_f32 v91, v91, v92
	v_exp_f32_e32 v95, v95
	s_nop 0
	v_add_f32_e32 v95, 1.0, v95
	v_rcp_f32_e32 v92, v94
	s_nop 0
	v_mul_f32_e32 v86, v86, v92
	v_mul_f32_e32 v82, v86, v82
	v_mul_f32_e32 v93, 0xbfb8aa3b, v88
	v_exp_f32_e32 v93, v93
	v_rcp_f32_e32 v86, v95
	s_nop 0
	v_mul_f32_e32 v86, v87, v86
	v_add_f32_e32 v93, 1.0, v93
	v_mul_f32_e32 v83, v86, v83
	v_mul_f32_e32 v86, 0xbfb8aa3b, v89
	v_exp_f32_e32 v86, v86
	v_cvt_pk_bf16_f32 v92, v82, v83
	v_add_f32_e32 v86, 1.0, v86
	v_rcp_f32_e32 v82, v93
	s_nop 0
	v_mul_f32_e32 v82, v88, v82
	v_mul_f32_e32 v82, v82, v84
	v_mul_f32_e32 v84, 0xbfb8aa3b, v78
	v_exp_f32_e32 v84, v84
	v_rcp_f32_e32 v83, v86
	s_nop 0
	v_mul_f32_e32 v83, v89, v83
	v_mul_f32_e32 v83, v83, v85
	v_cvt_pk_bf16_f32 v93, v82, v83
	v_add_f32_e32 v84, 1.0, v84
	v_or_b32_e32 v82, 32, v148
	v_mad_i64_i32 v[82:83], s[48:49], v82, s64, v[114:115]
	v_lshl_add_u64 v[82:83], v[82:83], 0, v[116:117]
	global_store_dwordx4 v[82:83], v[90:93], off
	v_mul_f32_e32 v87, 0xbfb8aa3b, v79
	v_exp_f32_e32 v87, v87
	s_nop 0
	v_add_f32_e32 v85, 1.0, v87
	v_rcp_f32_e32 v82, v84
	s_nop 0
	v_mul_f32_e32 v78, v78, v82
	v_mul_f32_e32 v74, v78, v74
	v_mul_f32_e32 v83, 0xbfb8aa3b, v80
	v_exp_f32_e32 v83, v83
	v_rcp_f32_e32 v78, v85
	s_nop 0
	v_mul_f32_e32 v78, v79, v78
	v_add_f32_e32 v82, 1.0, v83
	v_mul_f32_e32 v75, v78, v75
	v_mul_f32_e32 v79, 0xbfb8aa3b, v81
	v_cvt_pk_bf16_f32 v74, v74, v75
	v_exp_f32_e32 v79, v79
	s_nop 0
	v_add_f32_e32 v79, 1.0, v79
	v_rcp_f32_e32 v75, v82
	s_nop 0
	v_mul_f32_e32 v75, v80, v75
	v_mul_f32_e32 v75, v75, v76
	v_mul_f32_e32 v80, 0xbfb8aa3b, v70
	v_exp_f32_e32 v80, v80
	v_rcp_f32_e32 v76, v79
	s_nop 0
	v_mul_f32_e32 v76, v81, v76
	v_add_f32_e32 v78, 1.0, v80
	v_mul_f32_e32 v76, v76, v77
	v_mul_f32_e32 v79, 0xbfb8aa3b, v71
	v_cvt_pk_bf16_f32 v75, v75, v76
	v_exp_f32_e32 v79, v79
	s_nop 0
	v_add_f32_e32 v79, 1.0, v79
	v_rcp_f32_e32 v76, v78
	s_nop 0
	v_mul_f32_e32 v70, v70, v76
	v_mul_f32_e32 v66, v70, v66
	v_mul_f32_e32 v77, 0xbfb8aa3b, v72
	v_exp_f32_e32 v77, v77
	v_rcp_f32_e32 v70, v79
	s_nop 0
	v_mul_f32_e32 v70, v71, v70
	v_add_f32_e32 v77, 1.0, v77
	v_mul_f32_e32 v67, v70, v67
	v_mul_f32_e32 v70, 0xbfb8aa3b, v73
	v_exp_f32_e32 v70, v70
	v_cvt_pk_bf16_f32 v76, v66, v67
	v_add_f32_e32 v70, 1.0, v70
	v_rcp_f32_e32 v66, v77
	s_nop 0
	v_mul_f32_e32 v66, v72, v66
	v_mul_f32_e32 v66, v66, v68
	v_rcp_f32_e32 v67, v70
	s_nop 0
	v_mul_f32_e32 v67, v73, v67
	v_mul_f32_e32 v67, v67, v69
	v_cvt_pk_bf16_f32 v77, v66, v67
	v_mul_f32_e32 v66, 0xbfb8aa3b, v62
	v_exp_f32_e32 v68, v66
	v_or_b32_e32 v66, 48, v148
	v_mad_i64_i32 v[66:67], s[48:49], v66, s64, v[114:115]
	v_add_f32_e32 v68, 1.0, v68
	v_lshl_add_u64 v[66:67], v[66:67], 0, v[116:117]
	global_store_dwordx4 v[66:67], v[74:77], off
	v_mul_f32_e32 v72, 0xbfb8aa3b, v63
	v_exp_f32_e32 v72, v72
	s_nop 0
	v_add_f32_e32 v69, 1.0, v72
	v_rcp_f32_e32 v67, v68
	s_nop 0
	v_mul_f32_e32 v62, v62, v67
	v_mul_f32_e32 v58, v62, v58
	v_mul_f32_e32 v68, 0xbfb8aa3b, v64
	v_exp_f32_e32 v68, v68
	v_rcp_f32_e32 v62, v69
	s_nop 0
	v_mul_f32_e32 v62, v63, v62
	v_add_f32_e32 v67, 1.0, v68
	v_mul_f32_e32 v59, v62, v59
	v_mul_f32_e32 v63, 0xbfb8aa3b, v65
	v_cvt_pk_bf16_f32 v58, v58, v59
	v_exp_f32_e32 v63, v63
	s_nop 0
	v_add_f32_e32 v63, 1.0, v63
	v_rcp_f32_e32 v59, v67
	s_nop 0
	v_mul_f32_e32 v59, v64, v59
	v_mul_f32_e32 v59, v59, v60
	v_mul_f32_e32 v64, 0xbfb8aa3b, v54
	v_exp_f32_e32 v64, v64
	v_rcp_f32_e32 v60, v63
	s_nop 0
	v_mul_f32_e32 v60, v65, v60
	v_add_f32_e32 v62, 1.0, v64
	v_mul_f32_e32 v60, v60, v61
	v_mul_f32_e32 v63, 0xbfb8aa3b, v55
	v_cvt_pk_bf16_f32 v59, v59, v60
	v_exp_f32_e32 v63, v63
	s_nop 0
	v_add_f32_e32 v63, 1.0, v63
	v_rcp_f32_e32 v60, v62
	s_nop 0
	v_mul_f32_e32 v54, v54, v60
	v_mul_f32_e32 v50, v54, v50
	v_mul_f32_e32 v61, 0xbfb8aa3b, v56
	v_exp_f32_e32 v61, v61
	v_rcp_f32_e32 v54, v63
	s_nop 0
	v_mul_f32_e32 v54, v55, v54
	v_add_f32_e32 v61, 1.0, v61
	v_mul_f32_e32 v51, v54, v51
	v_mul_f32_e32 v54, 0xbfb8aa3b, v57
	v_exp_f32_e32 v54, v54
	v_cvt_pk_bf16_f32 v60, v50, v51
	v_add_f32_e32 v54, 1.0, v54
	v_rcp_f32_e32 v50, v61
	s_nop 0
	v_mul_f32_e32 v50, v56, v50
	v_mul_f32_e32 v50, v50, v52
	v_mul_f32_e32 v52, 0xbfb8aa3b, v46
	v_exp_f32_e32 v52, v52
	v_rcp_f32_e32 v51, v54
	s_nop 0
	v_mul_f32_e32 v51, v57, v51
	v_mul_f32_e32 v51, v51, v53
	v_add_u32_e32 v66, 0x80, v148
	v_add_f32_e32 v52, 1.0, v52
	v_cvt_pk_bf16_f32 v61, v50, v51
	v_mad_i64_i32 v[50:51], s[48:49], v66, s64, v[114:115]
	v_lshl_add_u64 v[50:51], v[50:51], 0, v[116:117]
	global_store_dwordx4 v[50:51], v[58:61], off
	v_mul_f32_e32 v55, 0xbfb8aa3b, v47
	v_exp_f32_e32 v55, v55
	s_nop 0
	v_add_f32_e32 v53, 1.0, v55
	v_rcp_f32_e32 v50, v52
	s_nop 0
	v_mul_f32_e32 v46, v46, v50
	v_mul_f32_e32 v42, v46, v42
	v_mul_f32_e32 v51, 0xbfb8aa3b, v48
	v_exp_f32_e32 v51, v51
	v_rcp_f32_e32 v46, v53
	s_nop 0
	v_mul_f32_e32 v46, v47, v46
	v_add_f32_e32 v50, 1.0, v51
	v_mul_f32_e32 v43, v46, v43
	v_mul_f32_e32 v47, 0xbfb8aa3b, v49
	v_cvt_pk_bf16_f32 v42, v42, v43
	v_exp_f32_e32 v47, v47
	s_nop 0
	v_add_f32_e32 v47, 1.0, v47
	v_rcp_f32_e32 v43, v50
	s_nop 0
	v_mul_f32_e32 v43, v48, v43
	v_mul_f32_e32 v43, v43, v44
	v_mul_f32_e32 v48, 0xbfb8aa3b, v38
	v_exp_f32_e32 v48, v48
	v_rcp_f32_e32 v44, v47
	s_nop 0
	v_mul_f32_e32 v44, v49, v44
	v_add_f32_e32 v46, 1.0, v48
	v_mul_f32_e32 v44, v44, v45
	v_mul_f32_e32 v47, 0xbfb8aa3b, v39
	v_cvt_pk_bf16_f32 v43, v43, v44
	v_exp_f32_e32 v47, v47
	s_nop 0
	v_add_f32_e32 v47, 1.0, v47
	v_rcp_f32_e32 v44, v46
	s_nop 0
	v_mul_f32_e32 v38, v38, v44
	v_mul_f32_e32 v34, v38, v34
	v_mul_f32_e32 v45, 0xbfb8aa3b, v40
	v_exp_f32_e32 v45, v45
	v_rcp_f32_e32 v38, v47
	s_nop 0
	v_mul_f32_e32 v38, v39, v38
	v_add_f32_e32 v45, 1.0, v45
	v_mul_f32_e32 v35, v38, v35
	v_mul_f32_e32 v38, 0xbfb8aa3b, v41
	v_exp_f32_e32 v38, v38
	v_cvt_pk_bf16_f32 v44, v34, v35
	v_add_f32_e32 v38, 1.0, v38
	v_rcp_f32_e32 v34, v45
	s_nop 0
	v_mul_f32_e32 v34, v40, v34
	v_mul_f32_e32 v34, v34, v36
	v_mul_f32_e32 v36, 0xbfb8aa3b, v30
	v_exp_f32_e32 v36, v36
	v_rcp_f32_e32 v35, v38
	s_nop 0
	v_mul_f32_e32 v35, v41, v35
	v_mul_f32_e32 v35, v35, v37
	v_cvt_pk_bf16_f32 v45, v34, v35
	v_add_f32_e32 v36, 1.0, v36
	v_add_u32_e32 v34, 0x90, v148
	v_mad_i64_i32 v[34:35], s[48:49], v34, s64, v[114:115]
	v_lshl_add_u64 v[34:35], v[34:35], 0, v[116:117]
	global_store_dwordx4 v[34:35], v[42:45], off
	v_mul_f32_e32 v39, 0xbfb8aa3b, v31
	v_exp_f32_e32 v39, v39
	s_nop 0
	v_add_f32_e32 v37, 1.0, v39
	v_rcp_f32_e32 v34, v36
	s_nop 0
	v_mul_f32_e32 v30, v30, v34
	v_mul_f32_e32 v26, v30, v26
	v_mul_f32_e32 v35, 0xbfb8aa3b, v32
	v_exp_f32_e32 v35, v35
	v_rcp_f32_e32 v30, v37
	s_nop 0
	v_mul_f32_e32 v30, v31, v30
	v_add_f32_e32 v34, 1.0, v35
	v_mul_f32_e32 v27, v30, v27
	v_mul_f32_e32 v31, 0xbfb8aa3b, v33
	v_cvt_pk_bf16_f32 v26, v26, v27
	v_exp_f32_e32 v31, v31
	s_nop 0
	v_add_f32_e32 v31, 1.0, v31
	v_rcp_f32_e32 v27, v34
	s_nop 0
	v_mul_f32_e32 v27, v32, v27
	v_mul_f32_e32 v27, v27, v28
	v_mul_f32_e32 v32, 0xbfb8aa3b, v22
	v_exp_f32_e32 v32, v32
	v_rcp_f32_e32 v28, v31
	s_nop 0
	v_mul_f32_e32 v28, v33, v28
	v_add_f32_e32 v30, 1.0, v32
	v_mul_f32_e32 v28, v28, v29
	v_mul_f32_e32 v31, 0xbfb8aa3b, v23
	v_cvt_pk_bf16_f32 v27, v27, v28
	v_exp_f32_e32 v31, v31
	s_nop 0
	v_add_f32_e32 v31, 1.0, v31
	v_rcp_f32_e32 v28, v30
	s_nop 0
	v_mul_f32_e32 v22, v22, v28
	v_mul_f32_e32 v18, v22, v18
	v_mul_f32_e32 v29, 0xbfb8aa3b, v24
	v_exp_f32_e32 v29, v29
	v_rcp_f32_e32 v22, v31
	s_nop 0
	v_mul_f32_e32 v22, v23, v22
	v_add_f32_e32 v29, 1.0, v29
	v_mul_f32_e32 v19, v22, v19
	v_mul_f32_e32 v22, 0xbfb8aa3b, v25
	v_exp_f32_e32 v22, v22
	v_cvt_pk_bf16_f32 v28, v18, v19
	v_add_f32_e32 v22, 1.0, v22
	v_rcp_f32_e32 v18, v29
	s_nop 0
	v_mul_f32_e32 v18, v24, v18
	v_mul_f32_e32 v18, v18, v20
	v_mul_f32_e32 v20, 0xbfb8aa3b, v14
	v_exp_f32_e32 v20, v20
	v_rcp_f32_e32 v19, v22
	s_nop 0
	v_mul_f32_e32 v19, v25, v19
	v_mul_f32_e32 v19, v19, v21
	v_cvt_pk_bf16_f32 v29, v18, v19
	v_add_f32_e32 v20, 1.0, v20
	v_add_u32_e32 v18, 0xa0, v148
	v_mad_i64_i32 v[18:19], s[48:49], v18, s64, v[114:115]
	v_lshl_add_u64 v[18:19], v[18:19], 0, v[116:117]
	global_store_dwordx4 v[18:19], v[26:29], off
	v_mul_f32_e32 v23, 0xbfb8aa3b, v15
	v_exp_f32_e32 v23, v23
	s_nop 0
	v_add_f32_e32 v21, 1.0, v23
	v_rcp_f32_e32 v18, v20
	s_nop 0
	v_mul_f32_e32 v14, v14, v18
	v_mul_f32_e32 v10, v14, v10
	v_mul_f32_e32 v19, 0xbfb8aa3b, v16
	v_exp_f32_e32 v19, v19
	v_rcp_f32_e32 v14, v21
	s_nop 0
	v_mul_f32_e32 v14, v15, v14
	v_add_f32_e32 v18, 1.0, v19
	v_mul_f32_e32 v11, v14, v11
	v_mul_f32_e32 v15, 0xbfb8aa3b, v17
	v_cvt_pk_bf16_f32 v10, v10, v11
	v_exp_f32_e32 v15, v15
	s_nop 0
	v_add_f32_e32 v15, 1.0, v15
	v_rcp_f32_e32 v11, v18
	s_nop 0
	v_mul_f32_e32 v11, v16, v11
	v_mul_f32_e32 v11, v11, v12
	v_mul_f32_e32 v16, 0xbfb8aa3b, v6
	v_exp_f32_e32 v16, v16
	v_rcp_f32_e32 v12, v15
	s_nop 0
	v_mul_f32_e32 v12, v17, v12
	v_add_f32_e32 v14, 1.0, v16
	v_mul_f32_e32 v12, v12, v13
	v_mul_f32_e32 v15, 0xbfb8aa3b, v7
	v_cvt_pk_bf16_f32 v11, v11, v12
	v_exp_f32_e32 v15, v15
	s_nop 0
	v_add_f32_e32 v15, 1.0, v15
	v_rcp_f32_e32 v12, v14
	s_nop 0
	v_mul_f32_e32 v6, v6, v12
	v_mul_f32_e32 v2, v6, v2
	v_mul_f32_e32 v13, 0xbfb8aa3b, v8
	v_exp_f32_e32 v13, v13
	v_rcp_f32_e32 v6, v15
	s_nop 0
	v_mul_f32_e32 v6, v7, v6
	v_add_f32_e32 v13, 1.0, v13
	v_mul_f32_e32 v3, v6, v3
	v_mul_f32_e32 v6, 0xbfb8aa3b, v9
	v_exp_f32_e32 v6, v6
	v_cvt_pk_bf16_f32 v12, v2, v3
	v_add_f32_e32 v6, 1.0, v6
	v_rcp_f32_e32 v2, v13
	s_nop 0
	v_mul_f32_e32 v2, v8, v2
	v_mul_f32_e32 v2, v2, v4
	v_rcp_f32_e32 v3, v6
	s_nop 0
	v_mul_f32_e32 v3, v9, v3
	v_mul_f32_e32 v3, v3, v5
	v_cvt_pk_bf16_f32 v13, v2, v3
	v_add_u32_e32 v2, 0xb0, v148
	v_mad_i64_i32 v[2:3], s[48:49], v2, s64, v[114:115]
	v_lshl_add_u64 v[2:3], v[2:3], 0, v[116:117]
	s_mov_b64 s[48:49], -1
	s_and_b64 vcc, exec, s[44:45]
	global_store_dwordx4 v[2:3], v[10:13], off
	s_cbranch_vccz .LBB0_3204
	s_andn2_b64 vcc, exec, s[6:7]
	s_cbranch_vccnz .LBB0_3203
	s_barrier
	s_branch .LBB0_3203

.LBB0_3404:
	v_mul_f32_e32 v133, 0xbfb8aa3b, v126
	v_exp_f32_e32 v133, v133
	s_lshl_b32 s5, s40, 7
	s_or_b32 s5, s34, s5
	v_or_b32_e32 v134, s5, v131
	v_add_f32_e32 v133, 1.0, v133
	v_mul_f32_e32 v140, 0xbfb8aa3b, v127
	v_exp_f32_e32 v140, v140
	v_add_u32_e32 v136, 0x4000, v1
	v_add_f32_e32 v137, 1.0, v140
	v_rcp_f32_e32 v131, v133
	s_nop 0
	v_mul_f32_e32 v126, v126, v131
	v_mul_f32_e32 v122, v126, v122
	v_mul_f32_e32 v133, 0xbfb8aa3b, v128
	v_exp_f32_e32 v133, v133
	v_rcp_f32_e32 v126, v137
	s_nop 0
	v_mul_f32_e32 v126, v127, v126
	v_add_f32_e32 v131, 1.0, v133
	v_mul_f32_e32 v123, v126, v123
	v_mul_f32_e32 v127, 0xbfb8aa3b, v129
	v_cvt_pk_bf16_f32 v122, v122, v123
	v_exp_f32_e32 v127, v127
	s_nop 0
	v_add_f32_e32 v127, 1.0, v127
	v_rcp_f32_e32 v123, v131
	s_nop 0
	v_mul_f32_e32 v123, v128, v123
	v_mul_f32_e32 v123, v123, v124
	v_mul_f32_e32 v128, 0xbfb8aa3b, v118
	v_exp_f32_e32 v128, v128
	v_rcp_f32_e32 v124, v127
	s_nop 0
	v_mul_f32_e32 v124, v129, v124
	v_add_f32_e32 v126, 1.0, v128
	v_mul_f32_e32 v124, v124, v125
	v_mul_f32_e32 v127, 0xbfb8aa3b, v119
	v_cvt_pk_bf16_f32 v123, v123, v124
	v_exp_f32_e32 v127, v127
	s_nop 0
	v_add_f32_e32 v127, 1.0, v127
	v_rcp_f32_e32 v124, v126
	s_nop 0
	v_mul_f32_e32 v118, v118, v124
	v_mul_f32_e32 v114, v118, v114
	v_mul_f32_e32 v125, 0xbfb8aa3b, v120
	v_exp_f32_e32 v125, v125
	v_rcp_f32_e32 v118, v127
	s_nop 0
	v_mul_f32_e32 v118, v119, v118
	v_add_f32_e32 v125, 1.0, v125
	v_mul_f32_e32 v115, v118, v115
	v_mul_f32_e32 v118, 0xbfb8aa3b, v121
	v_exp_f32_e32 v118, v118
	v_cvt_pk_bf16_f32 v124, v114, v115
	v_add_f32_e32 v118, 1.0, v118
	v_rcp_f32_e32 v114, v125
	s_nop 0
	v_mul_f32_e32 v114, v120, v114
	v_mul_f32_e32 v114, v114, v116
	v_rcp_f32_e32 v115, v118
	s_nop 0
	v_mul_f32_e32 v115, v121, v115
	v_mul_f32_e32 v115, v115, v117
	v_cvt_pk_bf16_f32 v125, v114, v115
	v_mul_f32_e32 v114, 0xbfb8aa3b, v110
	v_exp_f32_e32 v116, v114
	v_ashrrev_i32_e32 v135, 31, v134
	s_movk_i32 s5, 0x1600
	v_mov_b64_e32 v[114:115], s[18:19]
	v_add_f32_e32 v120, 1.0, v116
	v_mad_i64_i32 v[118:119], s[8:9], v136, s5, v[114:115]
	v_lshlrev_b64 v[116:117], 1, v[134:135]
	v_lshl_add_u64 v[118:119], v[118:119], 0, v[116:117]
	global_store_dwordx4 v[118:119], v[122:125], off
	s_nop 1
	v_mul_f32_e32 v122, 0xbfb8aa3b, v111
	v_exp_f32_e32 v122, v122
	s_nop 0
	v_add_f32_e32 v121, 1.0, v122
	v_rcp_f32_e32 v118, v120
	s_nop 0
	v_mul_f32_e32 v110, v110, v118
	v_mul_f32_e32 v106, v110, v106
	v_mul_f32_e32 v119, 0xbfb8aa3b, v112
	v_exp_f32_e32 v119, v119
	v_rcp_f32_e32 v110, v121
	s_nop 0
	v_mul_f32_e32 v110, v111, v110
	v_add_f32_e32 v118, 1.0, v119
	v_mul_f32_e32 v107, v110, v107
	v_mul_f32_e32 v111, 0xbfb8aa3b, v113
	v_cvt_pk_bf16_f32 v106, v106, v107
	v_exp_f32_e32 v111, v111
	s_nop 0
	v_add_f32_e32 v111, 1.0, v111
	v_rcp_f32_e32 v107, v118
	s_nop 0
	v_mul_f32_e32 v107, v112, v107
	v_mul_f32_e32 v107, v107, v108
	v_mul_f32_e32 v112, 0xbfb8aa3b, v102
	v_exp_f32_e32 v112, v112
	v_rcp_f32_e32 v108, v111
	s_nop 0
	v_mul_f32_e32 v108, v113, v108
	v_add_f32_e32 v110, 1.0, v112
	v_mul_f32_e32 v108, v108, v109
	v_mul_f32_e32 v111, 0xbfb8aa3b, v103
	v_cvt_pk_bf16_f32 v107, v107, v108
	v_exp_f32_e32 v111, v111
	s_nop 0
	v_add_f32_e32 v111, 1.0, v111
	v_rcp_f32_e32 v108, v110
	s_nop 0
	v_mul_f32_e32 v102, v102, v108
	v_mul_f32_e32 v98, v102, v98
	v_mul_f32_e32 v109, 0xbfb8aa3b, v104
	v_exp_f32_e32 v109, v109
	v_rcp_f32_e32 v102, v111
	s_nop 0
	v_mul_f32_e32 v102, v103, v102
	v_add_f32_e32 v109, 1.0, v109
	v_mul_f32_e32 v99, v102, v99
	v_mul_f32_e32 v102, 0xbfb8aa3b, v105
	v_exp_f32_e32 v102, v102
	v_cvt_pk_bf16_f32 v108, v98, v99
	v_add_f32_e32 v102, 1.0, v102
	v_rcp_f32_e32 v98, v109
	s_nop 0
	v_mul_f32_e32 v98, v104, v98
	v_mul_f32_e32 v98, v98, v100
	v_mul_f32_e32 v100, 0xbfb8aa3b, v94
	v_exp_f32_e32 v100, v100
	v_rcp_f32_e32 v99, v102
	s_nop 0
	v_mul_f32_e32 v99, v105, v99
	v_mul_f32_e32 v99, v99, v101
	v_cvt_pk_bf16_f32 v109, v98, v99
	v_add_f32_e32 v100, 1.0, v100
	v_add_u32_e32 v98, 0x4010, v1
	v_mad_i64_i32 v[98:99], s[8:9], v98, s5, v[114:115]
	v_lshl_add_u64 v[98:99], v[98:99], 0, v[116:117]
	global_store_dwordx4 v[98:99], v[106:109], off
	v_mul_f32_e32 v103, 0xbfb8aa3b, v95
	v_exp_f32_e32 v103, v103
	s_nop 0
	v_add_f32_e32 v101, 1.0, v103
	v_rcp_f32_e32 v98, v100
	s_nop 0
	v_mul_f32_e32 v94, v94, v98
	v_mul_f32_e32 v90, v94, v90
	v_mul_f32_e32 v99, 0xbfb8aa3b, v96
	v_exp_f32_e32 v99, v99
	v_rcp_f32_e32 v94, v101
	s_nop 0
	v_mul_f32_e32 v94, v95, v94
	v_add_f32_e32 v98, 1.0, v99
	v_mul_f32_e32 v91, v94, v91
	v_mul_f32_e32 v95, 0xbfb8aa3b, v97
	v_cvt_pk_bf16_f32 v90, v90, v91
	v_exp_f32_e32 v95, v95
	s_nop 0
	v_add_f32_e32 v95, 1.0, v95
	v_rcp_f32_e32 v91, v98
	s_nop 0
	v_mul_f32_e32 v91, v96, v91
	v_mul_f32_e32 v91, v91, v92
	v_mul_f32_e32 v96, 0xbfb8aa3b, v86
	v_exp_f32_e32 v96, v96
	v_rcp_f32_e32 v92, v95
	s_nop 0
	v_mul_f32_e32 v92, v97, v92
	v_add_f32_e32 v94, 1.0, v96
	v_mul_f32_e32 v92, v92, v93
	v_mul_f32_e32 v95, 0xbfb8aa3b, v87
	v_cvt_pk_bf16_f32 v91, v91, v92
	v_exp_f32_e32 v95, v95
	s_nop 0
	v_add_f32_e32 v95, 1.0, v95
	v_rcp_f32_e32 v92, v94
	s_nop 0
	v_mul_f32_e32 v86, v86, v92
	v_mul_f32_e32 v82, v86, v82
	v_mul_f32_e32 v93, 0xbfb8aa3b, v88
	v_exp_f32_e32 v93, v93
	v_rcp_f32_e32 v86, v95
	s_nop 0
	v_mul_f32_e32 v86, v87, v86
	v_add_f32_e32 v93, 1.0, v93
	v_mul_f32_e32 v83, v86, v83
	v_mul_f32_e32 v86, 0xbfb8aa3b, v89
	v_exp_f32_e32 v86, v86
	v_cvt_pk_bf16_f32 v92, v82, v83
	v_add_f32_e32 v86, 1.0, v86
	v_rcp_f32_e32 v82, v93
	s_nop 0
	v_mul_f32_e32 v82, v88, v82
	v_mul_f32_e32 v82, v82, v84
	v_mul_f32_e32 v84, 0xbfb8aa3b, v78
	v_exp_f32_e32 v84, v84
	v_rcp_f32_e32 v83, v86
	s_nop 0
	v_mul_f32_e32 v83, v89, v83
	v_mul_f32_e32 v83, v83, v85
	v_cvt_pk_bf16_f32 v93, v82, v83
	v_add_f32_e32 v84, 1.0, v84
	v_add_u32_e32 v82, 0x4020, v1
	v_mad_i64_i32 v[82:83], s[8:9], v82, s5, v[114:115]
	v_lshl_add_u64 v[82:83], v[82:83], 0, v[116:117]
	global_store_dwordx4 v[82:83], v[90:93], off
	v_mul_f32_e32 v87, 0xbfb8aa3b, v79
	v_exp_f32_e32 v87, v87
	s_nop 0
	v_add_f32_e32 v85, 1.0, v87
	v_rcp_f32_e32 v82, v84
	s_nop 0
	v_mul_f32_e32 v78, v78, v82
	v_mul_f32_e32 v74, v78, v74
	v_mul_f32_e32 v83, 0xbfb8aa3b, v80
	v_exp_f32_e32 v83, v83
	v_rcp_f32_e32 v78, v85
	s_nop 0
	v_mul_f32_e32 v78, v79, v78
	v_add_f32_e32 v82, 1.0, v83
	v_mul_f32_e32 v75, v78, v75
	v_mul_f32_e32 v79, 0xbfb8aa3b, v81
	v_cvt_pk_bf16_f32 v74, v74, v75
	v_exp_f32_e32 v79, v79
	s_nop 0
	v_add_f32_e32 v79, 1.0, v79
	v_rcp_f32_e32 v75, v82
	s_nop 0
	v_mul_f32_e32 v75, v80, v75
	v_mul_f32_e32 v75, v75, v76
	v_mul_f32_e32 v80, 0xbfb8aa3b, v70
	v_exp_f32_e32 v80, v80
	v_rcp_f32_e32 v76, v79
	s_nop 0
	v_mul_f32_e32 v76, v81, v76
	v_add_f32_e32 v78, 1.0, v80
	v_mul_f32_e32 v76, v76, v77
	v_mul_f32_e32 v79, 0xbfb8aa3b, v71
	v_cvt_pk_bf16_f32 v75, v75, v76
	v_exp_f32_e32 v79, v79
	s_nop 0
	v_add_f32_e32 v79, 1.0, v79
	v_rcp_f32_e32 v76, v78
	s_nop 0
	v_mul_f32_e32 v70, v70, v76
	v_mul_f32_e32 v66, v70, v66
	v_mul_f32_e32 v77, 0xbfb8aa3b, v72
	v_exp_f32_e32 v77, v77
	v_rcp_f32_e32 v70, v79
	s_nop 0
	v_mul_f32_e32 v70, v71, v70
	v_add_f32_e32 v77, 1.0, v77
	v_mul_f32_e32 v67, v70, v67
	v_mul_f32_e32 v70, 0xbfb8aa3b, v73
	v_exp_f32_e32 v70, v70
	v_cvt_pk_bf16_f32 v76, v66, v67
	v_add_f32_e32 v70, 1.0, v70
	v_rcp_f32_e32 v66, v77
	s_nop 0
	v_mul_f32_e32 v66, v72, v66
	v_mul_f32_e32 v66, v66, v68
	v_rcp_f32_e32 v67, v70
	s_nop 0
	v_mul_f32_e32 v67, v73, v67
	v_mul_f32_e32 v67, v67, v69
	v_cvt_pk_bf16_f32 v77, v66, v67
	v_mul_f32_e32 v66, 0xbfb8aa3b, v62
	v_exp_f32_e32 v68, v66
	v_add_u32_e32 v66, 0x4030, v1
	v_mad_i64_i32 v[66:67], s[8:9], v66, s5, v[114:115]
	v_add_f32_e32 v68, 1.0, v68
	v_lshl_add_u64 v[66:67], v[66:67], 0, v[116:117]
	global_store_dwordx4 v[66:67], v[74:77], off
	v_mul_f32_e32 v72, 0xbfb8aa3b, v63
	v_exp_f32_e32 v72, v72
	s_nop 0
	v_add_f32_e32 v69, 1.0, v72
	v_rcp_f32_e32 v67, v68
	s_nop 0
	v_mul_f32_e32 v62, v62, v67
	v_mul_f32_e32 v58, v62, v58
	v_mul_f32_e32 v68, 0xbfb8aa3b, v64
	v_exp_f32_e32 v68, v68
	v_rcp_f32_e32 v62, v69
	s_nop 0
	v_mul_f32_e32 v62, v63, v62
	v_add_f32_e32 v67, 1.0, v68
	v_mul_f32_e32 v59, v62, v59
	v_mul_f32_e32 v63, 0xbfb8aa3b, v65
	v_cvt_pk_bf16_f32 v58, v58, v59
	v_exp_f32_e32 v63, v63
	s_nop 0
	v_add_f32_e32 v63, 1.0, v63
	v_rcp_f32_e32 v59, v67
	s_nop 0
	v_mul_f32_e32 v59, v64, v59
	v_mul_f32_e32 v59, v59, v60
	v_mul_f32_e32 v64, 0xbfb8aa3b, v54
	v_exp_f32_e32 v64, v64
	v_rcp_f32_e32 v60, v63
	s_nop 0
	v_mul_f32_e32 v60, v65, v60
	v_add_f32_e32 v62, 1.0, v64
	v_mul_f32_e32 v60, v60, v61
	v_mul_f32_e32 v63, 0xbfb8aa3b, v55
	v_cvt_pk_bf16_f32 v59, v59, v60
	v_exp_f32_e32 v63, v63
	s_nop 0
	v_add_f32_e32 v63, 1.0, v63
	v_rcp_f32_e32 v60, v62
	s_nop 0
	v_mul_f32_e32 v54, v54, v60
	v_mul_f32_e32 v50, v54, v50
	v_mul_f32_e32 v61, 0xbfb8aa3b, v56
	v_exp_f32_e32 v61, v61
	v_rcp_f32_e32 v54, v63
	s_nop 0
	v_mul_f32_e32 v54, v55, v54
	v_add_f32_e32 v61, 1.0, v61
	v_mul_f32_e32 v51, v54, v51
	v_mul_f32_e32 v54, 0xbfb8aa3b, v57
	v_exp_f32_e32 v54, v54
	v_cvt_pk_bf16_f32 v60, v50, v51
	v_add_f32_e32 v54, 1.0, v54
	v_rcp_f32_e32 v50, v61
	s_nop 0
	v_mul_f32_e32 v50, v56, v50
	v_mul_f32_e32 v50, v50, v52
	v_mul_f32_e32 v52, 0xbfb8aa3b, v46
	v_exp_f32_e32 v52, v52
	v_rcp_f32_e32 v51, v54
	s_nop 0
	v_mul_f32_e32 v51, v57, v51
	v_mul_f32_e32 v51, v51, v53
	v_add_u32_e32 v66, 0x4080, v1
	v_add_f32_e32 v52, 1.0, v52
	v_cvt_pk_bf16_f32 v61, v50, v51
	v_mad_i64_i32 v[50:51], s[8:9], v66, s5, v[114:115]
	v_lshl_add_u64 v[50:51], v[50:51], 0, v[116:117]
	global_store_dwordx4 v[50:51], v[58:61], off
	v_mul_f32_e32 v55, 0xbfb8aa3b, v47
	v_exp_f32_e32 v55, v55
	s_nop 0
	v_add_f32_e32 v53, 1.0, v55
	v_rcp_f32_e32 v50, v52
	s_nop 0
	v_mul_f32_e32 v46, v46, v50
	v_mul_f32_e32 v42, v46, v42
	v_mul_f32_e32 v51, 0xbfb8aa3b, v48
	v_exp_f32_e32 v51, v51
	v_rcp_f32_e32 v46, v53
	s_nop 0
	v_mul_f32_e32 v46, v47, v46
	v_add_f32_e32 v50, 1.0, v51
	v_mul_f32_e32 v43, v46, v43
	v_mul_f32_e32 v47, 0xbfb8aa3b, v49
	v_cvt_pk_bf16_f32 v42, v42, v43
	v_exp_f32_e32 v47, v47
	s_nop 0
	v_add_f32_e32 v47, 1.0, v47
	v_rcp_f32_e32 v43, v50
	s_nop 0
	v_mul_f32_e32 v43, v48, v43
	v_mul_f32_e32 v43, v43, v44
	v_mul_f32_e32 v48, 0xbfb8aa3b, v38
	v_exp_f32_e32 v48, v48
	v_rcp_f32_e32 v44, v47
	s_nop 0
	v_mul_f32_e32 v44, v49, v44
	v_add_f32_e32 v46, 1.0, v48
	v_mul_f32_e32 v44, v44, v45
	v_mul_f32_e32 v47, 0xbfb8aa3b, v39
	v_cvt_pk_bf16_f32 v43, v43, v44
	v_exp_f32_e32 v47, v47
	s_nop 0
	v_add_f32_e32 v47, 1.0, v47
	v_rcp_f32_e32 v44, v46
	s_nop 0
	v_mul_f32_e32 v38, v38, v44
	v_mul_f32_e32 v34, v38, v34
	v_mul_f32_e32 v45, 0xbfb8aa3b, v40
	v_exp_f32_e32 v45, v45
	v_rcp_f32_e32 v38, v47
	s_nop 0
	v_mul_f32_e32 v38, v39, v38
	v_add_f32_e32 v45, 1.0, v45
	v_mul_f32_e32 v35, v38, v35
	v_mul_f32_e32 v38, 0xbfb8aa3b, v41
	v_exp_f32_e32 v38, v38
	v_cvt_pk_bf16_f32 v44, v34, v35
	v_add_f32_e32 v38, 1.0, v38
	v_rcp_f32_e32 v34, v45
	s_nop 0
	v_mul_f32_e32 v34, v40, v34
	v_mul_f32_e32 v34, v34, v36
	v_mul_f32_e32 v36, 0xbfb8aa3b, v30
	v_exp_f32_e32 v36, v36
	v_rcp_f32_e32 v35, v38
	s_nop 0
	v_mul_f32_e32 v35, v41, v35
	v_mul_f32_e32 v35, v35, v37
	v_cvt_pk_bf16_f32 v45, v34, v35
	v_add_f32_e32 v36, 1.0, v36
	v_add_u32_e32 v34, 0x4090, v1
	v_mad_i64_i32 v[34:35], s[8:9], v34, s5, v[114:115]
	v_lshl_add_u64 v[34:35], v[34:35], 0, v[116:117]
	global_store_dwordx4 v[34:35], v[42:45], off
	v_mul_f32_e32 v39, 0xbfb8aa3b, v31
	v_exp_f32_e32 v39, v39
	s_nop 0
	v_add_f32_e32 v37, 1.0, v39
	v_rcp_f32_e32 v34, v36
	s_nop 0
	v_mul_f32_e32 v30, v30, v34
	v_mul_f32_e32 v26, v30, v26
	v_mul_f32_e32 v35, 0xbfb8aa3b, v32
	v_exp_f32_e32 v35, v35
	v_rcp_f32_e32 v30, v37
	s_nop 0
	v_mul_f32_e32 v30, v31, v30
	v_add_f32_e32 v34, 1.0, v35
	v_mul_f32_e32 v27, v30, v27
	v_mul_f32_e32 v31, 0xbfb8aa3b, v33
	v_cvt_pk_bf16_f32 v26, v26, v27
	v_exp_f32_e32 v31, v31
	s_nop 0
	v_add_f32_e32 v31, 1.0, v31
	v_rcp_f32_e32 v27, v34
	s_nop 0
	v_mul_f32_e32 v27, v32, v27
	v_mul_f32_e32 v27, v27, v28
	v_mul_f32_e32 v32, 0xbfb8aa3b, v22
	v_exp_f32_e32 v32, v32
	v_rcp_f32_e32 v28, v31
	s_nop 0
	v_mul_f32_e32 v28, v33, v28
	v_add_f32_e32 v30, 1.0, v32
	v_mul_f32_e32 v28, v28, v29
	v_mul_f32_e32 v31, 0xbfb8aa3b, v23
	v_cvt_pk_bf16_f32 v27, v27, v28
	v_exp_f32_e32 v31, v31
	s_nop 0
	v_add_f32_e32 v31, 1.0, v31
	v_rcp_f32_e32 v28, v30
	s_nop 0
	v_mul_f32_e32 v22, v22, v28
	v_mul_f32_e32 v18, v22, v18
	v_mul_f32_e32 v29, 0xbfb8aa3b, v24
	v_exp_f32_e32 v29, v29
	v_rcp_f32_e32 v22, v31
	s_nop 0
	v_mul_f32_e32 v22, v23, v22
	v_add_f32_e32 v29, 1.0, v29
	v_mul_f32_e32 v19, v22, v19
	v_mul_f32_e32 v22, 0xbfb8aa3b, v25
	v_exp_f32_e32 v22, v22
	v_cvt_pk_bf16_f32 v28, v18, v19
	v_add_f32_e32 v22, 1.0, v22
	v_rcp_f32_e32 v18, v29
	s_nop 0
	v_mul_f32_e32 v18, v24, v18
	v_mul_f32_e32 v18, v18, v20
	v_mul_f32_e32 v20, 0xbfb8aa3b, v14
	v_exp_f32_e32 v20, v20
	v_rcp_f32_e32 v19, v22
	s_nop 0
	v_mul_f32_e32 v19, v25, v19
	v_mul_f32_e32 v19, v19, v21
	v_cvt_pk_bf16_f32 v29, v18, v19
	v_add_f32_e32 v20, 1.0, v20
	v_add_u32_e32 v18, 0x40a0, v1
	v_mad_i64_i32 v[18:19], s[8:9], v18, s5, v[114:115]
	v_lshl_add_u64 v[18:19], v[18:19], 0, v[116:117]
	global_store_dwordx4 v[18:19], v[26:29], off
	v_mul_f32_e32 v23, 0xbfb8aa3b, v15
	v_exp_f32_e32 v23, v23
	s_nop 0
	v_add_f32_e32 v21, 1.0, v23
	v_rcp_f32_e32 v18, v20
	s_nop 0
	v_mul_f32_e32 v14, v14, v18
	v_mul_f32_e32 v10, v14, v10
	v_mul_f32_e32 v19, 0xbfb8aa3b, v16
	v_exp_f32_e32 v19, v19
	v_rcp_f32_e32 v14, v21
	s_nop 0
	v_mul_f32_e32 v14, v15, v14
	v_add_f32_e32 v18, 1.0, v19
	v_mul_f32_e32 v11, v14, v11
	v_mul_f32_e32 v15, 0xbfb8aa3b, v17
	v_cvt_pk_bf16_f32 v10, v10, v11
	v_exp_f32_e32 v15, v15
	s_nop 0
	v_add_f32_e32 v15, 1.0, v15
	v_rcp_f32_e32 v11, v18
	s_nop 0
	v_mul_f32_e32 v11, v16, v11
	v_mul_f32_e32 v11, v11, v12
	v_mul_f32_e32 v16, 0xbfb8aa3b, v6
	v_exp_f32_e32 v16, v16
	v_rcp_f32_e32 v12, v15
	s_nop 0
	v_mul_f32_e32 v12, v17, v12
	v_add_f32_e32 v14, 1.0, v16
	v_mul_f32_e32 v12, v12, v13
	v_mul_f32_e32 v15, 0xbfb8aa3b, v7
	v_cvt_pk_bf16_f32 v11, v11, v12
	v_exp_f32_e32 v15, v15
	s_nop 0
	v_add_f32_e32 v15, 1.0, v15
	v_rcp_f32_e32 v12, v14
	s_nop 0
	v_mul_f32_e32 v6, v6, v12
	v_mul_f32_e32 v2, v6, v2
	v_mul_f32_e32 v13, 0xbfb8aa3b, v8
	v_exp_f32_e32 v13, v13
	v_rcp_f32_e32 v6, v15
	s_nop 0
	v_mul_f32_e32 v6, v7, v6
	v_add_f32_e32 v13, 1.0, v13
	v_mul_f32_e32 v3, v6, v3
	v_mul_f32_e32 v6, 0xbfb8aa3b, v9
	v_exp_f32_e32 v6, v6
	v_cvt_pk_bf16_f32 v12, v2, v3
	v_add_f32_e32 v6, 1.0, v6
	v_rcp_f32_e32 v2, v13
	s_nop 0
	v_mul_f32_e32 v2, v8, v2
	v_mul_f32_e32 v2, v2, v4
	v_rcp_f32_e32 v3, v6
	s_nop 0
	v_mul_f32_e32 v3, v9, v3
	v_mul_f32_e32 v3, v3, v5
	v_add_u32_e32 v1, 0x40b0, v1
	v_cvt_pk_bf16_f32 v13, v2, v3
	v_mad_i64_i32 v[2:3], s[8:9], v1, s5, v[114:115]
	v_lshl_add_u64 v[2:3], v[2:3], 0, v[116:117]
	global_store_dwordx4 v[2:3], v[10:13], off
	s_waitcnt vmcnt(0)
	s_barrier
	s_waitcnt vmcnt(0)
	s_waitcnt vmcnt(0) lgkmcnt(0)
	s_barrier
	s_mov_b64 s[8:9], exec
	v_readlane_b32 s10, v228, 2
	v_readlane_b32 s11, v228, 3
	s_and_b64 s[10:11], s[8:9], s[10:11]
	s_mov_b64 exec, s[10:11]
	s_cbranch_execz .LBB0_3407
	s_mov_b64 s[10:11], exec
	v_mbcnt_lo_u32_b32 v1, s10, 0
	buffer_wbl2 sc1
	s_waitcnt vmcnt(0)
	v_mbcnt_hi_u32_b32 v1, s11, v1
	v_cmp_eq_u32_e32 vcc, 0, v1
	s_and_b64 s[20:21], exec, vcc
	s_mov_b64 exec, s[20:21]
	s_cbranch_execz .LBB0_3407
	s_bcnt1_i32_b64 s5, s[10:11]
	v_mov_b32_e32 v1, 0
	v_mov_b32_e32 v2, s5
	global_atomic_add v1, v2, s[6:7]

.LBB0_3470:
	v_mul_f32_e32 v150, 0xbfb8aa3b, v126
	v_exp_f32_e32 v151, v150
	v_lshl_add_u32 v150, s52, 8, v1
	v_lshl_or_b32 v152, s53, 7, v131
	v_mul_f32_e32 v158, 0xbfb8aa3b, v127
	v_add_f32_e32 v151, 1.0, v151
	v_exp_f32_e32 v158, v158
	s_nop 0
	v_add_f32_e32 v156, 1.0, v158
	v_rcp_f32_e32 v154, v151
	s_nop 0
	v_mul_f32_e32 v126, v126, v154
	v_mul_f32_e32 v122, v126, v122
	v_mul_f32_e32 v154, 0xbfb8aa3b, v128
	v_exp_f32_e32 v154, v154
	v_rcp_f32_e32 v126, v156
	s_nop 0
	v_mul_f32_e32 v126, v127, v126
	v_add_f32_e32 v151, 1.0, v154
	v_mul_f32_e32 v123, v126, v123
	v_mul_f32_e32 v127, 0xbfb8aa3b, v129
	v_cvt_pk_bf16_f32 v122, v122, v123
	v_exp_f32_e32 v127, v127
	s_nop 0
	v_add_f32_e32 v127, 1.0, v127
	v_rcp_f32_e32 v123, v151
	s_nop 0
	v_mul_f32_e32 v123, v128, v123
	v_mul_f32_e32 v123, v123, v124
	v_mul_f32_e32 v128, 0xbfb8aa3b, v118
	v_exp_f32_e32 v128, v128
	v_rcp_f32_e32 v124, v127
	s_nop 0
	v_mul_f32_e32 v124, v129, v124
	v_add_f32_e32 v126, 1.0, v128
	v_mul_f32_e32 v124, v124, v125
	v_mul_f32_e32 v127, 0xbfb8aa3b, v119
	v_cvt_pk_bf16_f32 v123, v123, v124
	v_exp_f32_e32 v127, v127
	s_nop 0
	v_add_f32_e32 v127, 1.0, v127
	v_rcp_f32_e32 v124, v126
	s_nop 0
	v_mul_f32_e32 v118, v118, v124
	v_mul_f32_e32 v114, v118, v114
	v_mul_f32_e32 v125, 0xbfb8aa3b, v120
	v_exp_f32_e32 v125, v125
	v_rcp_f32_e32 v118, v127
	s_nop 0
	v_mul_f32_e32 v118, v119, v118
	v_add_f32_e32 v125, 1.0, v125
	v_mul_f32_e32 v115, v118, v115
	v_mul_f32_e32 v118, 0xbfb8aa3b, v121
	v_exp_f32_e32 v118, v118
	v_cvt_pk_bf16_f32 v124, v114, v115
	v_add_f32_e32 v118, 1.0, v118
	v_rcp_f32_e32 v114, v125
	s_nop 0
	v_mul_f32_e32 v114, v120, v114
	v_mul_f32_e32 v114, v114, v116
	v_rcp_f32_e32 v115, v118
	s_nop 0
	v_mul_f32_e32 v115, v121, v115
	v_mul_f32_e32 v115, v115, v117
	v_cvt_pk_bf16_f32 v125, v114, v115
	v_mul_f32_e32 v114, 0xbfb8aa3b, v110
	v_exp_f32_e32 v116, v114
	v_ashrrev_i32_e32 v153, 31, v152
	v_mov_b64_e32 v[114:115], s[18:19]
	v_mad_i64_i32 v[118:119], s[52:53], v150, s63, v[114:115]
	v_add_f32_e32 v120, 1.0, v116
	v_lshlrev_b64 v[116:117], 1, v[152:153]
	v_lshl_add_u64 v[118:119], v[118:119], 0, v[116:117]
	global_store_dwordx4 v[118:119], v[122:125], off
	s_nop 1
	v_mul_f32_e32 v122, 0xbfb8aa3b, v111
	v_exp_f32_e32 v122, v122
	s_nop 0
	v_add_f32_e32 v121, 1.0, v122
	v_rcp_f32_e32 v118, v120
	s_nop 0
	v_mul_f32_e32 v110, v110, v118
	v_mul_f32_e32 v106, v110, v106
	v_mul_f32_e32 v119, 0xbfb8aa3b, v112
	v_exp_f32_e32 v119, v119
	v_rcp_f32_e32 v110, v121
	s_nop 0
	v_mul_f32_e32 v110, v111, v110
	v_add_f32_e32 v118, 1.0, v119
	v_mul_f32_e32 v107, v110, v107
	v_mul_f32_e32 v111, 0xbfb8aa3b, v113
	v_cvt_pk_bf16_f32 v106, v106, v107
	v_exp_f32_e32 v111, v111
	s_nop 0
	v_add_f32_e32 v111, 1.0, v111
	v_rcp_f32_e32 v107, v118
	s_nop 0
	v_mul_f32_e32 v107, v112, v107
	v_mul_f32_e32 v107, v107, v108
	v_mul_f32_e32 v112, 0xbfb8aa3b, v102
	v_exp_f32_e32 v112, v112
	v_rcp_f32_e32 v108, v111
	s_nop 0
	v_mul_f32_e32 v108, v113, v108
	v_add_f32_e32 v110, 1.0, v112
	v_mul_f32_e32 v108, v108, v109
	v_mul_f32_e32 v111, 0xbfb8aa3b, v103
	v_cvt_pk_bf16_f32 v107, v107, v108
	v_exp_f32_e32 v111, v111
	s_nop 0
	v_add_f32_e32 v111, 1.0, v111
	v_rcp_f32_e32 v108, v110
	s_nop 0
	v_mul_f32_e32 v102, v102, v108
	v_mul_f32_e32 v98, v102, v98
	v_mul_f32_e32 v109, 0xbfb8aa3b, v104
	v_exp_f32_e32 v109, v109
	v_rcp_f32_e32 v102, v111
	s_nop 0
	v_mul_f32_e32 v102, v103, v102
	v_add_f32_e32 v109, 1.0, v109
	v_mul_f32_e32 v99, v102, v99
	v_mul_f32_e32 v102, 0xbfb8aa3b, v105
	v_exp_f32_e32 v102, v102
	v_cvt_pk_bf16_f32 v108, v98, v99
	v_add_f32_e32 v102, 1.0, v102
	v_rcp_f32_e32 v98, v109
	s_nop 0
	v_mul_f32_e32 v98, v104, v98
	v_mul_f32_e32 v98, v98, v100
	v_mul_f32_e32 v100, 0xbfb8aa3b, v94
	v_exp_f32_e32 v100, v100
	v_rcp_f32_e32 v99, v102
	s_nop 0
	v_mul_f32_e32 v99, v105, v99
	v_mul_f32_e32 v99, v99, v101
	v_cvt_pk_bf16_f32 v109, v98, v99
	v_add_f32_e32 v100, 1.0, v100
	v_or_b32_e32 v98, 16, v150
	v_mad_i64_i32 v[98:99], s[52:53], v98, s63, v[114:115]
	v_lshl_add_u64 v[98:99], v[98:99], 0, v[116:117]
	global_store_dwordx4 v[98:99], v[106:109], off
	v_mul_f32_e32 v103, 0xbfb8aa3b, v95
	v_exp_f32_e32 v103, v103
	s_nop 0
	v_add_f32_e32 v101, 1.0, v103
	v_rcp_f32_e32 v98, v100
	s_nop 0
	v_mul_f32_e32 v94, v94, v98
	v_mul_f32_e32 v90, v94, v90
	v_mul_f32_e32 v99, 0xbfb8aa3b, v96
	v_exp_f32_e32 v99, v99
	v_rcp_f32_e32 v94, v101
	s_nop 0
	v_mul_f32_e32 v94, v95, v94
	v_add_f32_e32 v98, 1.0, v99
	v_mul_f32_e32 v91, v94, v91
	v_mul_f32_e32 v95, 0xbfb8aa3b, v97
	v_cvt_pk_bf16_f32 v90, v90, v91
	v_exp_f32_e32 v95, v95
	s_nop 0
	v_add_f32_e32 v95, 1.0, v95
	v_rcp_f32_e32 v91, v98
	s_nop 0
	v_mul_f32_e32 v91, v96, v91
	v_mul_f32_e32 v91, v91, v92
	v_mul_f32_e32 v96, 0xbfb8aa3b, v86
	v_exp_f32_e32 v96, v96
	v_rcp_f32_e32 v92, v95
	s_nop 0
	v_mul_f32_e32 v92, v97, v92
	v_add_f32_e32 v94, 1.0, v96
	v_mul_f32_e32 v92, v92, v93
	v_mul_f32_e32 v95, 0xbfb8aa3b, v87
	v_cvt_pk_bf16_f32 v91, v91, v92
	v_exp_f32_e32 v95, v95
	s_nop 0
	v_add_f32_e32 v95, 1.0, v95
	v_rcp_f32_e32 v92, v94
	s_nop 0
	v_mul_f32_e32 v86, v86, v92
	v_mul_f32_e32 v82, v86, v82
	v_mul_f32_e32 v93, 0xbfb8aa3b, v88
	v_exp_f32_e32 v93, v93
	v_rcp_f32_e32 v86, v95
	s_nop 0
	v_mul_f32_e32 v86, v87, v86
	v_add_f32_e32 v93, 1.0, v93
	v_mul_f32_e32 v83, v86, v83
	v_mul_f32_e32 v86, 0xbfb8aa3b, v89
	v_exp_f32_e32 v86, v86
	v_cvt_pk_bf16_f32 v92, v82, v83
	v_add_f32_e32 v86, 1.0, v86
	v_rcp_f32_e32 v82, v93
	s_nop 0
	v_mul_f32_e32 v82, v88, v82
	v_mul_f32_e32 v82, v82, v84
	v_mul_f32_e32 v84, 0xbfb8aa3b, v78
	v_exp_f32_e32 v84, v84
	v_rcp_f32_e32 v83, v86
	s_nop 0
	v_mul_f32_e32 v83, v89, v83
	v_mul_f32_e32 v83, v83, v85
	v_cvt_pk_bf16_f32 v93, v82, v83
	v_add_f32_e32 v84, 1.0, v84
	v_or_b32_e32 v82, 32, v150
	v_mad_i64_i32 v[82:83], s[52:53], v82, s63, v[114:115]
	v_lshl_add_u64 v[82:83], v[82:83], 0, v[116:117]
	global_store_dwordx4 v[82:83], v[90:93], off
	v_mul_f32_e32 v87, 0xbfb8aa3b, v79
	v_exp_f32_e32 v87, v87
	s_nop 0
	v_add_f32_e32 v85, 1.0, v87
	v_rcp_f32_e32 v82, v84
	s_nop 0
	v_mul_f32_e32 v78, v78, v82
	v_mul_f32_e32 v74, v78, v74
	v_mul_f32_e32 v83, 0xbfb8aa3b, v80
	v_exp_f32_e32 v83, v83
	v_rcp_f32_e32 v78, v85
	s_nop 0
	v_mul_f32_e32 v78, v79, v78
	v_add_f32_e32 v82, 1.0, v83
	v_mul_f32_e32 v75, v78, v75
	v_mul_f32_e32 v79, 0xbfb8aa3b, v81
	v_cvt_pk_bf16_f32 v74, v74, v75
	v_exp_f32_e32 v79, v79
	s_nop 0
	v_add_f32_e32 v79, 1.0, v79
	v_rcp_f32_e32 v75, v82
	s_nop 0
	v_mul_f32_e32 v75, v80, v75
	v_mul_f32_e32 v75, v75, v76
	v_mul_f32_e32 v80, 0xbfb8aa3b, v70
	v_exp_f32_e32 v80, v80
	v_rcp_f32_e32 v76, v79
	s_nop 0
	v_mul_f32_e32 v76, v81, v76
	v_add_f32_e32 v78, 1.0, v80
	v_mul_f32_e32 v76, v76, v77
	v_mul_f32_e32 v79, 0xbfb8aa3b, v71
	v_cvt_pk_bf16_f32 v75, v75, v76
	v_exp_f32_e32 v79, v79
	s_nop 0
	v_add_f32_e32 v79, 1.0, v79
	v_rcp_f32_e32 v76, v78
	s_nop 0
	v_mul_f32_e32 v70, v70, v76
	v_mul_f32_e32 v66, v70, v66
	v_mul_f32_e32 v77, 0xbfb8aa3b, v72
	v_exp_f32_e32 v77, v77
	v_rcp_f32_e32 v70, v79
	s_nop 0
	v_mul_f32_e32 v70, v71, v70
	v_add_f32_e32 v77, 1.0, v77
	v_mul_f32_e32 v67, v70, v67
	v_mul_f32_e32 v70, 0xbfb8aa3b, v73
	v_exp_f32_e32 v70, v70
	v_cvt_pk_bf16_f32 v76, v66, v67
	v_add_f32_e32 v70, 1.0, v70
	v_rcp_f32_e32 v66, v77
	s_nop 0
	v_mul_f32_e32 v66, v72, v66
	v_mul_f32_e32 v66, v66, v68
	v_rcp_f32_e32 v67, v70
	s_nop 0
	v_mul_f32_e32 v67, v73, v67
	v_mul_f32_e32 v67, v67, v69
	v_cvt_pk_bf16_f32 v77, v66, v67
	v_mul_f32_e32 v66, 0xbfb8aa3b, v62
	v_exp_f32_e32 v68, v66
	v_or_b32_e32 v66, 48, v150
	v_mad_i64_i32 v[66:67], s[52:53], v66, s63, v[114:115]
	v_add_f32_e32 v68, 1.0, v68
	v_lshl_add_u64 v[66:67], v[66:67], 0, v[116:117]
	global_store_dwordx4 v[66:67], v[74:77], off
	v_mul_f32_e32 v72, 0xbfb8aa3b, v63
	v_exp_f32_e32 v72, v72
	s_nop 0
	v_add_f32_e32 v69, 1.0, v72
	v_rcp_f32_e32 v67, v68
	s_nop 0
	v_mul_f32_e32 v62, v62, v67
	v_mul_f32_e32 v58, v62, v58
	v_mul_f32_e32 v68, 0xbfb8aa3b, v64
	v_exp_f32_e32 v68, v68
	v_rcp_f32_e32 v62, v69
	s_nop 0
	v_mul_f32_e32 v62, v63, v62
	v_add_f32_e32 v67, 1.0, v68
	v_mul_f32_e32 v59, v62, v59
	v_mul_f32_e32 v63, 0xbfb8aa3b, v65
	v_cvt_pk_bf16_f32 v58, v58, v59
	v_exp_f32_e32 v63, v63
	s_nop 0
	v_add_f32_e32 v63, 1.0, v63
	v_rcp_f32_e32 v59, v67
	s_nop 0
	v_mul_f32_e32 v59, v64, v59
	v_mul_f32_e32 v59, v59, v60
	v_mul_f32_e32 v64, 0xbfb8aa3b, v54
	v_exp_f32_e32 v64, v64
	v_rcp_f32_e32 v60, v63
	s_nop 0
	v_mul_f32_e32 v60, v65, v60
	v_add_f32_e32 v62, 1.0, v64
	v_mul_f32_e32 v60, v60, v61
	v_mul_f32_e32 v63, 0xbfb8aa3b, v55
	v_cvt_pk_bf16_f32 v59, v59, v60
	v_exp_f32_e32 v63, v63
	s_nop 0
	v_add_f32_e32 v63, 1.0, v63
	v_rcp_f32_e32 v60, v62
	s_nop 0
	v_mul_f32_e32 v54, v54, v60
	v_mul_f32_e32 v50, v54, v50
	v_mul_f32_e32 v61, 0xbfb8aa3b, v56
	v_exp_f32_e32 v61, v61
	v_rcp_f32_e32 v54, v63
	s_nop 0
	v_mul_f32_e32 v54, v55, v54
	v_add_f32_e32 v61, 1.0, v61
	v_mul_f32_e32 v51, v54, v51
	v_mul_f32_e32 v54, 0xbfb8aa3b, v57
	v_exp_f32_e32 v54, v54
	v_cvt_pk_bf16_f32 v60, v50, v51
	v_add_f32_e32 v54, 1.0, v54
	v_rcp_f32_e32 v50, v61
	s_nop 0
	v_mul_f32_e32 v50, v56, v50
	v_mul_f32_e32 v50, v50, v52
	v_mul_f32_e32 v52, 0xbfb8aa3b, v46
	v_exp_f32_e32 v52, v52
	v_rcp_f32_e32 v51, v54
	s_nop 0
	v_mul_f32_e32 v51, v57, v51
	v_mul_f32_e32 v51, v51, v53
	v_add_u32_e32 v66, 0x80, v150
	v_add_f32_e32 v52, 1.0, v52
	v_cvt_pk_bf16_f32 v61, v50, v51
	v_mad_i64_i32 v[50:51], s[52:53], v66, s63, v[114:115]
	v_lshl_add_u64 v[50:51], v[50:51], 0, v[116:117]
	global_store_dwordx4 v[50:51], v[58:61], off
	v_mul_f32_e32 v55, 0xbfb8aa3b, v47
	v_exp_f32_e32 v55, v55
	s_nop 0
	v_add_f32_e32 v53, 1.0, v55
	v_rcp_f32_e32 v50, v52
	s_nop 0
	v_mul_f32_e32 v46, v46, v50
	v_mul_f32_e32 v42, v46, v42
	v_mul_f32_e32 v51, 0xbfb8aa3b, v48
	v_exp_f32_e32 v51, v51
	v_rcp_f32_e32 v46, v53
	s_nop 0
	v_mul_f32_e32 v46, v47, v46
	v_add_f32_e32 v50, 1.0, v51
	v_mul_f32_e32 v43, v46, v43
	v_mul_f32_e32 v47, 0xbfb8aa3b, v49
	v_cvt_pk_bf16_f32 v42, v42, v43
	v_exp_f32_e32 v47, v47
	s_nop 0
	v_add_f32_e32 v47, 1.0, v47
	v_rcp_f32_e32 v43, v50
	s_nop 0
	v_mul_f32_e32 v43, v48, v43
	v_mul_f32_e32 v43, v43, v44
	v_mul_f32_e32 v48, 0xbfb8aa3b, v38
	v_exp_f32_e32 v48, v48
	v_rcp_f32_e32 v44, v47
	s_nop 0
	v_mul_f32_e32 v44, v49, v44
	v_add_f32_e32 v46, 1.0, v48
	v_mul_f32_e32 v44, v44, v45
	v_mul_f32_e32 v47, 0xbfb8aa3b, v39
	v_cvt_pk_bf16_f32 v43, v43, v44
	v_exp_f32_e32 v47, v47
	s_nop 0
	v_add_f32_e32 v47, 1.0, v47
	v_rcp_f32_e32 v44, v46
	s_nop 0
	v_mul_f32_e32 v38, v38, v44
	v_mul_f32_e32 v34, v38, v34
	v_mul_f32_e32 v45, 0xbfb8aa3b, v40
	v_exp_f32_e32 v45, v45
	v_rcp_f32_e32 v38, v47
	s_nop 0
	v_mul_f32_e32 v38, v39, v38
	v_add_f32_e32 v45, 1.0, v45
	v_mul_f32_e32 v35, v38, v35
	v_mul_f32_e32 v38, 0xbfb8aa3b, v41
	v_exp_f32_e32 v38, v38
	v_cvt_pk_bf16_f32 v44, v34, v35
	v_add_f32_e32 v38, 1.0, v38
	v_rcp_f32_e32 v34, v45
	s_nop 0
	v_mul_f32_e32 v34, v40, v34
	v_mul_f32_e32 v34, v34, v36
	v_mul_f32_e32 v36, 0xbfb8aa3b, v30
	v_exp_f32_e32 v36, v36
	v_rcp_f32_e32 v35, v38
	s_nop 0
	v_mul_f32_e32 v35, v41, v35
	v_mul_f32_e32 v35, v35, v37
	v_cvt_pk_bf16_f32 v45, v34, v35
	v_add_f32_e32 v36, 1.0, v36
	v_add_u32_e32 v34, 0x90, v150
	v_mad_i64_i32 v[34:35], s[52:53], v34, s63, v[114:115]
	v_lshl_add_u64 v[34:35], v[34:35], 0, v[116:117]
	global_store_dwordx4 v[34:35], v[42:45], off
	v_mul_f32_e32 v39, 0xbfb8aa3b, v31
	v_exp_f32_e32 v39, v39
	s_nop 0
	v_add_f32_e32 v37, 1.0, v39
	v_rcp_f32_e32 v34, v36
	s_nop 0
	v_mul_f32_e32 v30, v30, v34
	v_mul_f32_e32 v26, v30, v26
	v_mul_f32_e32 v35, 0xbfb8aa3b, v32
	v_exp_f32_e32 v35, v35
	v_rcp_f32_e32 v30, v37
	s_nop 0
	v_mul_f32_e32 v30, v31, v30
	v_add_f32_e32 v34, 1.0, v35
	v_mul_f32_e32 v27, v30, v27
	v_mul_f32_e32 v31, 0xbfb8aa3b, v33
	v_cvt_pk_bf16_f32 v26, v26, v27
	v_exp_f32_e32 v31, v31
	s_nop 0
	v_add_f32_e32 v31, 1.0, v31
	v_rcp_f32_e32 v27, v34
	s_nop 0
	v_mul_f32_e32 v27, v32, v27
	v_mul_f32_e32 v27, v27, v28
	v_mul_f32_e32 v32, 0xbfb8aa3b, v22
	v_exp_f32_e32 v32, v32
	v_rcp_f32_e32 v28, v31
	s_nop 0
	v_mul_f32_e32 v28, v33, v28
	v_add_f32_e32 v30, 1.0, v32
	v_mul_f32_e32 v28, v28, v29
	v_mul_f32_e32 v31, 0xbfb8aa3b, v23
	v_cvt_pk_bf16_f32 v27, v27, v28
	v_exp_f32_e32 v31, v31
	s_nop 0
	v_add_f32_e32 v31, 1.0, v31
	v_rcp_f32_e32 v28, v30
	s_nop 0
	v_mul_f32_e32 v22, v22, v28
	v_mul_f32_e32 v18, v22, v18
	v_mul_f32_e32 v29, 0xbfb8aa3b, v24
	v_exp_f32_e32 v29, v29
	v_rcp_f32_e32 v22, v31
	s_nop 0
	v_mul_f32_e32 v22, v23, v22
	v_add_f32_e32 v29, 1.0, v29
	v_mul_f32_e32 v19, v22, v19
	v_mul_f32_e32 v22, 0xbfb8aa3b, v25
	v_exp_f32_e32 v22, v22
	v_cvt_pk_bf16_f32 v28, v18, v19
	v_add_f32_e32 v22, 1.0, v22
	v_rcp_f32_e32 v18, v29
	s_nop 0
	v_mul_f32_e32 v18, v24, v18
	v_mul_f32_e32 v18, v18, v20
	v_mul_f32_e32 v20, 0xbfb8aa3b, v14
	v_exp_f32_e32 v20, v20
	v_rcp_f32_e32 v19, v22
	s_nop 0
	v_mul_f32_e32 v19, v25, v19
	v_mul_f32_e32 v19, v19, v21
	v_cvt_pk_bf16_f32 v29, v18, v19
	v_add_f32_e32 v20, 1.0, v20
	v_add_u32_e32 v18, 0xa0, v150
	v_mad_i64_i32 v[18:19], s[52:53], v18, s63, v[114:115]
	v_lshl_add_u64 v[18:19], v[18:19], 0, v[116:117]
	global_store_dwordx4 v[18:19], v[26:29], off
	v_mul_f32_e32 v23, 0xbfb8aa3b, v15
	v_exp_f32_e32 v23, v23
	s_nop 0
	v_add_f32_e32 v21, 1.0, v23
	v_rcp_f32_e32 v18, v20
	s_nop 0
	v_mul_f32_e32 v14, v14, v18
	v_mul_f32_e32 v10, v14, v10
	v_mul_f32_e32 v19, 0xbfb8aa3b, v16
	v_exp_f32_e32 v19, v19
	v_rcp_f32_e32 v14, v21
	s_nop 0
	v_mul_f32_e32 v14, v15, v14
	v_add_f32_e32 v18, 1.0, v19
	v_mul_f32_e32 v11, v14, v11
	v_mul_f32_e32 v15, 0xbfb8aa3b, v17
	v_cvt_pk_bf16_f32 v10, v10, v11
	v_exp_f32_e32 v15, v15
	s_nop 0
	v_add_f32_e32 v15, 1.0, v15
	v_rcp_f32_e32 v11, v18
	s_nop 0
	v_mul_f32_e32 v11, v16, v11
	v_mul_f32_e32 v11, v11, v12
	v_mul_f32_e32 v16, 0xbfb8aa3b, v6
	v_exp_f32_e32 v16, v16
	v_rcp_f32_e32 v12, v15
	s_nop 0
	v_mul_f32_e32 v12, v17, v12
	v_add_f32_e32 v14, 1.0, v16
	v_mul_f32_e32 v12, v12, v13
	v_mul_f32_e32 v15, 0xbfb8aa3b, v7
	v_cvt_pk_bf16_f32 v11, v11, v12
	v_exp_f32_e32 v15, v15
	s_nop 0
	v_add_f32_e32 v15, 1.0, v15
	v_rcp_f32_e32 v12, v14
	s_nop 0
	v_mul_f32_e32 v6, v6, v12
	v_mul_f32_e32 v2, v6, v2
	v_mul_f32_e32 v13, 0xbfb8aa3b, v8
	v_exp_f32_e32 v13, v13
	v_rcp_f32_e32 v6, v15
	s_nop 0
	v_mul_f32_e32 v6, v7, v6
	v_add_f32_e32 v13, 1.0, v13
	v_mul_f32_e32 v3, v6, v3
	v_mul_f32_e32 v6, 0xbfb8aa3b, v9
	v_exp_f32_e32 v6, v6
	v_cvt_pk_bf16_f32 v12, v2, v3
	v_add_f32_e32 v6, 1.0, v6
	v_rcp_f32_e32 v2, v13
	s_nop 0
	v_mul_f32_e32 v2, v8, v2
	v_mul_f32_e32 v2, v2, v4
	v_rcp_f32_e32 v3, v6
	s_nop 0
	v_mul_f32_e32 v3, v9, v3
	v_mul_f32_e32 v3, v3, v5
	v_cvt_pk_bf16_f32 v13, v2, v3
	v_add_u32_e32 v2, 0xb0, v150
	v_mad_i64_i32 v[2:3], s[52:53], v2, s63, v[114:115]
	v_lshl_add_u64 v[2:3], v[2:3], 0, v[116:117]
	s_mov_b64 s[52:53], -1
	s_and_b64 vcc, exec, s[48:49]
	global_store_dwordx4 v[2:3], v[10:13], off
	s_cbranch_vccz .LBB0_3459
	s_andn2_b64 vcc, exec, s[6:7]
	s_cbranch_vccnz .LBB0_3458
	s_barrier
	s_branch .LBB0_3458

.LBB0_5338:
	s_or_b32 s6, s14, 1
	s_ashr_i32 s7, s6, 31
	s_lshl_b32 s26, s10, 6
	s_lshl_b32 s27, s11, 6
	s_add_i32 s28, s14, 0x601
	s_lshl_b64 s[6:7], s[6:7], 10
	v_lshrrev_b32_e32 v100, 4, v1
	s_add_u32 s8, s18, s52
	v_or_b32_e32 v14, s26, v100
	s_addc_u32 s9, s19, 0
	v_or_b32_e32 v17, 4, v14
	s_add_u32 s29, s8, 0xc00
	v_subrev_u32_e32 v12, s26, v17
	v_lshl_add_u64 v[104:105], v[6:7], 0, s[52:53]
	s_addc_u32 s30, s9, 0
	v_lshlrev_b32_e32 v98, 10, v100
	v_ashrrev_i32_e32 v13, 31, v12
	v_lshl_add_u64 v[2:3], v[104:105], 0, v[98:99]
	v_mov_b32_e32 v15, s30
	v_cmp_gt_i32_e32 vcc, s44, v14
	v_mov_b32_e32 v16, s29
	v_lshlrev_b64 v[12:13], 10, v[12:13]
	v_and_b32_e32 v50, 15, v138
	v_cndmask_b32_e32 v3, v15, v3, vcc
	v_cndmask_b32_e32 v2, v16, v2, vcc
	v_lshl_add_u64 v[12:13], v[104:105], 0, v[12:13]
	v_cmp_gt_i32_e32 vcc, s44, v17
	v_lshlrev_b32_e32 v98, 4, v50
	v_lshl_add_u64 v[6:7], v[2:3], 0, v[98:99]
	v_cndmask_b32_e32 v13, v15, v13, vcc
	v_cndmask_b32_e32 v12, v16, v12, vcc
	v_lshl_add_u64 v[12:13], v[12:13], 0, v[98:99]
	v_or_b32_e32 v17, 8, v14
	global_load_dwordx4 v[2:5], v[6:7], off
	s_nop 0
	global_load_dwordx4 v[6:9], v[6:7], off offset:512
	s_nop 0
	global_load_dwordx4 v[26:29], v[12:13], off
	global_load_dwordx4 v[30:33], v[12:13], off offset:512
	v_subrev_u32_e32 v12, s26, v17
	v_ashrrev_i32_e32 v13, 31, v12
	v_lshlrev_b64 v[12:13], 10, v[12:13]
	v_lshl_add_u64 v[12:13], v[104:105], 0, v[12:13]
	v_cmp_gt_i32_e32 vcc, s44, v17
	v_or_b32_e32 v14, 12, v14
	v_lshl_add_u64 v[108:109], v[42:43], 0, s[52:53]
	v_cndmask_b32_e32 v13, v15, v13, vcc
	v_cndmask_b32_e32 v12, v16, v12, vcc
	v_lshl_add_u64 v[12:13], v[12:13], 0, v[98:99]
	global_load_dwordx4 v[34:37], v[12:13], off
	global_load_dwordx4 v[38:41], v[12:13], off offset:512
	v_subrev_u32_e32 v12, s26, v14
	v_ashrrev_i32_e32 v13, 31, v12
	v_lshlrev_b64 v[12:13], 10, v[12:13]
	v_lshl_add_u64 v[12:13], v[104:105], 0, v[12:13]
	v_cmp_gt_i32_e32 vcc, s44, v14
	v_and_b32_e32 v43, 64, v166
	v_xor_b32_e32 v42, 1, v166
	v_cndmask_b32_e32 v13, v15, v13, vcc
	v_cndmask_b32_e32 v12, v16, v12, vcc
	v_lshl_add_u64 v[12:13], v[12:13], 0, v[98:99]
	global_load_dwordx4 v[46:49], v[12:13], off
	global_load_dwordx4 v[54:57], v[12:13], off offset:512
	v_add_u32_e32 v43, 64, v43
	v_cmp_lt_i32_e32 vcc, v42, v43
	v_lshl_add_u64 v[10:11], v[10:11], 0, s[56:57]
	v_lshl_add_u64 v[10:11], v[10:11], 0, s[6:7]
	v_cndmask_b32_e32 v42, v166, v42, vcc
	v_lshlrev_b32_e32 v138, 2, v42
	v_xor_b32_e32 v42, 2, v166
	v_cmp_lt_i32_e32 vcc, v42, v43
	v_lshl_add_u64 v[10:11], v[10:11], 0, s[52:53]
	s_mov_b64 s[6:7], 0x4000000
	v_cndmask_b32_e32 v42, v166, v42, vcc
	v_lshlrev_b32_e32 v139, 2, v42
	v_xor_b32_e32 v42, 4, v166
	v_cmp_lt_i32_e32 vcc, v42, v43
	v_lshlrev_b32_e32 v103, 4, v1
	v_lshl_add_u64 v[106:107], v[10:11], 0, s[6:7]
	v_cndmask_b32_e32 v42, v166, v42, vcc
	v_lshlrev_b32_e32 v140, 2, v42
	v_xor_b32_e32 v42, 8, v166
	v_cmp_lt_i32_e32 vcc, v42, v43
	v_and_b32_e32 v10, 0xf0, v103
	v_add_u32_e32 v22, s3, v10
	v_cndmask_b32_e32 v42, v166, v42, vcc
	v_lshlrev_b32_e32 v141, 2, v42
	v_xor_b32_e32 v42, 16, v166
	ds_read_b128 v[10:13], v22
	ds_read_b128 v[14:17], v22 offset:256
	ds_read_b128 v[18:21], v22 offset:512
	ds_read_b128 v[22:25], v22 offset:768
	v_cmp_lt_i32_e32 vcc, v42, v43
	v_mov_b32_e32 v44, v99
	v_mov_b32_e32 v45, v99
	v_cndmask_b32_e32 v42, v166, v42, vcc
	v_lshlrev_b32_e32 v142, 2, v42
	v_xor_b32_e32 v42, 32, v166
	v_cmp_lt_i32_e32 vcc, v42, v43
	s_add_u32 s31, s8, 0x1000
	v_mov_b32_e32 v43, v99
	v_cndmask_b32_e32 v42, v166, v42, vcc
	v_lshlrev_b32_e32 v143, 2, v42
	v_mov_b32_e32 v42, v99
	v_mov_b32_e32 v111, 0xff800000
	v_mov_b32_e32 v110, 0
	v_lshlrev_b32_e32 v98, 4, v50
	v_mov_b64_e32 v[52:53], v[44:45]
	v_mov_b64_e32 v[60:61], v[44:45]
	v_mov_b64_e32 v[64:65], v[44:45]
	s_addc_u32 s42, s9, 0
	s_mov_b32 s48, 0
	s_mov_b32 s43, 32
	v_cmp_eq_u32_e64 s[6:7], 0, v1
	v_cmp_gt_u32_e64 s[8:9], 16, v1
	v_mov_b64_e32 v[50:51], v[42:43]
	v_mov_b64_e32 v[58:59], v[42:43]
	v_mov_b64_e32 v[62:63], v[42:43]
	v_mov_b32_e32 v114, v110
	v_mov_b32_e32 v115, v111
	v_mov_b32_e32 v116, v110
	v_mov_b32_e32 v117, v111
	v_mov_b32_e32 v112, v110
	v_mov_b32_e32 v113, v111
	s_branch .LBB0_5341

.LBB0_5341:
	s_lshr_b32 s10, s48, 2
	s_cmp_lt_u32 s48, 4
	s_cselect_b64 vcc, -1, 0
	s_cmp_eq_u32 s10, 2
	s_cselect_b32 s12, s31, s29
	s_cselect_b32 s13, s42, s30
	s_cmp_eq_u32 s10, 1
	s_cselect_b64 s[10:11], -1, 0
	v_cndmask_b32_e64 v66, v106, v108, s[10:11]
	v_cndmask_b32_e64 v67, v107, v109, s[10:11]
	s_and_b64 s[10:11], s[10:11], exec
	s_cselect_b32 s14, s27, s28
	s_and_b64 s[10:11], vcc, exec
	s_cselect_b32 s14, s26, s14
	s_sub_i32 s10, s43, 32
	s_and_b32 s15, s10, 32
	s_or_b32 s10, s15, s14
	v_add_u32_e32 v80, s10, v100
	v_add_u32_e32 v144, 16, v80
	v_cndmask_b32_e32 v78, v66, v104, vcc
	v_subrev_u32_e32 v66, s14, v144
	v_cndmask_b32_e32 v79, v67, v105, vcc
	v_ashrrev_i32_e32 v67, 31, v66
	v_lshlrev_b64 v[66:67], 10, v[66:67]
	v_lshl_add_u64 v[66:67], v[78:79], 0, v[66:67]
	v_mov_b32_e32 v82, s13
	v_cmp_gt_i32_e64 s[10:11], s44, v144
	v_mov_b32_e32 v83, s12
	v_add_u32_e32 v147, 20, v80
	v_cndmask_b32_e64 v67, v82, v67, s[10:11]
	v_cndmask_b32_e64 v66, v83, v66, s[10:11]
	v_lshl_add_u64 v[66:67], v[66:67], 0, v[98:99]
	v_add_u32_e32 v146, 24, v80
	v_add_u32_e32 v145, 28, v80
	global_load_dwordx4 v[94:97], v[66:67], off
	global_load_dwordx4 v[74:77], v[66:67], off offset:512
	v_subrev_u32_e32 v66, s14, v147
	v_subrev_u32_e32 v70, s14, v146
	v_subrev_u32_e32 v80, s14, v145
	v_ashrrev_i32_e32 v67, 31, v66
	v_ashrrev_i32_e32 v71, 31, v70
	v_ashrrev_i32_e32 v81, 31, v80
	v_lshlrev_b64 v[66:67], 10, v[66:67]
	v_lshlrev_b64 v[70:71], 10, v[70:71]
	v_lshlrev_b64 v[80:81], 10, v[80:81]
	v_lshl_add_u64 v[66:67], v[78:79], 0, v[66:67]
	v_lshl_add_u64 v[70:71], v[78:79], 0, v[70:71]
	v_lshl_add_u64 v[78:79], v[78:79], 0, v[80:81]
	s_waitcnt vmcnt(0) lgkmcnt(0)
	v_mul_f32_e32 v80, v11, v3
	v_fmac_f32_e32 v80, v10, v2
	v_fmac_f32_e32 v80, v12, v4
	v_fmac_f32_e32 v80, v13, v5
	ds_bpermute_b32 v81, v138, v80
	v_cmp_gt_i32_e64 s[10:11], s44, v147
	v_mul_f32_e32 v148, v11, v27
	v_fmac_f32_e32 v148, v10, v26
	v_cndmask_b32_e64 v67, v82, v67, s[10:11]
	s_waitcnt lgkmcnt(0)
	v_add_f32_e32 v80, v80, v81
	v_cndmask_b32_e64 v66, v83, v66, s[10:11]
	v_cmp_gt_i32_e64 s[10:11], s44, v146
	ds_bpermute_b32 v81, v139, v80
	v_mul_f32_e32 v125, v23, v3
	v_cndmask_b32_e64 v71, v82, v71, s[10:11]
	v_cndmask_b32_e64 v70, v83, v70, s[10:11]
	v_cmp_gt_i32_e64 s[10:11], s44, v145
	s_waitcnt lgkmcnt(0)
	v_add_f32_e32 v80, v80, v81
	ds_bpermute_b32 v81, v140, v80
	v_cndmask_b32_e64 v79, v82, v79, s[10:11]
	v_mul_f32_e32 v82, v15, v3
	v_fmac_f32_e32 v82, v14, v2
	v_fmac_f32_e32 v82, v16, v4
	v_fmac_f32_e32 v82, v17, v5
	v_cndmask_b32_e64 v78, v83, v78, s[10:11]
	ds_bpermute_b32 v83, v138, v82
	s_and_b32 s10, s48, 12
	s_waitcnt lgkmcnt(1)
	v_add_f32_e32 v118, v80, v81
	s_cmp_eq_u32 s10, 4
	ds_bpermute_b32 v119, v141, v118
	s_waitcnt lgkmcnt(1)
	v_add_f32_e32 v120, v82, v83
	ds_bpermute_b32 v121, v139, v120
	s_cselect_b32 s12, s27, s28
	s_and_b64 s[10:11], vcc, exec
	s_cselect_b32 s10, s26, s12
	s_or_b32 s10, s10, s15
	v_add_u32_e32 v156, s10, v100
	v_sub_u32_e32 v84, 0x800, v156
	s_waitcnt lgkmcnt(1)
	v_add_f32_e32 v118, v118, v119
	s_waitcnt lgkmcnt(0)
	v_add_f32_e32 v119, v120, v121
	v_cvt_f32_u32_e32 v124, v84
	ds_bpermute_b32 v120, v140, v119
	v_cmp_gt_i32_e32 vcc, s2, v156
	v_fmac_f32_e32 v125, v22, v2
	v_fma_f32 v118, -v127, v124, v118
	v_cndmask_b32_e32 v169, v135, v118, vcc
	s_waitcnt lgkmcnt(0)
	v_add_f32_e32 v120, v119, v120
	v_pk_mul_f32 v[118:119], v[12:13], v[28:29]
	v_fmac_f32_e32 v125, v24, v4
	v_add_f32_e32 v118, v118, v148
	v_add_f32_e32 v118, v119, v118
	ds_bpermute_b32 v119, v138, v118
	v_fmac_f32_e32 v125, v25, v5
	ds_bpermute_b32 v148, v138, v125
	v_mul_f32_e32 v150, v15, v27
	v_fmac_f32_e32 v150, v14, v26
	s_waitcnt lgkmcnt(1)
	v_add_f32_e32 v118, v118, v119
	ds_bpermute_b32 v119, v139, v118
	v_fmac_f32_e32 v150, v16, v28
	s_waitcnt lgkmcnt(1)
	v_add_f32_e32 v125, v125, v148
	v_fmac_f32_e32 v150, v17, v29
	ds_bpermute_b32 v148, v139, v125
	s_waitcnt lgkmcnt(1)
	v_add_f32_e32 v118, v118, v119
	ds_bpermute_b32 v119, v140, v118
	ds_bpermute_b32 v151, v138, v150
	s_movk_i32 s10, 0x7fd
	s_waitcnt lgkmcnt(2)
	v_add_f32_e32 v148, v125, v148
	v_sub_u32_e32 v125, 0x7fc, v156
	s_waitcnt lgkmcnt(1)
	v_add_f32_e32 v118, v118, v119
	ds_bpermute_b32 v119, v141, v118
	v_cvt_f32_u32_e32 v125, v125
	v_cmp_gt_i32_e64 s[10:11], s10, v156
	v_mul_f32_e32 v154, v11, v35
	v_fmac_f32_e32 v154, v10, v34
	s_waitcnt lgkmcnt(0)
	v_add_f32_e32 v118, v118, v119
	v_add_f32_e32 v119, v150, v151
	ds_bpermute_b32 v150, v139, v119
	v_mul_f32_e32 v151, v19, v27
	v_fma_f32 v118, -v127, v125, v118
	v_fmac_f32_e32 v151, v18, v26
	v_fmac_f32_e32 v151, v20, v28
	v_cndmask_b32_e64 v172, v135, v118, s[10:11]
	s_waitcnt lgkmcnt(0)
	v_add_f32_e32 v118, v119, v150
	v_fmac_f32_e32 v151, v21, v29
	ds_bpermute_b32 v119, v140, v118
	ds_bpermute_b32 v152, v138, v151
	v_lshl_add_u64 v[66:67], v[66:67], 0, v[98:99]
	v_lshl_add_u64 v[70:71], v[70:71], 0, v[98:99]
	v_lshl_add_u64 v[78:79], v[78:79], 0, v[98:99]
	s_waitcnt lgkmcnt(1)
	v_add_f32_e32 v164, v118, v119
	v_pk_mul_f32 v[118:119], v[12:13], v[36:37]
	s_waitcnt lgkmcnt(0)
	v_add_f32_e32 v150, v151, v152
	v_mul_f32_e32 v152, v23, v27
	v_add_f32_e32 v118, v118, v154
	v_fmac_f32_e32 v152, v22, v26
	v_add_f32_e32 v118, v119, v118
	v_fmac_f32_e32 v152, v24, v28
	ds_bpermute_b32 v119, v138, v118
	v_fmac_f32_e32 v152, v25, v29
	ds_bpermute_b32 v153, v138, v152
	ds_bpermute_b32 v151, v139, v150
	global_load_dwordx4 v[90:93], v[66:67], off
	s_nop 0
	global_load_dwordx4 v[66:69], v[66:67], off offset:512
	s_waitcnt lgkmcnt(0)
	v_add_f32_e32 v118, v118, v119
	ds_bpermute_b32 v119, v139, v118
	v_add_f32_e32 v152, v152, v153
	ds_bpermute_b32 v153, v139, v152
	global_load_dwordx4 v[86:89], v[70:71], off
	s_nop 0
	global_load_dwordx4 v[70:73], v[70:71], off offset:512
	s_nop 0
	global_load_dwordx4 v[82:85], v[78:79], off
	s_nop 0
	global_load_dwordx4 v[78:81], v[78:79], off offset:512
	v_mul_f32_e32 v154, v15, v35
	s_waitcnt lgkmcnt(0)
	v_add_f32_e32 v118, v118, v119
	v_fmac_f32_e32 v154, v14, v34
	ds_bpermute_b32 v119, v140, v118
	v_fmac_f32_e32 v154, v16, v36
	v_add_f32_e32 v150, v150, v151
	v_add_f32_e32 v152, v152, v153
	v_fmac_f32_e32 v154, v17, v37
	ds_bpermute_b32 v151, v140, v150
	ds_bpermute_b32 v153, v140, v152
	ds_bpermute_b32 v155, v138, v154
	s_waitcnt lgkmcnt(0)
	v_add_f32_e32 v118, v118, v119
	ds_bpermute_b32 v119, v141, v118
	v_add_f32_e32 v158, v150, v151
	v_add_f32_e32 v150, v152, v153
	v_sub_u32_e32 v152, 0x7f8, v156
	v_add_f32_e32 v154, v154, v155
	v_cvt_f32_u32_e32 v152, v152
	ds_bpermute_b32 v155, v139, v154
	v_or_b32_e32 v153, 8, v156
	s_waitcnt lgkmcnt(0)
	v_add_f32_e32 v118, v118, v119
	v_fma_f32 v118, -v127, v152, v118
	v_cmp_gt_i32_e64 s[12:13], s2, v153
	v_mul_f32_e32 v153, v19, v35
	v_fmac_f32_e32 v153, v18, v34
	v_cndmask_b32_e64 v173, v135, v118, s[12:13]
	v_add_f32_e32 v118, v154, v155
	v_mul_f32_e32 v155, v23, v35
	v_fmac_f32_e32 v155, v22, v34
	v_fmac_f32_e32 v153, v20, v36
	v_fmac_f32_e32 v155, v24, v36
	v_fmac_f32_e32 v153, v21, v37
	v_fmac_f32_e32 v155, v25, v37
	ds_bpermute_b32 v154, v138, v153
	ds_bpermute_b32 v160, v138, v155
	ds_bpermute_b32 v119, v140, v118
	s_movk_i32 s14, 0x7f5
	v_cmp_gt_i32_e64 s[14:15], s14, v156
	s_waitcnt lgkmcnt(0)
	v_add_f32_e32 v153, v153, v154
	v_add_f32_e32 v160, v155, v160
	v_pk_mul_f32 v[154:155], v[10:11], v[46:47]
	v_add_f32_e32 v167, v118, v119
	v_pk_mul_f32 v[118:119], v[12:13], v[48:49]
	v_add_f32_e32 v154, v154, v155
	v_add_f32_e32 v118, v118, v154
	ds_bpermute_b32 v161, v139, v153
	ds_bpermute_b32 v162, v139, v160
	v_add_f32_e32 v118, v119, v118
	ds_bpermute_b32 v119, v138, v118
	v_mul_f32_e32 v122, v19, v3
	s_waitcnt lgkmcnt(0)
	v_add_f32_e32 v153, v153, v161
	v_add_f32_e32 v155, v160, v162
	ds_bpermute_b32 v154, v140, v153
	ds_bpermute_b32 v162, v140, v155
	v_add_f32_e32 v118, v118, v119
	ds_bpermute_b32 v119, v139, v118
	v_fmac_f32_e32 v122, v18, v2
	s_waitcnt lgkmcnt(0)
	v_add_f32_e32 v160, v153, v154
	v_add_f32_e32 v153, v155, v162
	v_mul_f32_e32 v162, v15, v47
	v_add_f32_e32 v118, v118, v119
	v_fmac_f32_e32 v162, v14, v46
	ds_bpermute_b32 v119, v140, v118
	v_fmac_f32_e32 v162, v16, v48
	v_fmac_f32_e32 v162, v17, v49
	ds_bpermute_b32 v163, v138, v162
	v_sub_u32_e32 v155, 0x7f4, v156
	s_waitcnt lgkmcnt(0)
	v_add_f32_e32 v118, v118, v119
	ds_bpermute_b32 v119, v141, v118
	v_cvt_f32_u32_e32 v155, v155
	v_add_f32_e32 v162, v162, v163
	ds_bpermute_b32 v163, v139, v162
	v_mul_f32_e32 v156, v19, v47
	s_waitcnt lgkmcnt(0)
	v_add_f32_e32 v118, v118, v119
	v_fma_f32 v118, -v127, v155, v118
	v_cndmask_b32_e64 v174, v135, v118, s[14:15]
	v_add_f32_e32 v118, v162, v163
	v_mul_f32_e32 v163, v23, v47
	v_fmac_f32_e32 v156, v18, v46
	v_fmac_f32_e32 v163, v22, v46
	v_fmac_f32_e32 v122, v20, v4
	v_fmac_f32_e32 v156, v20, v48
	v_fmac_f32_e32 v163, v24, v48
	v_fmac_f32_e32 v122, v21, v5
	v_fmac_f32_e32 v156, v21, v49
	v_fmac_f32_e32 v163, v25, v49
	ds_bpermute_b32 v123, v138, v122
	ds_bpermute_b32 v119, v140, v118
	ds_bpermute_b32 v162, v138, v156
	ds_bpermute_b32 v171, v138, v163
	v_max3_f32 v157, v169, s33, v172
	s_waitcnt lgkmcnt(0)
	v_add_f32_e32 v122, v122, v123
	v_add_f32_e32 v170, v118, v119
	v_add_f32_e32 v118, v156, v162
	v_add_f32_e32 v156, v163, v171
	ds_bpermute_b32 v123, v139, v122
	ds_bpermute_b32 v119, v139, v118
	ds_bpermute_b32 v162, v139, v156
	v_max3_f32 v157, v157, v173, v174
	ds_bpermute_b32 v163, v142, v157
	s_waitcnt lgkmcnt(0)
	v_add_f32_e32 v122, v122, v123
	v_add_f32_e32 v118, v118, v119
	v_add_f32_e32 v156, v156, v162
	ds_bpermute_b32 v123, v140, v122
	ds_bpermute_b32 v149, v140, v148
	ds_bpermute_b32 v119, v140, v118
	ds_bpermute_b32 v175, v140, v156
	v_max_f32_e32 v162, v163, v163
	v_max_f32_e32 v176, v157, v162
	ds_bpermute_b32 v177, v143, v176
	s_waitcnt lgkmcnt(0)
	v_add_f32_e32 v122, v122, v123
	v_add_f32_e32 v148, v148, v149
	v_add_f32_e32 v162, v118, v119
	v_add_f32_e32 v156, v156, v175
	ds_bpermute_b32 v121, v141, v120
	ds_bpermute_b32 v123, v141, v122
	ds_bpermute_b32 v149, v141, v148
	ds_bpermute_b32 v165, v141, v164
	ds_bpermute_b32 v159, v141, v158
	ds_bpermute_b32 v151, v141, v150
	ds_bpermute_b32 v168, v141, v167
	ds_bpermute_b32 v161, v141, v160
	ds_bpermute_b32 v154, v141, v153
	ds_bpermute_b32 v171, v141, v170
	ds_bpermute_b32 v163, v141, v162
	ds_bpermute_b32 v157, v141, v156
	v_max_f32_e32 v118, v177, v177
	v_max_f32_e32 v175, v176, v118
	v_cmp_neq_f32_e64 s[16:17], s33, v175
	v_mov_b64_e32 v[118:119], v[112:113]
	s_and_saveexec_b64 s[22:23], s[16:17]
	s_cbranch_execz .LBB0_5343
	v_max_f32_e32 v118, v175, v175
	v_max_f32_e32 v119, v113, v113
	v_max_f32_e32 v119, v119, v118
	v_sub_f32_e32 v118, v169, v119
	v_mul_f32_e32 v118, 0x3fb8aa3b, v118
	v_exp_f32_e32 v118, v118
	v_sub_f32_e32 v113, v113, v119
	v_mul_f32_e32 v113, 0x3fb8aa3b, v113
	v_add_f32_e32 v169, 0, v118
	v_pk_fma_f32 v[176:177], v[8:9], v[118:119], 0 op_sel_hi:[1,0,0]
	v_pk_fma_f32 v[178:179], v[6:7], v[118:119], 0 op_sel_hi:[1,0,0]
	v_sub_f32_e32 v118, v172, v119
	v_mul_f32_e32 v118, 0x3fb8aa3b, v118
	v_exp_f32_e32 v118, v118
	s_nop 0
	v_add_f32_e32 v169, v118, v169
	v_pk_fma_f32 v[176:177], v[32:33], v[118:119], v[176:177] op_sel_hi:[1,0,1]
	v_pk_fma_f32 v[178:179], v[30:31], v[118:119], v[178:179] op_sel_hi:[1,0,1]
	v_sub_f32_e32 v118, v173, v119
	v_mul_f32_e32 v118, 0x3fb8aa3b, v118
	v_exp_f32_e32 v118, v118
	s_nop 0
	v_add_f32_e32 v169, v118, v169
	v_pk_fma_f32 v[172:173], v[38:39], v[118:119], v[178:179] op_sel_hi:[1,0,1]
	v_pk_fma_f32 v[176:177], v[40:41], v[118:119], v[176:177] op_sel_hi:[1,0,1]
	v_sub_f32_e32 v118, v174, v119
	v_mul_f32_e32 v118, 0x3fb8aa3b, v118
	v_exp_f32_e32 v118, v118
	s_nop 0
	v_add_f32_e32 v169, v118, v169
	v_pk_fma_f32 v[174:175], v[56:57], v[118:119], v[176:177] op_sel_hi:[1,0,1]
	v_exp_f32_e32 v176, v113
	ds_bpermute_b32 v113, v142, v169
	v_pk_fma_f32 v[172:173], v[54:55], v[118:119], v[172:173] op_sel_hi:[1,0,1]
	ds_bpermute_b32 v178, v142, v174
	ds_bpermute_b32 v179, v142, v175
	s_waitcnt lgkmcnt(0)
	v_add_f32_e32 v113, v169, v113
	ds_bpermute_b32 v118, v143, v113
	v_pk_add_f32 v[174:175], v[174:175], v[178:179]
	ds_bpermute_b32 v178, v143, v174
	ds_bpermute_b32 v179, v143, v175
	s_waitcnt lgkmcnt(0)
	v_add_f32_e32 v118, v113, v118
	v_fmac_f32_e32 v118, v112, v176
	ds_bpermute_b32 v112, v142, v172
	ds_bpermute_b32 v113, v142, v173
	s_waitcnt lgkmcnt(0)
	v_pk_add_f32 v[112:113], v[172:173], v[112:113]
	ds_bpermute_b32 v172, v143, v112
	ds_bpermute_b32 v173, v143, v113
	s_waitcnt lgkmcnt(0)
	v_pk_add_f32 v[112:113], v[112:113], v[172:173]
	v_pk_add_f32 v[172:173], v[174:175], v[178:179]
	v_pk_fma_f32 v[62:63], v[62:63], v[176:177], v[112:113] op_sel_hi:[1,0,1]
	v_pk_fma_f32 v[64:65], v[64:65], v[176:177], v[172:173] op_sel_hi:[1,0,1]
	v_mov_b32_e32 v112, v118
	v_mov_b32_e32 v113, v119

.LBB0_5349:
	s_or_b64 exec, exec, s[10:11]
	s_add_i32 s49, s48, 2
	s_cmp_gt_u32 s48, 9
	s_cselect_b64 s[22:23], -1, 0
	s_and_b64 vcc, exec, s[22:23]
	s_cbranch_vccnz .LBB0_5351
	s_lshr_b32 s10, s49, 2
	s_cmp_eq_u32 s10, 2
	s_cselect_b32 s12, s31, s29
	s_cselect_b32 s13, s42, s30
	s_cmp_eq_u32 s10, 1
	s_cselect_b64 vcc, -1, 0
	s_and_b64 s[10:11], vcc, exec
	s_cselect_b32 s14, s27, s28
	s_cmp_eq_u32 s48, 0
	v_cndmask_b32_e32 v2, v106, v108, vcc
	v_cndmask_b32_e32 v3, v107, v109, vcc
	s_cselect_b64 vcc, -1, 0
	s_and_b64 s[10:11], vcc, exec
	s_cselect_b32 s10, s26, s14
	s_and_b32 s11, s43, 32
	s_or_b32 s11, s10, s11
	v_add_u32_e32 v54, s11, v100
	v_subrev_u32_e32 v48, s10, v54
	v_ashrrev_i32_e32 v49, 31, v48
	v_add_u32_e32 v26, 4, v48
	v_or_b32_e32 v36, 8, v54
	v_cndmask_b32_e32 v47, v3, v105, vcc
	v_cndmask_b32_e32 v46, v2, v104, vcc
	v_lshlrev_b64 v[2:3], 10, v[48:49]
	v_ashrrev_i32_e32 v27, 31, v26
	v_subrev_u32_e32 v34, s10, v36
	v_lshl_add_u64 v[2:3], v[46:47], 0, v[2:3]
	v_mov_b32_e32 v55, s13
	v_cmp_gt_i32_e32 vcc, s44, v54
	v_mov_b32_e32 v56, s12
	v_lshlrev_b64 v[26:27], 10, v[26:27]
	s_movk_i32 s11, 0x7fc
	v_ashrrev_i32_e32 v35, 31, v34
	v_add_u32_e32 v48, 12, v48
	v_cndmask_b32_e32 v3, v55, v3, vcc
	v_cndmask_b32_e32 v2, v56, v2, vcc
	v_lshl_add_u64 v[26:27], v[46:47], 0, v[26:27]
	v_cmp_gt_i32_e32 vcc, s11, v54
	v_lshlrev_b64 v[34:35], 10, v[34:35]
	v_ashrrev_i32_e32 v49, 31, v48
	v_cndmask_b32_e32 v27, v55, v27, vcc
	v_cndmask_b32_e32 v26, v56, v26, vcc
	v_lshl_add_u64 v[34:35], v[46:47], 0, v[34:35]
	v_cmp_gt_i32_e32 vcc, s44, v36
	v_lshlrev_b64 v[48:49], 10, v[48:49]
	s_movk_i32 s10, 0x7f4
	v_cndmask_b32_e32 v35, v55, v35, vcc
	v_cndmask_b32_e32 v34, v56, v34, vcc
	v_lshl_add_u64 v[46:47], v[46:47], 0, v[48:49]
	v_cmp_gt_i32_e32 vcc, s10, v54
	v_lshl_add_u64 v[6:7], v[2:3], 0, v[98:99]
	v_lshl_add_u64 v[30:31], v[26:27], 0, v[98:99]
	v_cndmask_b32_e32 v47, v55, v47, vcc
	v_cndmask_b32_e32 v46, v56, v46, vcc
	v_lshl_add_u64 v[38:39], v[34:35], 0, v[98:99]
	v_lshl_add_u64 v[54:55], v[46:47], 0, v[98:99]
	global_load_dwordx4 v[2:5], v[6:7], off
	s_nop 0
	global_load_dwordx4 v[6:9], v[6:7], off offset:512
	s_nop 0
	global_load_dwordx4 v[26:29], v[30:31], off
	s_nop 0
	global_load_dwordx4 v[30:33], v[30:31], off offset:512
	s_nop 0
	global_load_dwordx4 v[34:37], v[38:39], off
	s_nop 0
	global_load_dwordx4 v[38:41], v[38:39], off offset:512
	s_nop 0
	global_load_dwordx4 v[46:49], v[54:55], off
	s_nop 0
	global_load_dwordx4 v[54:57], v[54:55], off offset:512

.LBB0_5756:
	v_mul_f32_e32 v130, 0xbfb8aa3b, v126
	v_exp_f32_e32 v130, v130
	v_mul_f32_e32 v138, 0xbfb8aa3b, v127
	v_exp_f32_e32 v138, v138
	s_lshl_b32 s5, s82, 7
	v_add_f32_e32 v133, 1.0, v130
	s_or_b32 s5, s35, s5
	v_or_b32_e32 v130, s5, v142
	v_add_u32_e32 v132, 0x4000, v1
	v_add_f32_e32 v136, 1.0, v138
	v_rcp_f32_e32 v134, v133
	s_nop 0
	v_mul_f32_e32 v126, v126, v134
	v_mul_f32_e32 v122, v126, v122
	v_mul_f32_e32 v134, 0xbfb8aa3b, v128
	v_exp_f32_e32 v134, v134
	v_rcp_f32_e32 v126, v136
	s_nop 0
	v_mul_f32_e32 v126, v127, v126
	v_add_f32_e32 v133, 1.0, v134
	v_mul_f32_e32 v123, v126, v123
	v_mul_f32_e32 v127, 0xbfb8aa3b, v129
	v_cvt_pk_bf16_f32 v122, v122, v123
	v_exp_f32_e32 v127, v127
	s_nop 0
	v_add_f32_e32 v127, 1.0, v127
	v_rcp_f32_e32 v123, v133
	s_nop 0
	v_mul_f32_e32 v123, v128, v123
	v_mul_f32_e32 v123, v123, v124
	v_mul_f32_e32 v128, 0xbfb8aa3b, v118
	v_exp_f32_e32 v128, v128
	v_rcp_f32_e32 v124, v127
	s_nop 0
	v_mul_f32_e32 v124, v129, v124
	v_add_f32_e32 v126, 1.0, v128
	v_mul_f32_e32 v124, v124, v125
	v_mul_f32_e32 v127, 0xbfb8aa3b, v119
	v_cvt_pk_bf16_f32 v123, v123, v124
	v_exp_f32_e32 v127, v127
	s_nop 0
	v_add_f32_e32 v127, 1.0, v127
	v_rcp_f32_e32 v124, v126
	s_nop 0
	v_mul_f32_e32 v118, v118, v124
	v_mul_f32_e32 v114, v118, v114
	v_mul_f32_e32 v125, 0xbfb8aa3b, v120
	v_exp_f32_e32 v125, v125
	v_rcp_f32_e32 v118, v127
	s_nop 0
	v_mul_f32_e32 v118, v119, v118
	v_add_f32_e32 v125, 1.0, v125
	v_mul_f32_e32 v115, v118, v115
	v_mul_f32_e32 v118, 0xbfb8aa3b, v121
	v_exp_f32_e32 v118, v118
	v_cvt_pk_bf16_f32 v124, v114, v115
	v_add_f32_e32 v118, 1.0, v118
	v_rcp_f32_e32 v114, v125
	s_nop 0
	v_mul_f32_e32 v114, v120, v114
	v_mul_f32_e32 v114, v114, v116
	v_rcp_f32_e32 v115, v118
	s_nop 0
	v_mul_f32_e32 v115, v121, v115
	v_mul_f32_e32 v115, v115, v117
	v_cvt_pk_bf16_f32 v125, v114, v115
	v_mul_f32_e32 v114, 0xbfb8aa3b, v110
	v_exp_f32_e32 v116, v114
	v_ashrrev_i32_e32 v131, 31, v130
	s_movk_i32 s5, 0x1600
	v_mov_b64_e32 v[114:115], s[18:19]
	v_add_f32_e32 v120, 1.0, v116
	v_mad_i64_i32 v[118:119], s[8:9], v132, s5, v[114:115]
	v_lshlrev_b64 v[116:117], 1, v[130:131]
	v_lshl_add_u64 v[118:119], v[118:119], 0, v[116:117]
	global_store_dwordx4 v[118:119], v[122:125], off
	s_nop 1
	v_mul_f32_e32 v122, 0xbfb8aa3b, v111
	v_exp_f32_e32 v122, v122
	s_nop 0
	v_add_f32_e32 v121, 1.0, v122
	v_rcp_f32_e32 v118, v120
	s_nop 0
	v_mul_f32_e32 v110, v110, v118
	v_mul_f32_e32 v106, v110, v106
	v_mul_f32_e32 v119, 0xbfb8aa3b, v112
	v_exp_f32_e32 v119, v119
	v_rcp_f32_e32 v110, v121
	s_nop 0
	v_mul_f32_e32 v110, v111, v110
	v_add_f32_e32 v118, 1.0, v119
	v_mul_f32_e32 v107, v110, v107
	v_mul_f32_e32 v111, 0xbfb8aa3b, v113
	v_cvt_pk_bf16_f32 v106, v106, v107
	v_exp_f32_e32 v111, v111
	s_nop 0
	v_add_f32_e32 v111, 1.0, v111
	v_rcp_f32_e32 v107, v118
	s_nop 0
	v_mul_f32_e32 v107, v112, v107
	v_mul_f32_e32 v107, v107, v108
	v_mul_f32_e32 v112, 0xbfb8aa3b, v102
	v_exp_f32_e32 v112, v112
	v_rcp_f32_e32 v108, v111
	s_nop 0
	v_mul_f32_e32 v108, v113, v108
	v_add_f32_e32 v110, 1.0, v112
	v_mul_f32_e32 v108, v108, v109
	v_mul_f32_e32 v111, 0xbfb8aa3b, v103
	v_cvt_pk_bf16_f32 v107, v107, v108
	v_exp_f32_e32 v111, v111
	s_nop 0
	v_add_f32_e32 v111, 1.0, v111
	v_rcp_f32_e32 v108, v110
	s_nop 0
	v_mul_f32_e32 v102, v102, v108
	v_mul_f32_e32 v98, v102, v98
	v_mul_f32_e32 v109, 0xbfb8aa3b, v104
	v_exp_f32_e32 v109, v109
	v_rcp_f32_e32 v102, v111
	s_nop 0
	v_mul_f32_e32 v102, v103, v102
	v_add_f32_e32 v109, 1.0, v109
	v_mul_f32_e32 v99, v102, v99
	v_mul_f32_e32 v102, 0xbfb8aa3b, v105
	v_exp_f32_e32 v102, v102
	v_cvt_pk_bf16_f32 v108, v98, v99
	v_add_f32_e32 v102, 1.0, v102
	v_rcp_f32_e32 v98, v109
	s_nop 0
	v_mul_f32_e32 v98, v104, v98
	v_mul_f32_e32 v98, v98, v100
	v_mul_f32_e32 v100, 0xbfb8aa3b, v94
	v_exp_f32_e32 v100, v100
	v_rcp_f32_e32 v99, v102
	s_nop 0
	v_mul_f32_e32 v99, v105, v99
	v_mul_f32_e32 v99, v99, v101
	v_cvt_pk_bf16_f32 v109, v98, v99
	v_add_f32_e32 v100, 1.0, v100
	v_add_u32_e32 v98, 0x4010, v1
	v_mad_i64_i32 v[98:99], s[8:9], v98, s5, v[114:115]
	v_lshl_add_u64 v[98:99], v[98:99], 0, v[116:117]
	global_store_dwordx4 v[98:99], v[106:109], off
	v_mul_f32_e32 v103, 0xbfb8aa3b, v95
	v_exp_f32_e32 v103, v103
	s_nop 0
	v_add_f32_e32 v101, 1.0, v103
	v_rcp_f32_e32 v98, v100
	s_nop 0
	v_mul_f32_e32 v94, v94, v98
	v_mul_f32_e32 v90, v94, v90
	v_mul_f32_e32 v99, 0xbfb8aa3b, v96
	v_exp_f32_e32 v99, v99
	v_rcp_f32_e32 v94, v101
	s_nop 0
	v_mul_f32_e32 v94, v95, v94
	v_add_f32_e32 v98, 1.0, v99
	v_mul_f32_e32 v91, v94, v91
	v_mul_f32_e32 v95, 0xbfb8aa3b, v97
	v_cvt_pk_bf16_f32 v90, v90, v91
	v_exp_f32_e32 v95, v95
	s_nop 0
	v_add_f32_e32 v95, 1.0, v95
	v_rcp_f32_e32 v91, v98
	s_nop 0
	v_mul_f32_e32 v91, v96, v91
	v_mul_f32_e32 v91, v91, v92
	v_mul_f32_e32 v96, 0xbfb8aa3b, v86
	v_exp_f32_e32 v96, v96
	v_rcp_f32_e32 v92, v95
	s_nop 0
	v_mul_f32_e32 v92, v97, v92
	v_add_f32_e32 v94, 1.0, v96
	v_mul_f32_e32 v92, v92, v93
	v_mul_f32_e32 v95, 0xbfb8aa3b, v87
	v_cvt_pk_bf16_f32 v91, v91, v92
	v_exp_f32_e32 v95, v95
	s_nop 0
	v_add_f32_e32 v95, 1.0, v95
	v_rcp_f32_e32 v92, v94
	s_nop 0
	v_mul_f32_e32 v86, v86, v92
	v_mul_f32_e32 v82, v86, v82
	v_mul_f32_e32 v93, 0xbfb8aa3b, v88
	v_exp_f32_e32 v93, v93
	v_rcp_f32_e32 v86, v95
	s_nop 0
	v_mul_f32_e32 v86, v87, v86
	v_add_f32_e32 v93, 1.0, v93
	v_mul_f32_e32 v83, v86, v83
	v_mul_f32_e32 v86, 0xbfb8aa3b, v89
	v_exp_f32_e32 v86, v86
	v_cvt_pk_bf16_f32 v92, v82, v83
	v_add_f32_e32 v86, 1.0, v86
	v_rcp_f32_e32 v82, v93
	s_nop 0
	v_mul_f32_e32 v82, v88, v82
	v_mul_f32_e32 v82, v82, v84
	v_mul_f32_e32 v84, 0xbfb8aa3b, v78
	v_exp_f32_e32 v84, v84
	v_rcp_f32_e32 v83, v86
	s_nop 0
	v_mul_f32_e32 v83, v89, v83
	v_mul_f32_e32 v83, v83, v85
	v_cvt_pk_bf16_f32 v93, v82, v83
	v_add_f32_e32 v84, 1.0, v84
	v_add_u32_e32 v82, 0x4020, v1
	v_mad_i64_i32 v[82:83], s[8:9], v82, s5, v[114:115]
	v_lshl_add_u64 v[82:83], v[82:83], 0, v[116:117]
	global_store_dwordx4 v[82:83], v[90:93], off
	v_mul_f32_e32 v87, 0xbfb8aa3b, v79
	v_exp_f32_e32 v87, v87
	s_nop 0
	v_add_f32_e32 v85, 1.0, v87
	v_rcp_f32_e32 v82, v84
	s_nop 0
	v_mul_f32_e32 v78, v78, v82
	v_mul_f32_e32 v74, v78, v74
	v_mul_f32_e32 v83, 0xbfb8aa3b, v80
	v_exp_f32_e32 v83, v83
	v_rcp_f32_e32 v78, v85
	s_nop 0
	v_mul_f32_e32 v78, v79, v78
	v_add_f32_e32 v82, 1.0, v83
	v_mul_f32_e32 v75, v78, v75
	v_mul_f32_e32 v79, 0xbfb8aa3b, v81
	v_cvt_pk_bf16_f32 v74, v74, v75
	v_exp_f32_e32 v79, v79
	s_nop 0
	v_add_f32_e32 v79, 1.0, v79
	v_rcp_f32_e32 v75, v82
	s_nop 0
	v_mul_f32_e32 v75, v80, v75
	v_mul_f32_e32 v75, v75, v76
	v_mul_f32_e32 v80, 0xbfb8aa3b, v70
	v_exp_f32_e32 v80, v80
	v_rcp_f32_e32 v76, v79
	s_nop 0
	v_mul_f32_e32 v76, v81, v76
	v_add_f32_e32 v78, 1.0, v80
	v_mul_f32_e32 v76, v76, v77
	v_mul_f32_e32 v79, 0xbfb8aa3b, v71
	v_cvt_pk_bf16_f32 v75, v75, v76
	v_exp_f32_e32 v79, v79
	s_nop 0
	v_add_f32_e32 v79, 1.0, v79
	v_rcp_f32_e32 v76, v78
	s_nop 0
	v_mul_f32_e32 v70, v70, v76
	v_mul_f32_e32 v66, v70, v66
	v_mul_f32_e32 v77, 0xbfb8aa3b, v72
	v_exp_f32_e32 v77, v77
	v_rcp_f32_e32 v70, v79
	s_nop 0
	v_mul_f32_e32 v70, v71, v70
	v_add_f32_e32 v77, 1.0, v77
	v_mul_f32_e32 v67, v70, v67
	v_mul_f32_e32 v70, 0xbfb8aa3b, v73
	v_exp_f32_e32 v70, v70
	v_cvt_pk_bf16_f32 v76, v66, v67
	v_add_f32_e32 v70, 1.0, v70
	v_rcp_f32_e32 v66, v77
	s_nop 0
	v_mul_f32_e32 v66, v72, v66
	v_mul_f32_e32 v66, v66, v68
	v_rcp_f32_e32 v67, v70
	s_nop 0
	v_mul_f32_e32 v67, v73, v67
	v_mul_f32_e32 v67, v67, v69
	v_cvt_pk_bf16_f32 v77, v66, v67
	v_mul_f32_e32 v66, 0xbfb8aa3b, v62
	v_exp_f32_e32 v68, v66
	v_add_u32_e32 v66, 0x4030, v1
	v_mad_i64_i32 v[66:67], s[8:9], v66, s5, v[114:115]
	v_add_f32_e32 v68, 1.0, v68
	v_lshl_add_u64 v[66:67], v[66:67], 0, v[116:117]
	global_store_dwordx4 v[66:67], v[74:77], off
	v_mul_f32_e32 v72, 0xbfb8aa3b, v63
	v_exp_f32_e32 v72, v72
	s_nop 0
	v_add_f32_e32 v69, 1.0, v72
	v_rcp_f32_e32 v67, v68
	s_nop 0
	v_mul_f32_e32 v62, v62, v67
	v_mul_f32_e32 v58, v62, v58
	v_mul_f32_e32 v68, 0xbfb8aa3b, v64
	v_exp_f32_e32 v68, v68
	v_rcp_f32_e32 v62, v69
	s_nop 0
	v_mul_f32_e32 v62, v63, v62
	v_add_f32_e32 v67, 1.0, v68
	v_mul_f32_e32 v59, v62, v59
	v_mul_f32_e32 v63, 0xbfb8aa3b, v65
	v_cvt_pk_bf16_f32 v58, v58, v59
	v_exp_f32_e32 v63, v63
	s_nop 0
	v_add_f32_e32 v63, 1.0, v63
	v_rcp_f32_e32 v59, v67
	s_nop 0
	v_mul_f32_e32 v59, v64, v59
	v_mul_f32_e32 v59, v59, v60
	v_mul_f32_e32 v64, 0xbfb8aa3b, v54
	v_exp_f32_e32 v64, v64
	v_rcp_f32_e32 v60, v63
	s_nop 0
	v_mul_f32_e32 v60, v65, v60
	v_add_f32_e32 v62, 1.0, v64
	v_mul_f32_e32 v60, v60, v61
	v_mul_f32_e32 v63, 0xbfb8aa3b, v55
	v_cvt_pk_bf16_f32 v59, v59, v60
	v_exp_f32_e32 v63, v63
	s_nop 0
	v_add_f32_e32 v63, 1.0, v63
	v_rcp_f32_e32 v60, v62
	s_nop 0
	v_mul_f32_e32 v54, v54, v60
	v_mul_f32_e32 v50, v54, v50
	v_mul_f32_e32 v61, 0xbfb8aa3b, v56
	v_exp_f32_e32 v61, v61
	v_rcp_f32_e32 v54, v63
	s_nop 0
	v_mul_f32_e32 v54, v55, v54
	v_add_f32_e32 v61, 1.0, v61
	v_mul_f32_e32 v51, v54, v51
	v_mul_f32_e32 v54, 0xbfb8aa3b, v57
	v_exp_f32_e32 v54, v54
	v_cvt_pk_bf16_f32 v60, v50, v51
	v_add_f32_e32 v54, 1.0, v54
	v_rcp_f32_e32 v50, v61
	s_nop 0
	v_mul_f32_e32 v50, v56, v50
	v_mul_f32_e32 v50, v50, v52
	v_mul_f32_e32 v52, 0xbfb8aa3b, v46
	v_exp_f32_e32 v52, v52
	v_rcp_f32_e32 v51, v54
	s_nop 0
	v_mul_f32_e32 v51, v57, v51
	v_mul_f32_e32 v51, v51, v53
	v_add_u32_e32 v66, 0x4080, v1
	v_add_f32_e32 v52, 1.0, v52
	v_cvt_pk_bf16_f32 v61, v50, v51
	v_mad_i64_i32 v[50:51], s[8:9], v66, s5, v[114:115]
	v_lshl_add_u64 v[50:51], v[50:51], 0, v[116:117]
	global_store_dwordx4 v[50:51], v[58:61], off
	v_mul_f32_e32 v55, 0xbfb8aa3b, v47
	v_exp_f32_e32 v55, v55
	s_nop 0
	v_add_f32_e32 v53, 1.0, v55
	v_rcp_f32_e32 v50, v52
	s_nop 0
	v_mul_f32_e32 v46, v46, v50
	v_mul_f32_e32 v42, v46, v42
	v_mul_f32_e32 v51, 0xbfb8aa3b, v48
	v_exp_f32_e32 v51, v51
	v_rcp_f32_e32 v46, v53
	s_nop 0
	v_mul_f32_e32 v46, v47, v46
	v_add_f32_e32 v50, 1.0, v51
	v_mul_f32_e32 v43, v46, v43
	v_mul_f32_e32 v47, 0xbfb8aa3b, v49
	v_cvt_pk_bf16_f32 v42, v42, v43
	v_exp_f32_e32 v47, v47
	s_nop 0
	v_add_f32_e32 v47, 1.0, v47
	v_rcp_f32_e32 v43, v50
	s_nop 0
	v_mul_f32_e32 v43, v48, v43
	v_mul_f32_e32 v43, v43, v44
	v_mul_f32_e32 v48, 0xbfb8aa3b, v38
	v_exp_f32_e32 v48, v48
	v_rcp_f32_e32 v44, v47
	s_nop 0
	v_mul_f32_e32 v44, v49, v44
	v_add_f32_e32 v46, 1.0, v48
	v_mul_f32_e32 v44, v44, v45
	v_mul_f32_e32 v47, 0xbfb8aa3b, v39
	v_cvt_pk_bf16_f32 v43, v43, v44
	v_exp_f32_e32 v47, v47
	s_nop 0
	v_add_f32_e32 v47, 1.0, v47
	v_rcp_f32_e32 v44, v46
	s_nop 0
	v_mul_f32_e32 v38, v38, v44
	v_mul_f32_e32 v34, v38, v34
	v_mul_f32_e32 v45, 0xbfb8aa3b, v40
	v_exp_f32_e32 v45, v45
	v_rcp_f32_e32 v38, v47
	s_nop 0
	v_mul_f32_e32 v38, v39, v38
	v_add_f32_e32 v45, 1.0, v45
	v_mul_f32_e32 v35, v38, v35
	v_mul_f32_e32 v38, 0xbfb8aa3b, v41
	v_exp_f32_e32 v38, v38
	v_cvt_pk_bf16_f32 v44, v34, v35
	v_add_f32_e32 v38, 1.0, v38
	v_rcp_f32_e32 v34, v45
	s_nop 0
	v_mul_f32_e32 v34, v40, v34
	v_mul_f32_e32 v34, v34, v36
	v_mul_f32_e32 v36, 0xbfb8aa3b, v30
	v_exp_f32_e32 v36, v36
	v_rcp_f32_e32 v35, v38
	s_nop 0
	v_mul_f32_e32 v35, v41, v35
	v_mul_f32_e32 v35, v35, v37
	v_cvt_pk_bf16_f32 v45, v34, v35
	v_add_f32_e32 v36, 1.0, v36
	v_add_u32_e32 v34, 0x4090, v1
	v_mad_i64_i32 v[34:35], s[8:9], v34, s5, v[114:115]
	v_lshl_add_u64 v[34:35], v[34:35], 0, v[116:117]
	global_store_dwordx4 v[34:35], v[42:45], off
	v_mul_f32_e32 v39, 0xbfb8aa3b, v31
	v_exp_f32_e32 v39, v39
	s_nop 0
	v_add_f32_e32 v37, 1.0, v39
	v_rcp_f32_e32 v34, v36
	s_nop 0
	v_mul_f32_e32 v30, v30, v34
	v_mul_f32_e32 v26, v30, v26
	v_mul_f32_e32 v35, 0xbfb8aa3b, v32
	v_exp_f32_e32 v35, v35
	v_rcp_f32_e32 v30, v37
	s_nop 0
	v_mul_f32_e32 v30, v31, v30
	v_add_f32_e32 v34, 1.0, v35
	v_mul_f32_e32 v27, v30, v27
	v_mul_f32_e32 v31, 0xbfb8aa3b, v33
	v_cvt_pk_bf16_f32 v26, v26, v27
	v_exp_f32_e32 v31, v31
	s_nop 0
	v_add_f32_e32 v31, 1.0, v31
	v_rcp_f32_e32 v27, v34
	s_nop 0
	v_mul_f32_e32 v27, v32, v27
	v_mul_f32_e32 v27, v27, v28
	v_mul_f32_e32 v32, 0xbfb8aa3b, v22
	v_exp_f32_e32 v32, v32
	v_rcp_f32_e32 v28, v31
	s_nop 0
	v_mul_f32_e32 v28, v33, v28
	v_add_f32_e32 v30, 1.0, v32
	v_mul_f32_e32 v28, v28, v29
	v_mul_f32_e32 v31, 0xbfb8aa3b, v23
	v_cvt_pk_bf16_f32 v27, v27, v28
	v_exp_f32_e32 v31, v31
	s_nop 0
	v_add_f32_e32 v31, 1.0, v31
	v_rcp_f32_e32 v28, v30
	s_nop 0
	v_mul_f32_e32 v22, v22, v28
	v_mul_f32_e32 v18, v22, v18
	v_mul_f32_e32 v29, 0xbfb8aa3b, v24
	v_exp_f32_e32 v29, v29
	v_rcp_f32_e32 v22, v31
	s_nop 0
	v_mul_f32_e32 v22, v23, v22
	v_add_f32_e32 v29, 1.0, v29
	v_mul_f32_e32 v19, v22, v19
	v_mul_f32_e32 v22, 0xbfb8aa3b, v25
	v_exp_f32_e32 v22, v22
	v_cvt_pk_bf16_f32 v28, v18, v19
	v_add_f32_e32 v22, 1.0, v22
	v_rcp_f32_e32 v18, v29
	s_nop 0
	v_mul_f32_e32 v18, v24, v18
	v_mul_f32_e32 v18, v18, v20
	v_mul_f32_e32 v20, 0xbfb8aa3b, v14
	v_exp_f32_e32 v20, v20
	v_rcp_f32_e32 v19, v22
	s_nop 0
	v_mul_f32_e32 v19, v25, v19
	v_mul_f32_e32 v19, v19, v21
	v_cvt_pk_bf16_f32 v29, v18, v19
	v_add_f32_e32 v20, 1.0, v20
	v_add_u32_e32 v18, 0x40a0, v1
	v_mad_i64_i32 v[18:19], s[8:9], v18, s5, v[114:115]
	v_lshl_add_u64 v[18:19], v[18:19], 0, v[116:117]
	global_store_dwordx4 v[18:19], v[26:29], off
	v_mul_f32_e32 v23, 0xbfb8aa3b, v15
	v_exp_f32_e32 v23, v23
	s_nop 0
	v_add_f32_e32 v21, 1.0, v23
	v_rcp_f32_e32 v18, v20
	s_nop 0
	v_mul_f32_e32 v14, v14, v18
	v_mul_f32_e32 v10, v14, v10
	v_mul_f32_e32 v19, 0xbfb8aa3b, v16
	v_exp_f32_e32 v19, v19
	v_rcp_f32_e32 v14, v21
	s_nop 0
	v_mul_f32_e32 v14, v15, v14
	v_add_f32_e32 v18, 1.0, v19
	v_mul_f32_e32 v11, v14, v11
	v_mul_f32_e32 v15, 0xbfb8aa3b, v17
	v_cvt_pk_bf16_f32 v10, v10, v11
	v_exp_f32_e32 v15, v15
	s_nop 0
	v_add_f32_e32 v15, 1.0, v15
	v_rcp_f32_e32 v11, v18
	s_nop 0
	v_mul_f32_e32 v11, v16, v11
	v_mul_f32_e32 v11, v11, v12
	v_mul_f32_e32 v16, 0xbfb8aa3b, v6
	v_exp_f32_e32 v16, v16
	v_rcp_f32_e32 v12, v15
	s_nop 0
	v_mul_f32_e32 v12, v17, v12
	v_add_f32_e32 v14, 1.0, v16
	v_mul_f32_e32 v12, v12, v13
	v_mul_f32_e32 v15, 0xbfb8aa3b, v7
	v_cvt_pk_bf16_f32 v11, v11, v12
	v_exp_f32_e32 v15, v15
	s_nop 0
	v_add_f32_e32 v15, 1.0, v15
	v_rcp_f32_e32 v12, v14
	s_nop 0
	v_mul_f32_e32 v6, v6, v12
	v_mul_f32_e32 v2, v6, v2
	v_mul_f32_e32 v13, 0xbfb8aa3b, v8
	v_exp_f32_e32 v13, v13
	v_rcp_f32_e32 v6, v15
	s_nop 0
	v_mul_f32_e32 v6, v7, v6
	v_add_f32_e32 v13, 1.0, v13
	v_mul_f32_e32 v3, v6, v3
	v_mul_f32_e32 v6, 0xbfb8aa3b, v9
	v_exp_f32_e32 v6, v6
	v_cvt_pk_bf16_f32 v12, v2, v3
	v_add_f32_e32 v6, 1.0, v6
	v_rcp_f32_e32 v2, v13
	s_nop 0
	v_mul_f32_e32 v2, v8, v2
	v_mul_f32_e32 v2, v2, v4
	v_rcp_f32_e32 v3, v6
	s_nop 0
	v_mul_f32_e32 v3, v9, v3
	v_mul_f32_e32 v3, v3, v5
	v_add_u32_e32 v1, 0x40b0, v1
	v_cvt_pk_bf16_f32 v13, v2, v3
	v_mad_i64_i32 v[2:3], s[8:9], v1, s5, v[114:115]
	v_lshl_add_u64 v[2:3], v[2:3], 0, v[116:117]
	global_store_dwordx4 v[2:3], v[10:13], off
	s_waitcnt vmcnt(0)
	s_barrier
	s_waitcnt vmcnt(0)
	s_waitcnt vmcnt(0) lgkmcnt(0)
	s_barrier
	s_mov_b64 s[8:9], exec
	v_readlane_b32 s10, v228, 2
	v_readlane_b32 s11, v228, 3
	s_and_b64 s[10:11], s[8:9], s[10:11]
	s_mov_b64 exec, s[10:11]
	s_cbranch_execz .LBB0_5759
	s_mov_b64 s[10:11], exec
	v_mbcnt_lo_u32_b32 v1, s10, 0
	buffer_wbl2 sc1
	s_waitcnt vmcnt(0)
	v_mbcnt_hi_u32_b32 v1, s11, v1
	v_cmp_eq_u32_e32 vcc, 0, v1
	s_and_b64 s[12:13], exec, vcc
	s_mov_b64 exec, s[12:13]
	s_cbranch_execz .LBB0_5759
	s_bcnt1_i32_b64 s5, s[10:11]
	v_mov_b32_e32 v1, 0
	v_mov_b32_e32 v2, s5
	global_atomic_add v1, v2, s[6:7]

.LBB0_5822:
	v_mul_f32_e32 v148, 0xbfb8aa3b, v126
	v_exp_f32_e32 v149, v148
	v_lshl_add_u32 v148, s42, 8, v1
	v_lshl_or_b32 v150, s43, 7, v142
	v_mul_f32_e32 v156, 0xbfb8aa3b, v127
	v_add_f32_e32 v149, 1.0, v149
	v_exp_f32_e32 v156, v156
	s_nop 0
	v_add_f32_e32 v154, 1.0, v156
	v_rcp_f32_e32 v152, v149
	s_nop 0
	v_mul_f32_e32 v126, v126, v152
	v_mul_f32_e32 v122, v126, v122
	v_mul_f32_e32 v152, 0xbfb8aa3b, v128
	v_exp_f32_e32 v152, v152
	v_rcp_f32_e32 v126, v154
	s_nop 0
	v_mul_f32_e32 v126, v127, v126
	v_add_f32_e32 v149, 1.0, v152
	v_mul_f32_e32 v123, v126, v123
	v_mul_f32_e32 v127, 0xbfb8aa3b, v129
	v_cvt_pk_bf16_f32 v122, v122, v123
	v_exp_f32_e32 v127, v127
	s_nop 0
	v_add_f32_e32 v127, 1.0, v127
	v_rcp_f32_e32 v123, v149
	s_nop 0
	v_mul_f32_e32 v123, v128, v123
	v_mul_f32_e32 v123, v123, v124
	v_mul_f32_e32 v128, 0xbfb8aa3b, v118
	v_exp_f32_e32 v128, v128
	v_rcp_f32_e32 v124, v127
	s_nop 0
	v_mul_f32_e32 v124, v129, v124
	v_add_f32_e32 v126, 1.0, v128
	v_mul_f32_e32 v124, v124, v125
	v_mul_f32_e32 v127, 0xbfb8aa3b, v119
	v_cvt_pk_bf16_f32 v123, v123, v124
	v_exp_f32_e32 v127, v127
	s_nop 0
	v_add_f32_e32 v127, 1.0, v127
	v_rcp_f32_e32 v124, v126
	s_nop 0
	v_mul_f32_e32 v118, v118, v124
	v_mul_f32_e32 v114, v118, v114
	v_mul_f32_e32 v125, 0xbfb8aa3b, v120
	v_exp_f32_e32 v125, v125
	v_rcp_f32_e32 v118, v127
	s_nop 0
	v_mul_f32_e32 v118, v119, v118
	v_add_f32_e32 v125, 1.0, v125
	v_mul_f32_e32 v115, v118, v115
	v_mul_f32_e32 v118, 0xbfb8aa3b, v121
	v_exp_f32_e32 v118, v118
	v_cvt_pk_bf16_f32 v124, v114, v115
	v_add_f32_e32 v118, 1.0, v118
	v_rcp_f32_e32 v114, v125
	s_nop 0
	v_mul_f32_e32 v114, v120, v114
	v_mul_f32_e32 v114, v114, v116
	v_rcp_f32_e32 v115, v118
	s_nop 0
	v_mul_f32_e32 v115, v121, v115
	v_mul_f32_e32 v115, v115, v117
	v_cvt_pk_bf16_f32 v125, v114, v115
	v_mul_f32_e32 v114, 0xbfb8aa3b, v110
	v_exp_f32_e32 v116, v114
	v_ashrrev_i32_e32 v151, 31, v150
	v_mov_b64_e32 v[114:115], s[18:19]
	v_mad_i64_i32 v[118:119], s[42:43], v148, s59, v[114:115]
	v_add_f32_e32 v120, 1.0, v116
	v_lshlrev_b64 v[116:117], 1, v[150:151]
	v_lshl_add_u64 v[118:119], v[118:119], 0, v[116:117]
	global_store_dwordx4 v[118:119], v[122:125], off
	s_nop 1
	v_mul_f32_e32 v122, 0xbfb8aa3b, v111
	v_exp_f32_e32 v122, v122
	s_nop 0
	v_add_f32_e32 v121, 1.0, v122
	v_rcp_f32_e32 v118, v120
	s_nop 0
	v_mul_f32_e32 v110, v110, v118
	v_mul_f32_e32 v106, v110, v106
	v_mul_f32_e32 v119, 0xbfb8aa3b, v112
	v_exp_f32_e32 v119, v119
	v_rcp_f32_e32 v110, v121
	s_nop 0
	v_mul_f32_e32 v110, v111, v110
	v_add_f32_e32 v118, 1.0, v119
	v_mul_f32_e32 v107, v110, v107
	v_mul_f32_e32 v111, 0xbfb8aa3b, v113
	v_cvt_pk_bf16_f32 v106, v106, v107
	v_exp_f32_e32 v111, v111
	s_nop 0
	v_add_f32_e32 v111, 1.0, v111
	v_rcp_f32_e32 v107, v118
	s_nop 0
	v_mul_f32_e32 v107, v112, v107
	v_mul_f32_e32 v107, v107, v108
	v_mul_f32_e32 v112, 0xbfb8aa3b, v102
	v_exp_f32_e32 v112, v112
	v_rcp_f32_e32 v108, v111
	s_nop 0
	v_mul_f32_e32 v108, v113, v108
	v_add_f32_e32 v110, 1.0, v112
	v_mul_f32_e32 v108, v108, v109
	v_mul_f32_e32 v111, 0xbfb8aa3b, v103
	v_cvt_pk_bf16_f32 v107, v107, v108
	v_exp_f32_e32 v111, v111
	s_nop 0
	v_add_f32_e32 v111, 1.0, v111
	v_rcp_f32_e32 v108, v110
	s_nop 0
	v_mul_f32_e32 v102, v102, v108
	v_mul_f32_e32 v98, v102, v98
	v_mul_f32_e32 v109, 0xbfb8aa3b, v104
	v_exp_f32_e32 v109, v109
	v_rcp_f32_e32 v102, v111
	s_nop 0
	v_mul_f32_e32 v102, v103, v102
	v_add_f32_e32 v109, 1.0, v109
	v_mul_f32_e32 v99, v102, v99
	v_mul_f32_e32 v102, 0xbfb8aa3b, v105
	v_exp_f32_e32 v102, v102
	v_cvt_pk_bf16_f32 v108, v98, v99
	v_add_f32_e32 v102, 1.0, v102
	v_rcp_f32_e32 v98, v109
	s_nop 0
	v_mul_f32_e32 v98, v104, v98
	v_mul_f32_e32 v98, v98, v100
	v_mul_f32_e32 v100, 0xbfb8aa3b, v94
	v_exp_f32_e32 v100, v100
	v_rcp_f32_e32 v99, v102
	s_nop 0
	v_mul_f32_e32 v99, v105, v99
	v_mul_f32_e32 v99, v99, v101
	v_cvt_pk_bf16_f32 v109, v98, v99
	v_add_f32_e32 v100, 1.0, v100
	v_or_b32_e32 v98, 16, v148
	v_mad_i64_i32 v[98:99], s[42:43], v98, s59, v[114:115]
	v_lshl_add_u64 v[98:99], v[98:99], 0, v[116:117]
	global_store_dwordx4 v[98:99], v[106:109], off
	v_mul_f32_e32 v103, 0xbfb8aa3b, v95
	v_exp_f32_e32 v103, v103
	s_nop 0
	v_add_f32_e32 v101, 1.0, v103
	v_rcp_f32_e32 v98, v100
	s_nop 0
	v_mul_f32_e32 v94, v94, v98
	v_mul_f32_e32 v90, v94, v90
	v_mul_f32_e32 v99, 0xbfb8aa3b, v96
	v_exp_f32_e32 v99, v99
	v_rcp_f32_e32 v94, v101
	s_nop 0
	v_mul_f32_e32 v94, v95, v94
	v_add_f32_e32 v98, 1.0, v99
	v_mul_f32_e32 v91, v94, v91
	v_mul_f32_e32 v95, 0xbfb8aa3b, v97
	v_cvt_pk_bf16_f32 v90, v90, v91
	v_exp_f32_e32 v95, v95
	s_nop 0
	v_add_f32_e32 v95, 1.0, v95
	v_rcp_f32_e32 v91, v98
	s_nop 0
	v_mul_f32_e32 v91, v96, v91
	v_mul_f32_e32 v91, v91, v92
	v_mul_f32_e32 v96, 0xbfb8aa3b, v86
	v_exp_f32_e32 v96, v96
	v_rcp_f32_e32 v92, v95
	s_nop 0
	v_mul_f32_e32 v92, v97, v92
	v_add_f32_e32 v94, 1.0, v96
	v_mul_f32_e32 v92, v92, v93
	v_mul_f32_e32 v95, 0xbfb8aa3b, v87
	v_cvt_pk_bf16_f32 v91, v91, v92
	v_exp_f32_e32 v95, v95
	s_nop 0
	v_add_f32_e32 v95, 1.0, v95
	v_rcp_f32_e32 v92, v94
	s_nop 0
	v_mul_f32_e32 v86, v86, v92
	v_mul_f32_e32 v82, v86, v82
	v_mul_f32_e32 v93, 0xbfb8aa3b, v88
	v_exp_f32_e32 v93, v93
	v_rcp_f32_e32 v86, v95
	s_nop 0
	v_mul_f32_e32 v86, v87, v86
	v_add_f32_e32 v93, 1.0, v93
	v_mul_f32_e32 v83, v86, v83
	v_mul_f32_e32 v86, 0xbfb8aa3b, v89
	v_exp_f32_e32 v86, v86
	v_cvt_pk_bf16_f32 v92, v82, v83
	v_add_f32_e32 v86, 1.0, v86
	v_rcp_f32_e32 v82, v93
	s_nop 0
	v_mul_f32_e32 v82, v88, v82
	v_mul_f32_e32 v82, v82, v84
	v_mul_f32_e32 v84, 0xbfb8aa3b, v78
	v_exp_f32_e32 v84, v84
	v_rcp_f32_e32 v83, v86
	s_nop 0
	v_mul_f32_e32 v83, v89, v83
	v_mul_f32_e32 v83, v83, v85
	v_cvt_pk_bf16_f32 v93, v82, v83
	v_add_f32_e32 v84, 1.0, v84
	v_or_b32_e32 v82, 32, v148
	v_mad_i64_i32 v[82:83], s[42:43], v82, s59, v[114:115]
	v_lshl_add_u64 v[82:83], v[82:83], 0, v[116:117]
	global_store_dwordx4 v[82:83], v[90:93], off
	v_mul_f32_e32 v87, 0xbfb8aa3b, v79
	v_exp_f32_e32 v87, v87
	s_nop 0
	v_add_f32_e32 v85, 1.0, v87
	v_rcp_f32_e32 v82, v84
	s_nop 0
	v_mul_f32_e32 v78, v78, v82
	v_mul_f32_e32 v74, v78, v74
	v_mul_f32_e32 v83, 0xbfb8aa3b, v80
	v_exp_f32_e32 v83, v83
	v_rcp_f32_e32 v78, v85
	s_nop 0
	v_mul_f32_e32 v78, v79, v78
	v_add_f32_e32 v82, 1.0, v83
	v_mul_f32_e32 v75, v78, v75
	v_mul_f32_e32 v79, 0xbfb8aa3b, v81
	v_cvt_pk_bf16_f32 v74, v74, v75
	v_exp_f32_e32 v79, v79
	s_nop 0
	v_add_f32_e32 v79, 1.0, v79
	v_rcp_f32_e32 v75, v82
	s_nop 0
	v_mul_f32_e32 v75, v80, v75
	v_mul_f32_e32 v75, v75, v76
	v_mul_f32_e32 v80, 0xbfb8aa3b, v70
	v_exp_f32_e32 v80, v80
	v_rcp_f32_e32 v76, v79
	s_nop 0
	v_mul_f32_e32 v76, v81, v76
	v_add_f32_e32 v78, 1.0, v80
	v_mul_f32_e32 v76, v76, v77
	v_mul_f32_e32 v79, 0xbfb8aa3b, v71
	v_cvt_pk_bf16_f32 v75, v75, v76
	v_exp_f32_e32 v79, v79
	s_nop 0
	v_add_f32_e32 v79, 1.0, v79
	v_rcp_f32_e32 v76, v78
	s_nop 0
	v_mul_f32_e32 v70, v70, v76
	v_mul_f32_e32 v66, v70, v66
	v_mul_f32_e32 v77, 0xbfb8aa3b, v72
	v_exp_f32_e32 v77, v77
	v_rcp_f32_e32 v70, v79
	s_nop 0
	v_mul_f32_e32 v70, v71, v70
	v_add_f32_e32 v77, 1.0, v77
	v_mul_f32_e32 v67, v70, v67
	v_mul_f32_e32 v70, 0xbfb8aa3b, v73
	v_exp_f32_e32 v70, v70
	v_cvt_pk_bf16_f32 v76, v66, v67
	v_add_f32_e32 v70, 1.0, v70
	v_rcp_f32_e32 v66, v77
	s_nop 0
	v_mul_f32_e32 v66, v72, v66
	v_mul_f32_e32 v66, v66, v68
	v_rcp_f32_e32 v67, v70
	s_nop 0
	v_mul_f32_e32 v67, v73, v67
	v_mul_f32_e32 v67, v67, v69
	v_cvt_pk_bf16_f32 v77, v66, v67
	v_mul_f32_e32 v66, 0xbfb8aa3b, v62
	v_exp_f32_e32 v68, v66
	v_or_b32_e32 v66, 48, v148
	v_mad_i64_i32 v[66:67], s[42:43], v66, s59, v[114:115]
	v_add_f32_e32 v68, 1.0, v68
	v_lshl_add_u64 v[66:67], v[66:67], 0, v[116:117]
	global_store_dwordx4 v[66:67], v[74:77], off
	v_mul_f32_e32 v72, 0xbfb8aa3b, v63
	v_exp_f32_e32 v72, v72
	s_nop 0
	v_add_f32_e32 v69, 1.0, v72
	v_rcp_f32_e32 v67, v68
	s_nop 0
	v_mul_f32_e32 v62, v62, v67
	v_mul_f32_e32 v58, v62, v58
	v_mul_f32_e32 v68, 0xbfb8aa3b, v64
	v_exp_f32_e32 v68, v68
	v_rcp_f32_e32 v62, v69
	s_nop 0
	v_mul_f32_e32 v62, v63, v62
	v_add_f32_e32 v67, 1.0, v68
	v_mul_f32_e32 v59, v62, v59
	v_mul_f32_e32 v63, 0xbfb8aa3b, v65
	v_cvt_pk_bf16_f32 v58, v58, v59
	v_exp_f32_e32 v63, v63
	s_nop 0
	v_add_f32_e32 v63, 1.0, v63
	v_rcp_f32_e32 v59, v67
	s_nop 0
	v_mul_f32_e32 v59, v64, v59
	v_mul_f32_e32 v59, v59, v60
	v_mul_f32_e32 v64, 0xbfb8aa3b, v54
	v_exp_f32_e32 v64, v64
	v_rcp_f32_e32 v60, v63
	s_nop 0
	v_mul_f32_e32 v60, v65, v60
	v_add_f32_e32 v62, 1.0, v64
	v_mul_f32_e32 v60, v60, v61
	v_mul_f32_e32 v63, 0xbfb8aa3b, v55
	v_cvt_pk_bf16_f32 v59, v59, v60
	v_exp_f32_e32 v63, v63
	s_nop 0
	v_add_f32_e32 v63, 1.0, v63
	v_rcp_f32_e32 v60, v62
	s_nop 0
	v_mul_f32_e32 v54, v54, v60
	v_mul_f32_e32 v50, v54, v50
	v_mul_f32_e32 v61, 0xbfb8aa3b, v56
	v_exp_f32_e32 v61, v61
	v_rcp_f32_e32 v54, v63
	s_nop 0
	v_mul_f32_e32 v54, v55, v54
	v_add_f32_e32 v61, 1.0, v61
	v_mul_f32_e32 v51, v54, v51
	v_mul_f32_e32 v54, 0xbfb8aa3b, v57
	v_exp_f32_e32 v54, v54
	v_cvt_pk_bf16_f32 v60, v50, v51
	v_add_f32_e32 v54, 1.0, v54
	v_rcp_f32_e32 v50, v61
	s_nop 0
	v_mul_f32_e32 v50, v56, v50
	v_mul_f32_e32 v50, v50, v52
	v_mul_f32_e32 v52, 0xbfb8aa3b, v46
	v_exp_f32_e32 v52, v52
	v_rcp_f32_e32 v51, v54
	s_nop 0
	v_mul_f32_e32 v51, v57, v51
	v_mul_f32_e32 v51, v51, v53
	v_add_u32_e32 v66, 0x80, v148
	v_add_f32_e32 v52, 1.0, v52
	v_cvt_pk_bf16_f32 v61, v50, v51
	v_mad_i64_i32 v[50:51], s[42:43], v66, s59, v[114:115]
	v_lshl_add_u64 v[50:51], v[50:51], 0, v[116:117]
	global_store_dwordx4 v[50:51], v[58:61], off
	v_mul_f32_e32 v55, 0xbfb8aa3b, v47
	v_exp_f32_e32 v55, v55
	s_nop 0
	v_add_f32_e32 v53, 1.0, v55
	v_rcp_f32_e32 v50, v52
	s_nop 0
	v_mul_f32_e32 v46, v46, v50
	v_mul_f32_e32 v42, v46, v42
	v_mul_f32_e32 v51, 0xbfb8aa3b, v48
	v_exp_f32_e32 v51, v51
	v_rcp_f32_e32 v46, v53
	s_nop 0
	v_mul_f32_e32 v46, v47, v46
	v_add_f32_e32 v50, 1.0, v51
	v_mul_f32_e32 v43, v46, v43
	v_mul_f32_e32 v47, 0xbfb8aa3b, v49
	v_cvt_pk_bf16_f32 v42, v42, v43
	v_exp_f32_e32 v47, v47
	s_nop 0
	v_add_f32_e32 v47, 1.0, v47
	v_rcp_f32_e32 v43, v50
	s_nop 0
	v_mul_f32_e32 v43, v48, v43
	v_mul_f32_e32 v43, v43, v44
	v_mul_f32_e32 v48, 0xbfb8aa3b, v38
	v_exp_f32_e32 v48, v48
	v_rcp_f32_e32 v44, v47
	s_nop 0
	v_mul_f32_e32 v44, v49, v44
	v_add_f32_e32 v46, 1.0, v48
	v_mul_f32_e32 v44, v44, v45
	v_mul_f32_e32 v47, 0xbfb8aa3b, v39
	v_cvt_pk_bf16_f32 v43, v43, v44
	v_exp_f32_e32 v47, v47
	s_nop 0
	v_add_f32_e32 v47, 1.0, v47
	v_rcp_f32_e32 v44, v46
	s_nop 0
	v_mul_f32_e32 v38, v38, v44
	v_mul_f32_e32 v34, v38, v34
	v_mul_f32_e32 v45, 0xbfb8aa3b, v40
	v_exp_f32_e32 v45, v45
	v_rcp_f32_e32 v38, v47
	s_nop 0
	v_mul_f32_e32 v38, v39, v38
	v_add_f32_e32 v45, 1.0, v45
	v_mul_f32_e32 v35, v38, v35
	v_mul_f32_e32 v38, 0xbfb8aa3b, v41
	v_exp_f32_e32 v38, v38
	v_cvt_pk_bf16_f32 v44, v34, v35
	v_add_f32_e32 v38, 1.0, v38
	v_rcp_f32_e32 v34, v45
	s_nop 0
	v_mul_f32_e32 v34, v40, v34
	v_mul_f32_e32 v34, v34, v36
	v_mul_f32_e32 v36, 0xbfb8aa3b, v30
	v_exp_f32_e32 v36, v36
	v_rcp_f32_e32 v35, v38
	s_nop 0
	v_mul_f32_e32 v35, v41, v35
	v_mul_f32_e32 v35, v35, v37
	v_cvt_pk_bf16_f32 v45, v34, v35
	v_add_f32_e32 v36, 1.0, v36
	v_add_u32_e32 v34, 0x90, v148
	v_mad_i64_i32 v[34:35], s[42:43], v34, s59, v[114:115]
	v_lshl_add_u64 v[34:35], v[34:35], 0, v[116:117]
	global_store_dwordx4 v[34:35], v[42:45], off
	v_mul_f32_e32 v39, 0xbfb8aa3b, v31
	v_exp_f32_e32 v39, v39
	s_nop 0
	v_add_f32_e32 v37, 1.0, v39
	v_rcp_f32_e32 v34, v36
	s_nop 0
	v_mul_f32_e32 v30, v30, v34
	v_mul_f32_e32 v26, v30, v26
	v_mul_f32_e32 v35, 0xbfb8aa3b, v32
	v_exp_f32_e32 v35, v35
	v_rcp_f32_e32 v30, v37
	s_nop 0
	v_mul_f32_e32 v30, v31, v30
	v_add_f32_e32 v34, 1.0, v35
	v_mul_f32_e32 v27, v30, v27
	v_mul_f32_e32 v31, 0xbfb8aa3b, v33
	v_cvt_pk_bf16_f32 v26, v26, v27
	v_exp_f32_e32 v31, v31
	s_nop 0
	v_add_f32_e32 v31, 1.0, v31
	v_rcp_f32_e32 v27, v34
	s_nop 0
	v_mul_f32_e32 v27, v32, v27
	v_mul_f32_e32 v27, v27, v28
	v_mul_f32_e32 v32, 0xbfb8aa3b, v22
	v_exp_f32_e32 v32, v32
	v_rcp_f32_e32 v28, v31
	s_nop 0
	v_mul_f32_e32 v28, v33, v28
	v_add_f32_e32 v30, 1.0, v32
	v_mul_f32_e32 v28, v28, v29
	v_mul_f32_e32 v31, 0xbfb8aa3b, v23
	v_cvt_pk_bf16_f32 v27, v27, v28
	v_exp_f32_e32 v31, v31
	s_nop 0
	v_add_f32_e32 v31, 1.0, v31
	v_rcp_f32_e32 v28, v30
	s_nop 0
	v_mul_f32_e32 v22, v22, v28
	v_mul_f32_e32 v18, v22, v18
	v_mul_f32_e32 v29, 0xbfb8aa3b, v24
	v_exp_f32_e32 v29, v29
	v_rcp_f32_e32 v22, v31
	s_nop 0
	v_mul_f32_e32 v22, v23, v22
	v_add_f32_e32 v29, 1.0, v29
	v_mul_f32_e32 v19, v22, v19
	v_mul_f32_e32 v22, 0xbfb8aa3b, v25
	v_exp_f32_e32 v22, v22
	v_cvt_pk_bf16_f32 v28, v18, v19
	v_add_f32_e32 v22, 1.0, v22
	v_rcp_f32_e32 v18, v29
	s_nop 0
	v_mul_f32_e32 v18, v24, v18
	v_mul_f32_e32 v18, v18, v20
	v_mul_f32_e32 v20, 0xbfb8aa3b, v14
	v_exp_f32_e32 v20, v20
	v_rcp_f32_e32 v19, v22
	s_nop 0
	v_mul_f32_e32 v19, v25, v19
	v_mul_f32_e32 v19, v19, v21
	v_cvt_pk_bf16_f32 v29, v18, v19
	v_add_f32_e32 v20, 1.0, v20
	v_add_u32_e32 v18, 0xa0, v148
	v_mad_i64_i32 v[18:19], s[42:43], v18, s59, v[114:115]
	v_lshl_add_u64 v[18:19], v[18:19], 0, v[116:117]
	global_store_dwordx4 v[18:19], v[26:29], off
	v_mul_f32_e32 v23, 0xbfb8aa3b, v15
	v_exp_f32_e32 v23, v23
	s_nop 0
	v_add_f32_e32 v21, 1.0, v23
	v_rcp_f32_e32 v18, v20
	s_nop 0
	v_mul_f32_e32 v14, v14, v18
	v_mul_f32_e32 v10, v14, v10
	v_mul_f32_e32 v19, 0xbfb8aa3b, v16
	v_exp_f32_e32 v19, v19
	v_rcp_f32_e32 v14, v21
	s_nop 0
	v_mul_f32_e32 v14, v15, v14
	v_add_f32_e32 v18, 1.0, v19
	v_mul_f32_e32 v11, v14, v11
	v_mul_f32_e32 v15, 0xbfb8aa3b, v17
	v_cvt_pk_bf16_f32 v10, v10, v11
	v_exp_f32_e32 v15, v15
	s_nop 0
	v_add_f32_e32 v15, 1.0, v15
	v_rcp_f32_e32 v11, v18
	s_nop 0
	v_mul_f32_e32 v11, v16, v11
	v_mul_f32_e32 v11, v11, v12
	v_mul_f32_e32 v16, 0xbfb8aa3b, v6
	v_exp_f32_e32 v16, v16
	v_rcp_f32_e32 v12, v15
	s_nop 0
	v_mul_f32_e32 v12, v17, v12
	v_add_f32_e32 v14, 1.0, v16
	v_mul_f32_e32 v12, v12, v13
	v_mul_f32_e32 v15, 0xbfb8aa3b, v7
	v_cvt_pk_bf16_f32 v11, v11, v12
	v_exp_f32_e32 v15, v15
	s_nop 0
	v_add_f32_e32 v15, 1.0, v15
	v_rcp_f32_e32 v12, v14
	s_nop 0
	v_mul_f32_e32 v6, v6, v12
	v_mul_f32_e32 v2, v6, v2
	v_mul_f32_e32 v13, 0xbfb8aa3b, v8
	v_exp_f32_e32 v13, v13
	v_rcp_f32_e32 v6, v15
	s_nop 0
	v_mul_f32_e32 v6, v7, v6
	v_add_f32_e32 v13, 1.0, v13
	v_mul_f32_e32 v3, v6, v3
	v_mul_f32_e32 v6, 0xbfb8aa3b, v9
	v_exp_f32_e32 v6, v6
	v_cvt_pk_bf16_f32 v12, v2, v3
	v_add_f32_e32 v6, 1.0, v6
	v_rcp_f32_e32 v2, v13
	s_nop 0
	v_mul_f32_e32 v2, v8, v2
	v_mul_f32_e32 v2, v2, v4
	v_rcp_f32_e32 v3, v6
	s_nop 0
	v_mul_f32_e32 v3, v9, v3
	v_mul_f32_e32 v3, v3, v5
	v_cvt_pk_bf16_f32 v13, v2, v3
	v_add_u32_e32 v2, 0xb0, v148
	v_mad_i64_i32 v[2:3], s[42:43], v2, s59, v[114:115]
	v_lshl_add_u64 v[2:3], v[2:3], 0, v[116:117]
	s_mov_b64 s[42:43], -1
	s_and_b64 vcc, exec, s[38:39]
	global_store_dwordx4 v[2:3], v[10:13], off
	s_cbranch_vccz .LBB0_5811
	s_andn2_b64 vcc, exec, s[6:7]
	s_cbranch_vccnz .LBB0_5810
	s_barrier
	s_branch .LBB0_5810
